# B-fragment LDS base addresses precomputed per unit (4 fewer VALU per K-loop iteration)
# baseline (speedup 1.0000x reference)
; template <class Epi, bool ALIGN_EPI>
; __device__ __forceinline__ void gemm_phase(LAS unsigned char* lds, const Gemm g, const StaticOrder& S, const Epi& E, const int tid) {
;     ...
;         const bool has_next = S.next(ui + 1, nxt);
;         const char* nA = has_next ? (const char*)g.A + (size_t)nxt.pm * tstepA + (size_t)nxt.pn * g.acs : cA; const char* nB = has_next ? (const char*)g.Bt + (size_t)nxt.pn * tstepB : cB;
;         for (int t = 0; t < nt; t += 2) {
;             const bool last = (t == nt - 2);
;             const char* a1 = cA + (size_t)(t + 1) * kstepA;
;             const char* a2 = last ? nA : cA + (size_t)(t + 2) * kstepA; const char* b2 = last ? nB : cB + (size_t)(t + 2) * kstepB;
;             const char* a3 = a2 + kstepA; const char* b3 = b2 + kstepB;
.LBB0_210:
	s_ashr_i32 s43, s42, 31
	s_lshl_b64 s[44:45], s[42:43], 20
	s_add_u32 s44, s56, s44
	s_addc_u32 s45, s57, s45
	s_and_b64 s[46:47], s[40:41], exec
	s_cselect_b32 s43, s45, s49
	s_cselect_b32 s87, s44, s48
	s_ashr_i32 s35, s34, 31
	s_lshl_b64 s[46:47], s[34:35], 20
	s_add_u32 s46, s60, s46
	s_addc_u32 s47, s61, s47
	s_and_b64 s[52:53], s[40:41], exec
	s_cselect_b32 s35, s47, s51
	s_cselect_b32 vcc_lo, s46, s50
	s_add_u32 s48, s48, 0xc000
	s_addc_u32 s49, s49, 0
	s_add_u32 vcc_hi, s50, 0x10000
	s_addc_u32 s88, s51, 0
	s_mov_b32 s89, -2
	v_add_u32_e32 v241, 0x10000, v160
	v_add_u32_e32 v242, 0x14000, v160
	v_add_u32_e32 v243, 0x18000, v160
	v_add_u32_e32 v244, 0x1c000, v160
.LBB0_211:
	s_add_u32 s50, s48, 0x4000
	s_addc_u32 s51, s49, 0
	s_cmp_eq_u32 s89, 28
	s_cselect_b32 s54, s87, s50
	s_cselect_b32 s55, s43, s51
	s_cselect_b32 s52, vcc_lo, vcc_hi
	s_cselect_b32 s53, s35, s88
	s_add_u32 s50, s54, 0x8000
	s_addc_u32 s51, s55, 0
	s_add_i32 s90, 0, 0x10000

; #define PG8_STAGE(bufoff, gbase, voff) do { _Pragma("unroll") for (int _i = 0; _i < 2; ++_i) \
;         __builtin_amdgcn_global_load_lds((const unsigned*)((const char*)(gbase) + (voff)[_i]), (LAS unsigned*)(lds + (bufoff) + ldsw + _i * 8192), 16, 0, 0); } while (0)
; #define PG8_LDA(dst, b, h) do { _Pragma("unroll") for (int m = 0; m < 4; ++m) _Pragma("unroll") for (int k = 0; k < 2; ++k) dst[m][k] = *(const LAS bf16x8*)(lds + PG8_SA(b, h) + aoff + m * 2048 + k * 1024); } while (0)
; #define PG8_LDB(dst, b, h) do { _Pragma("unroll") for (int n = 0; n < 2; ++n) _Pragma("unroll") for (int k = 0; k < 2; ++k) dst[n][k] = *(const LAS bf16x8*)(lds + PG8_SB(b, h) + boff + n * 2048 + k * 1024); } while (0)
; #define PG8_SCHED __builtin_amdgcn_sched_barrier(0)
; template <class Epi, bool ALIGN_EPI>
; __device__ __forceinline__ void gemm_phase(LAS unsigned char* lds, const Gemm g, const StaticOrder& S, const Epi& E, const int tid) {
;     ...
;             PG8_LDB(B0, 0, 0); PG8_LDB(B1, 0, 1); PG8_SCHED; PG8_LDA(At, 0, 0); PG8_STAGE(PG8_SA(1, 1), a1 + hstepA, voffA);
	s_add_i32 s92, 0, 0x14000
	ds_read_b128 v[132:135], v241
	ds_read_b128 v[136:139], v241 offset:1024
	ds_read_b128 v[152:155], v241 offset:2048
	ds_read_b128 v[156:159], v241 offset:3072

; #define PG8_STAGE(bufoff, gbase, voff) do { _Pragma("unroll") for (int _i = 0; _i < 2; ++_i) \
;         __builtin_amdgcn_global_load_lds((const unsigned*)((const char*)(gbase) + (voff)[_i]), (LAS unsigned*)(lds + (bufoff) + ldsw + _i * 8192), 16, 0, 0); } while (0)
; #define PG8_LDA(dst, b, h) do { _Pragma("unroll") for (int m = 0; m < 4; ++m) _Pragma("unroll") for (int k = 0; k < 2; ++k) dst[m][k] = *(const LAS bf16x8*)(lds + PG8_SA(b, h) + aoff + m * 2048 + k * 1024); } while (0)
; #define PG8_LDB(dst, b, h) do { _Pragma("unroll") for (int n = 0; n < 2; ++n) _Pragma("unroll") for (int k = 0; k < 2; ++k) dst[n][k] = *(const LAS bf16x8*)(lds + PG8_SB(b, h) + boff + n * 2048 + k * 1024); } while (0)
; #define PG8_SCHED __builtin_amdgcn_sched_barrier(0)
; template <class Epi, bool ALIGN_EPI>
; __device__ __forceinline__ void gemm_phase(LAS unsigned char* lds, const Gemm g, const StaticOrder& S, const Epi& E, const int tid) {
;     ...
;             PG8_LDB(B0, 0, 0); PG8_LDB(B1, 0, 1); PG8_SCHED; PG8_LDA(At, 0, 0); PG8_STAGE(PG8_SA(1, 1), a1 + hstepA, voffA);
	ds_read_b128 v[162:165], v242
	ds_read_b128 v[166:169], v242 offset:1024
	ds_read_b128 v[170:173], v242 offset:2048
	ds_read_b128 v[174:177], v242 offset:3072
	s_add_i32 m0, s72, 0xc000
	ds_read_b128 v[178:181], v161
	ds_read_b128 v[182:185], v161 offset:1024
	ds_read_b128 v[186:189], v161 offset:2048
	ds_read_b128 v[190:193], v161 offset:3072
	ds_read_b128 v[194:197], v161 offset:4096
	ds_read_b128 v[198:201], v161 offset:5120
	ds_read_b128 v[214:217], v161 offset:6144

; #define PG8_STAGE(bufoff, gbase, voff) do { _Pragma("unroll") for (int _i = 0; _i < 2; ++_i) \
;         __builtin_amdgcn_global_load_lds((const unsigned*)((const char*)(gbase) + (voff)[_i]), (LAS unsigned*)(lds + (bufoff) + ldsw + _i * 8192), 16, 0, 0); } while (0)
; #define PG8_LDA(dst, b, h) do { _Pragma("unroll") for (int m = 0; m < 4; ++m) _Pragma("unroll") for (int k = 0; k < 2; ++k) dst[m][k] = *(const LAS bf16x8*)(lds + PG8_SA(b, h) + aoff + m * 2048 + k * 1024); } while (0)
; #define PG8_LDB(dst, b, h) do { _Pragma("unroll") for (int n = 0; n < 2; ++n) _Pragma("unroll") for (int k = 0; k < 2; ++k) dst[n][k] = *(const LAS bf16x8*)(lds + PG8_SB(b, h) + boff + n * 2048 + k * 1024); } while (0)
; #define PG8_MMA(ai, bj, At, Bt) do { __builtin_amdgcn_s_setprio(1); _Pragma("unroll") for (int m = 0; m < 4; ++m) _Pragma("unroll") for (int n = 0; n < 2; ++n) _Pragma("unroll") for (int k = 0; k < 2; ++k) \
;         acc[ai][bj][m][n] = __builtin_amdgcn_mfma_f32_16x16x32_bf16(Bt[n][k], At[m][k], acc[ai][bj][m][n], 0, 0, 0); __builtin_amdgcn_s_setprio(0); } while (0)
; #define PG8_WAIT_V(n) asm volatile("s_waitcnt vmcnt(" #n ")" ::: "memory")
; #define PG8_WAIT_L(n) asm volatile("s_waitcnt lgkmcnt(" #n ")" ::: "memory")
; #define PG8_BAR __builtin_amdgcn_s_barrier()
; #define PG8_SCHED __builtin_amdgcn_sched_barrier(0)
; template <class Epi, bool ALIGN_EPI>
; __device__ __forceinline__ void gemm_phase(LAS unsigned char* lds, const Gemm g, const StaticOrder& S, const Epi& E, const int tid) {
;     ...
;             PG8_LDB(B0, 0, 0); PG8_LDB(B1, 0, 1); PG8_SCHED; PG8_LDA(At, 0, 0); PG8_STAGE(PG8_SA(1, 1), a1 + hstepA, voffA);
;             PG8_WAIT_V(8); PG8_WAIT_L(0); PG8_BAR; PG8_MMA(0, 0, At, B0); PG8_MMA(0, 1, At, B1); PG8_BAR; PG8_SCHED;
	global_load_lds_dwordx4 v148, s[48:49]
	s_add_i32 m0, s72, 0xe000
	ds_read_b128 v[218:221], v161 offset:7168
	global_load_lds_dwordx4 v150, s[48:49]
	s_waitcnt vmcnt(8)
	s_waitcnt lgkmcnt(0)
	s_barrier


	v_mfma_f32_16x16x32_bf16 v[88:91], v[132:135], v[178:181], v[88:91]
	v_mfma_f32_16x16x32_bf16 v[124:127], v[152:155], v[178:181], v[124:127]
	v_mfma_f32_16x16x32_bf16 v[52:55], v[132:135], v[186:189], v[52:55]
	v_mfma_f32_16x16x32_bf16 v[120:123], v[152:155], v[186:189], v[120:123]
	v_mfma_f32_16x16x32_bf16 v[40:43], v[132:135], v[194:197], v[40:43]
	v_mfma_f32_16x16x32_bf16 v[116:119], v[152:155], v[194:197], v[116:119]
	v_mfma_f32_16x16x32_bf16 v[36:39], v[132:135], v[214:217], v[36:39]
	v_mfma_f32_16x16x32_bf16 v[112:115], v[152:155], v[214:217], v[112:115]
	v_mfma_f32_16x16x32_bf16 v[88:91], v[136:139], v[182:185], v[88:91]
	v_mfma_f32_16x16x32_bf16 v[124:127], v[156:159], v[182:185], v[124:127]
	v_mfma_f32_16x16x32_bf16 v[52:55], v[136:139], v[190:193], v[52:55]
	v_mfma_f32_16x16x32_bf16 v[120:123], v[156:159], v[190:193], v[120:123]
	v_mfma_f32_16x16x32_bf16 v[40:43], v[136:139], v[198:201], v[40:43]
	v_mfma_f32_16x16x32_bf16 v[116:119], v[156:159], v[198:201], v[116:119]
	v_mfma_f32_16x16x32_bf16 v[36:39], v[136:139], v[218:221], v[36:39]
	v_mfma_f32_16x16x32_bf16 v[112:115], v[156:159], v[218:221], v[112:115]


	v_mfma_f32_16x16x32_bf16 v[80:83], v[162:165], v[178:181], v[80:83]
	v_mfma_f32_16x16x32_bf16 v[128:131], v[170:173], v[178:181], v[128:131]
	v_mfma_f32_16x16x32_bf16 v[68:71], v[162:165], v[186:189], v[68:71]
	v_mfma_f32_16x16x32_bf16 v[108:111], v[170:173], v[186:189], v[108:111]
	v_mfma_f32_16x16x32_bf16 v[60:63], v[162:165], v[194:197], v[60:63]
	v_mfma_f32_16x16x32_bf16 v[104:107], v[170:173], v[194:197], v[104:107]
	v_mfma_f32_16x16x32_bf16 v[48:51], v[162:165], v[214:217], v[48:51]
	v_mfma_f32_16x16x32_bf16 v[100:103], v[170:173], v[214:217], v[100:103]
	v_mfma_f32_16x16x32_bf16 v[80:83], v[166:169], v[182:185], v[80:83]
	v_mfma_f32_16x16x32_bf16 v[128:131], v[174:177], v[182:185], v[128:131]
	v_mfma_f32_16x16x32_bf16 v[68:71], v[166:169], v[190:193], v[68:71]
	v_mfma_f32_16x16x32_bf16 v[108:111], v[174:177], v[190:193], v[108:111]
	v_mfma_f32_16x16x32_bf16 v[60:63], v[166:169], v[198:201], v[60:63]
	v_mfma_f32_16x16x32_bf16 v[104:107], v[174:177], v[198:201], v[104:107]
	v_mfma_f32_16x16x32_bf16 v[48:51], v[166:169], v[218:221], v[48:51]
	v_mfma_f32_16x16x32_bf16 v[100:103], v[174:177], v[218:221], v[100:103]

; #define PG8_STAGE(bufoff, gbase, voff) do { _Pragma("unroll") for (int _i = 0; _i < 2; ++_i) \
;         __builtin_amdgcn_global_load_lds((const unsigned*)((const char*)(gbase) + (voff)[_i]), (LAS unsigned*)(lds + (bufoff) + ldsw + _i * 8192), 16, 0, 0); } while (0)
; #define PG8_LDA(dst, b, h) do { _Pragma("unroll") for (int m = 0; m < 4; ++m) _Pragma("unroll") for (int k = 0; k < 2; ++k) dst[m][k] = *(const LAS bf16x8*)(lds + PG8_SA(b, h) + aoff + m * 2048 + k * 1024); } while (0)
; #define PG8_MMA(ai, bj, At, Bt) do { __builtin_amdgcn_s_setprio(1); _Pragma("unroll") for (int m = 0; m < 4; ++m) _Pragma("unroll") for (int n = 0; n < 2; ++n) _Pragma("unroll") for (int k = 0; k < 2; ++k) \
;         acc[ai][bj][m][n] = __builtin_amdgcn_mfma_f32_16x16x32_bf16(Bt[n][k], At[m][k], acc[ai][bj][m][n], 0, 0, 0); __builtin_amdgcn_s_setprio(0); } while (0)
; #define PG8_WAIT_V(n) asm volatile("s_waitcnt vmcnt(" #n ")" ::: "memory")
; #define PG8_WAIT_L(n) asm volatile("s_waitcnt lgkmcnt(" #n ")" ::: "memory")
; #define PG8_BAR __builtin_amdgcn_s_barrier()
; #define PG8_SCHED __builtin_amdgcn_sched_barrier(0)
; template <class Epi, bool ALIGN_EPI>
; __device__ __forceinline__ void gemm_phase(LAS unsigned char* lds, const Gemm g, const StaticOrder& S, const Epi& E, const int tid) {
;     ...
;             PG8_WAIT_V(8); PG8_WAIT_L(0); PG8_BAR; PG8_MMA(0, 0, At, B0); PG8_MMA(0, 1, At, B1); PG8_BAR; PG8_SCHED;
;             PG8_LDA(At, 0, 1); PG8_STAGE(PG8_SB(0, 0), b2, voffB); PG8_STAGE(PG8_SB(0, 1), b2 + hstepB, voffB); PG8_STAGE(PG8_SA(0, 0), a2, voffA);
	s_barrier
	s_add_i32 s90, s90, s71
	s_mov_b32 m0, s90
	ds_read_b128 v[178:181], v161 offset:16384
	ds_read_b128 v[182:185], v161 offset:17408
	ds_read_b128 v[186:189], v161 offset:18432
	ds_read_b128 v[190:193], v161 offset:19456


; #define PG8_STAGE(bufoff, gbase, voff) do { _Pragma("unroll") for (int _i = 0; _i < 2; ++_i) \
;         __builtin_amdgcn_global_load_lds((const unsigned*)((const char*)(gbase) + (voff)[_i]), (LAS unsigned*)(lds + (bufoff) + ldsw + _i * 8192), 16, 0, 0); } while (0)
; #define PG8_LDA(dst, b, h) do { _Pragma("unroll") for (int m = 0; m < 4; ++m) _Pragma("unroll") for (int k = 0; k < 2; ++k) dst[m][k] = *(const LAS bf16x8*)(lds + PG8_SA(b, h) + aoff + m * 2048 + k * 1024); } while (0)
; #define PG8_MMA(ai, bj, At, Bt) do { __builtin_amdgcn_s_setprio(1); _Pragma("unroll") for (int m = 0; m < 4; ++m) _Pragma("unroll") for (int n = 0; n < 2; ++n) _Pragma("unroll") for (int k = 0; k < 2; ++k) \
;         acc[ai][bj][m][n] = __builtin_amdgcn_mfma_f32_16x16x32_bf16(Bt[n][k], At[m][k], acc[ai][bj][m][n], 0, 0, 0); __builtin_amdgcn_s_setprio(0); } while (0)
; #define PG8_WAIT_V(n) asm volatile("s_waitcnt vmcnt(" #n ")" ::: "memory")
; #define PG8_WAIT_L(n) asm volatile("s_waitcnt lgkmcnt(" #n ")" ::: "memory")
; #define PG8_BAR __builtin_amdgcn_s_barrier()
; #define PG8_SCHED __builtin_amdgcn_sched_barrier(0)
; template <class Epi, bool ALIGN_EPI>
; __device__ __forceinline__ void gemm_phase(LAS unsigned char* lds, const Gemm g, const StaticOrder& S, const Epi& E, const int tid) {
;     ...
;             PG8_LDA(At, 0, 1); PG8_STAGE(PG8_SB(0, 0), b2, voffB); PG8_STAGE(PG8_SB(0, 1), b2 + hstepB, voffB); PG8_STAGE(PG8_SA(0, 0), a2, voffA);
;             PG8_WAIT_V(8); PG8_WAIT_L(0); PG8_BAR; PG8_MMA(1, 0, At, B0); PG8_MMA(1, 1, At, B1); PG8_BAR; PG8_SCHED;
	global_load_lds_dwordx4 v144, s[52:53]
	s_add_i32 m0, s90, 0x2000
	s_add_u32 s90, s52, 0x4000
	s_addc_u32 s91, s53, 0
	s_add_i32 s92, s92, s71
	global_load_lds_dwordx4 v140, s[52:53]
	s_mov_b32 m0, s92
	ds_read_b128 v[218:221], v161 offset:23552
	global_load_lds_dwordx4 v144, s[90:91]
	s_add_i32 m0, s92, 0x2000
	ds_read_b128 v[214:217], v161 offset:22528
	global_load_lds_dwordx4 v140, s[90:91]
	s_mov_b32 m0, s72
	ds_read_b128 v[198:201], v161 offset:21504
	global_load_lds_dwordx4 v146, s[54:55]
	s_mov_b32 m0, s73
	ds_read_b128 v[194:197], v161 offset:20480
	global_load_lds_dwordx4 v142, s[54:55]
	s_waitcnt vmcnt(8)
	s_waitcnt lgkmcnt(0)
	s_barrier


	v_mfma_f32_16x16x32_bf16 v[24:27], v[132:135], v[178:181], v[24:27]
	v_mfma_f32_16x16x32_bf16 v[92:95], v[152:155], v[178:181], v[92:95]
	v_mfma_f32_16x16x32_bf16 v[16:19], v[132:135], v[186:189], v[16:19]
	v_mfma_f32_16x16x32_bf16 v[84:87], v[152:155], v[186:189], v[84:87]
	v_mfma_f32_16x16x32_bf16 v[8:11], v[132:135], v[194:197], v[8:11]
	v_mfma_f32_16x16x32_bf16 v[76:79], v[152:155], v[194:197], v[76:79]
	v_mfma_f32_16x16x32_bf16 v[2:5], v[132:135], v[214:217], v[4:7]
	v_mfma_f32_16x16x32_bf16 v[64:67], v[152:155], v[214:217], v[64:67]
	v_mfma_f32_16x16x32_bf16 v[24:27], v[136:139], v[182:185], v[24:27]
	v_mfma_f32_16x16x32_bf16 v[92:95], v[156:159], v[182:185], v[92:95]
	v_mfma_f32_16x16x32_bf16 v[16:19], v[136:139], v[190:193], v[16:19]
	v_mfma_f32_16x16x32_bf16 v[84:87], v[156:159], v[190:193], v[84:87]
	v_mfma_f32_16x16x32_bf16 v[8:11], v[136:139], v[198:201], v[8:11]
	v_mfma_f32_16x16x32_bf16 v[76:79], v[156:159], v[198:201], v[76:79]
	v_mfma_f32_16x16x32_bf16 v[2:5], v[136:139], v[218:221], v[2:5]
	v_mfma_f32_16x16x32_bf16 v[64:67], v[156:159], v[218:221], v[64:67]


	v_mfma_f32_16x16x32_bf16 v[32:35], v[162:165], v[178:181], v[32:35]
	v_mfma_f32_16x16x32_bf16 v[72:75], v[170:173], v[178:181], v[72:75]
	v_mfma_f32_16x16x32_bf16 v[28:31], v[162:165], v[186:189], v[28:31]
	v_mfma_f32_16x16x32_bf16 v[96:99], v[170:173], v[186:189], v[96:99]
	v_mfma_f32_16x16x32_bf16 v[20:23], v[162:165], v[194:197], v[20:23]
	v_mfma_f32_16x16x32_bf16 v[56:59], v[170:173], v[194:197], v[56:59]
	v_mfma_f32_16x16x32_bf16 v[12:15], v[162:165], v[214:217], v[12:15]
	v_mfma_f32_16x16x32_bf16 v[44:47], v[170:173], v[214:217], v[44:47]
	v_mfma_f32_16x16x32_bf16 v[32:35], v[166:169], v[182:185], v[32:35]
	v_mfma_f32_16x16x32_bf16 v[72:75], v[174:177], v[182:185], v[72:75]
	v_mfma_f32_16x16x32_bf16 v[28:31], v[166:169], v[190:193], v[28:31]
	v_mfma_f32_16x16x32_bf16 v[96:99], v[174:177], v[190:193], v[96:99]
	v_mfma_f32_16x16x32_bf16 v[20:23], v[166:169], v[198:201], v[20:23]
	v_mfma_f32_16x16x32_bf16 v[56:59], v[174:177], v[198:201], v[56:59]
	v_mfma_f32_16x16x32_bf16 v[12:15], v[166:169], v[218:221], v[12:15]
	v_mfma_f32_16x16x32_bf16 v[44:47], v[174:177], v[218:221], v[44:47]

; #define PG8_STAGE(bufoff, gbase, voff) do { _Pragma("unroll") for (int _i = 0; _i < 2; ++_i) \
;         __builtin_amdgcn_global_load_lds((const unsigned*)((const char*)(gbase) + (voff)[_i]), (LAS unsigned*)(lds + (bufoff) + ldsw + _i * 8192), 16, 0, 0); } while (0)
; #define PG8_LDA(dst, b, h) do { _Pragma("unroll") for (int m = 0; m < 4; ++m) _Pragma("unroll") for (int k = 0; k < 2; ++k) dst[m][k] = *(const LAS bf16x8*)(lds + PG8_SA(b, h) + aoff + m * 2048 + k * 1024); } while (0)
; #define PG8_LDB(dst, b, h) do { _Pragma("unroll") for (int n = 0; n < 2; ++n) _Pragma("unroll") for (int k = 0; k < 2; ++k) dst[n][k] = *(const LAS bf16x8*)(lds + PG8_SB(b, h) + boff + n * 2048 + k * 1024); } while (0)
; #define PG8_MMA(ai, bj, At, Bt) do { __builtin_amdgcn_s_setprio(1); _Pragma("unroll") for (int m = 0; m < 4; ++m) _Pragma("unroll") for (int n = 0; n < 2; ++n) _Pragma("unroll") for (int k = 0; k < 2; ++k) \
;         acc[ai][bj][m][n] = __builtin_amdgcn_mfma_f32_16x16x32_bf16(Bt[n][k], At[m][k], acc[ai][bj][m][n], 0, 0, 0); __builtin_amdgcn_s_setprio(0); } while (0)
; #define PG8_WAIT_V(n) asm volatile("s_waitcnt vmcnt(" #n ")" ::: "memory")
; #define PG8_WAIT_L(n) asm volatile("s_waitcnt lgkmcnt(" #n ")" ::: "memory")
; #define PG8_BAR __builtin_amdgcn_s_barrier()
; #define PG8_SCHED __builtin_amdgcn_sched_barrier(0)
; template <class Epi, bool ALIGN_EPI>
; __device__ __forceinline__ void gemm_phase(LAS unsigned char* lds, const Gemm g, const StaticOrder& S, const Epi& E, const int tid) {
;     ...
;             PG8_WAIT_V(8); PG8_WAIT_L(0); PG8_BAR; PG8_MMA(1, 0, At, B0); PG8_MMA(1, 1, At, B1); PG8_BAR; PG8_SCHED;
;             PG8_LDB(B0, 1, 0); PG8_LDB(B1, 1, 1); PG8_SCHED; PG8_LDA(At, 1, 0); PG8_STAGE(PG8_SA(0, 1), a2 + hstepA, voffA);
	s_barrier
	s_add_i32 s90, 0, 0x18000

; #define PG8_STAGE(bufoff, gbase, voff) do { _Pragma("unroll") for (int _i = 0; _i < 2; ++_i) \
;         __builtin_amdgcn_global_load_lds((const unsigned*)((const char*)(gbase) + (voff)[_i]), (LAS unsigned*)(lds + (bufoff) + ldsw + _i * 8192), 16, 0, 0); } while (0)
; #define PG8_LDA(dst, b, h) do { _Pragma("unroll") for (int m = 0; m < 4; ++m) _Pragma("unroll") for (int k = 0; k < 2; ++k) dst[m][k] = *(const LAS bf16x8*)(lds + PG8_SA(b, h) + aoff + m * 2048 + k * 1024); } while (0)
; #define PG8_LDB(dst, b, h) do { _Pragma("unroll") for (int n = 0; n < 2; ++n) _Pragma("unroll") for (int k = 0; k < 2; ++k) dst[n][k] = *(const LAS bf16x8*)(lds + PG8_SB(b, h) + boff + n * 2048 + k * 1024); } while (0)
; #define PG8_SCHED __builtin_amdgcn_sched_barrier(0)
; template <class Epi, bool ALIGN_EPI>
; __device__ __forceinline__ void gemm_phase(LAS unsigned char* lds, const Gemm g, const StaticOrder& S, const Epi& E, const int tid) {
;     ...
;             PG8_LDB(B0, 1, 0); PG8_LDB(B1, 1, 1); PG8_SCHED; PG8_LDA(At, 1, 0); PG8_STAGE(PG8_SA(0, 1), a2 + hstepA, voffA);
	s_add_i32 s91, 0, 0x1c000
	ds_read_b128 v[132:135], v243
	ds_read_b128 v[136:139], v243 offset:1024
	ds_read_b128 v[152:155], v243 offset:2048
	ds_read_b128 v[156:159], v243 offset:3072

; #define PG8_STAGE(bufoff, gbase, voff) do { _Pragma("unroll") for (int _i = 0; _i < 2; ++_i) \
;         __builtin_amdgcn_global_load_lds((const unsigned*)((const char*)(gbase) + (voff)[_i]), (LAS unsigned*)(lds + (bufoff) + ldsw + _i * 8192), 16, 0, 0); } while (0)
; #define PG8_LDA(dst, b, h) do { _Pragma("unroll") for (int m = 0; m < 4; ++m) _Pragma("unroll") for (int k = 0; k < 2; ++k) dst[m][k] = *(const LAS bf16x8*)(lds + PG8_SA(b, h) + aoff + m * 2048 + k * 1024); } while (0)
; #define PG8_LDB(dst, b, h) do { _Pragma("unroll") for (int n = 0; n < 2; ++n) _Pragma("unroll") for (int k = 0; k < 2; ++k) dst[n][k] = *(const LAS bf16x8*)(lds + PG8_SB(b, h) + boff + n * 2048 + k * 1024); } while (0)
; #define PG8_SCHED __builtin_amdgcn_sched_barrier(0)
; template <class Epi, bool ALIGN_EPI>
; __device__ __forceinline__ void gemm_phase(LAS unsigned char* lds, const Gemm g, const StaticOrder& S, const Epi& E, const int tid) {
;     ...
;             PG8_LDB(B0, 1, 0); PG8_LDB(B1, 1, 1); PG8_SCHED; PG8_LDA(At, 1, 0); PG8_STAGE(PG8_SA(0, 1), a2 + hstepA, voffA);
	ds_read_b128 v[162:165], v244
	ds_read_b128 v[166:169], v244 offset:1024
	ds_read_b128 v[170:173], v244 offset:2048
	ds_read_b128 v[174:177], v244 offset:3072
	s_add_u32 s54, s54, 0x4000
	s_addc_u32 s55, s55, 0
	s_mov_b32 m0, s74
	ds_read_b128 v[178:181], v161 offset:32768
	ds_read_b128 v[182:185], v161 offset:33792
	ds_read_b128 v[186:189], v161 offset:34816
	ds_read_b128 v[190:193], v161 offset:35840
	ds_read_b128 v[194:197], v161 offset:36864
	ds_read_b128 v[198:201], v161 offset:37888
	ds_read_b128 v[214:217], v161 offset:38912

; #define PG8_STAGE(bufoff, gbase, voff) do { _Pragma("unroll") for (int _i = 0; _i < 2; ++_i) \
;         __builtin_amdgcn_global_load_lds((const unsigned*)((const char*)(gbase) + (voff)[_i]), (LAS unsigned*)(lds + (bufoff) + ldsw + _i * 8192), 16, 0, 0); } while (0)
; #define PG8_LDA(dst, b, h) do { _Pragma("unroll") for (int m = 0; m < 4; ++m) _Pragma("unroll") for (int k = 0; k < 2; ++k) dst[m][k] = *(const LAS bf16x8*)(lds + PG8_SA(b, h) + aoff + m * 2048 + k * 1024); } while (0)
; #define PG8_LDB(dst, b, h) do { _Pragma("unroll") for (int n = 0; n < 2; ++n) _Pragma("unroll") for (int k = 0; k < 2; ++k) dst[n][k] = *(const LAS bf16x8*)(lds + PG8_SB(b, h) + boff + n * 2048 + k * 1024); } while (0)
; #define PG8_MMA(ai, bj, At, Bt) do { __builtin_amdgcn_s_setprio(1); _Pragma("unroll") for (int m = 0; m < 4; ++m) _Pragma("unroll") for (int n = 0; n < 2; ++n) _Pragma("unroll") for (int k = 0; k < 2; ++k) \
;         acc[ai][bj][m][n] = __builtin_amdgcn_mfma_f32_16x16x32_bf16(Bt[n][k], At[m][k], acc[ai][bj][m][n], 0, 0, 0); __builtin_amdgcn_s_setprio(0); } while (0)
; #define PG8_WAIT_V(n) asm volatile("s_waitcnt vmcnt(" #n ")" ::: "memory")
; #define PG8_WAIT_L(n) asm volatile("s_waitcnt lgkmcnt(" #n ")" ::: "memory")
; #define PG8_BAR __builtin_amdgcn_s_barrier()
; #define PG8_SCHED __builtin_amdgcn_sched_barrier(0)
; template <class Epi, bool ALIGN_EPI>
; __device__ __forceinline__ void gemm_phase(LAS unsigned char* lds, const Gemm g, const StaticOrder& S, const Epi& E, const int tid) {
;     ...
;             PG8_LDB(B0, 1, 0); PG8_LDB(B1, 1, 1); PG8_SCHED; PG8_LDA(At, 1, 0); PG8_STAGE(PG8_SA(0, 1), a2 + hstepA, voffA);
;             PG8_WAIT_V(8); PG8_WAIT_L(0); PG8_BAR; PG8_MMA(0, 0, At, B0); PG8_MMA(0, 1, At, B1); PG8_BAR; PG8_SCHED;
	global_load_lds_dwordx4 v146, s[54:55]
	s_mov_b32 m0, s75
	ds_read_b128 v[218:221], v161 offset:39936
	global_load_lds_dwordx4 v142, s[54:55]
	s_waitcnt vmcnt(8)
	s_waitcnt lgkmcnt(0)
	s_barrier


	v_mfma_f32_16x16x32_bf16 v[88:91], v[132:135], v[178:181], v[88:91]
	v_mfma_f32_16x16x32_bf16 v[124:127], v[152:155], v[178:181], v[124:127]
	v_mfma_f32_16x16x32_bf16 v[52:55], v[132:135], v[186:189], v[52:55]
	v_mfma_f32_16x16x32_bf16 v[120:123], v[152:155], v[186:189], v[120:123]
	v_mfma_f32_16x16x32_bf16 v[40:43], v[132:135], v[194:197], v[40:43]
	v_mfma_f32_16x16x32_bf16 v[116:119], v[152:155], v[194:197], v[116:119]
	v_mfma_f32_16x16x32_bf16 v[36:39], v[132:135], v[214:217], v[36:39]
	v_mfma_f32_16x16x32_bf16 v[112:115], v[152:155], v[214:217], v[112:115]
	v_mfma_f32_16x16x32_bf16 v[88:91], v[136:139], v[182:185], v[88:91]
	v_mfma_f32_16x16x32_bf16 v[124:127], v[156:159], v[182:185], v[124:127]
	v_mfma_f32_16x16x32_bf16 v[52:55], v[136:139], v[190:193], v[52:55]
	v_mfma_f32_16x16x32_bf16 v[120:123], v[156:159], v[190:193], v[120:123]
	v_mfma_f32_16x16x32_bf16 v[40:43], v[136:139], v[198:201], v[40:43]
	v_mfma_f32_16x16x32_bf16 v[116:119], v[156:159], v[198:201], v[116:119]
	v_mfma_f32_16x16x32_bf16 v[36:39], v[136:139], v[218:221], v[36:39]
	v_mfma_f32_16x16x32_bf16 v[112:115], v[156:159], v[218:221], v[112:115]


	v_mfma_f32_16x16x32_bf16 v[80:83], v[162:165], v[178:181], v[80:83]
	v_mfma_f32_16x16x32_bf16 v[128:131], v[170:173], v[178:181], v[128:131]
	v_mfma_f32_16x16x32_bf16 v[68:71], v[162:165], v[186:189], v[68:71]
	v_mfma_f32_16x16x32_bf16 v[108:111], v[170:173], v[186:189], v[108:111]
	v_mfma_f32_16x16x32_bf16 v[60:63], v[162:165], v[194:197], v[60:63]
	v_mfma_f32_16x16x32_bf16 v[104:107], v[170:173], v[194:197], v[104:107]
	v_mfma_f32_16x16x32_bf16 v[48:51], v[162:165], v[214:217], v[48:51]
	v_mfma_f32_16x16x32_bf16 v[100:103], v[170:173], v[214:217], v[100:103]
	v_mfma_f32_16x16x32_bf16 v[80:83], v[166:169], v[182:185], v[80:83]
	v_mfma_f32_16x16x32_bf16 v[128:131], v[174:177], v[182:185], v[128:131]
	v_mfma_f32_16x16x32_bf16 v[68:71], v[166:169], v[190:193], v[68:71]
	v_mfma_f32_16x16x32_bf16 v[108:111], v[174:177], v[190:193], v[108:111]
	v_mfma_f32_16x16x32_bf16 v[60:63], v[166:169], v[198:201], v[60:63]
	v_mfma_f32_16x16x32_bf16 v[104:107], v[174:177], v[198:201], v[104:107]
	v_mfma_f32_16x16x32_bf16 v[48:51], v[166:169], v[218:221], v[48:51]
	v_mfma_f32_16x16x32_bf16 v[100:103], v[174:177], v[218:221], v[100:103]

; #define PG8_STAGE(bufoff, gbase, voff) do { _Pragma("unroll") for (int _i = 0; _i < 2; ++_i) \
;         __builtin_amdgcn_global_load_lds((const unsigned*)((const char*)(gbase) + (voff)[_i]), (LAS unsigned*)(lds + (bufoff) + ldsw + _i * 8192), 16, 0, 0); } while (0)
; #define PG8_LDA(dst, b, h) do { _Pragma("unroll") for (int m = 0; m < 4; ++m) _Pragma("unroll") for (int k = 0; k < 2; ++k) dst[m][k] = *(const LAS bf16x8*)(lds + PG8_SA(b, h) + aoff + m * 2048 + k * 1024); } while (0)
; #define PG8_MMA(ai, bj, At, Bt) do { __builtin_amdgcn_s_setprio(1); _Pragma("unroll") for (int m = 0; m < 4; ++m) _Pragma("unroll") for (int n = 0; n < 2; ++n) _Pragma("unroll") for (int k = 0; k < 2; ++k) \
;         acc[ai][bj][m][n] = __builtin_amdgcn_mfma_f32_16x16x32_bf16(Bt[n][k], At[m][k], acc[ai][bj][m][n], 0, 0, 0); __builtin_amdgcn_s_setprio(0); } while (0)
; #define PG8_WAIT_V(n) asm volatile("s_waitcnt vmcnt(" #n ")" ::: "memory")
; #define PG8_WAIT_L(n) asm volatile("s_waitcnt lgkmcnt(" #n ")" ::: "memory")
; #define PG8_BAR __builtin_amdgcn_s_barrier()
; #define PG8_SCHED __builtin_amdgcn_sched_barrier(0)
; template <class Epi, bool ALIGN_EPI>
; __device__ __forceinline__ void gemm_phase(LAS unsigned char* lds, const Gemm g, const StaticOrder& S, const Epi& E, const int tid) {
;     ...
;             PG8_WAIT_V(8); PG8_WAIT_L(0); PG8_BAR; PG8_MMA(0, 0, At, B0); PG8_MMA(0, 1, At, B1); PG8_BAR; PG8_SCHED;
;             PG8_LDA(At, 1, 1); PG8_STAGE(PG8_SB(1, 0), b3, voffB); PG8_STAGE(PG8_SB(1, 1), b3 + hstepB, voffB); PG8_STAGE(PG8_SA(1, 0), a3, voffA);
	s_barrier
	s_add_u32 s54, s52, 0x8000
	s_addc_u32 s55, s53, 0
	s_add_i32 s90, s90, s71
	s_mov_b32 m0, s90
	ds_read_b128 v[178:181], v161 offset:49152
	ds_read_b128 v[182:185], v161 offset:50176
	ds_read_b128 v[186:189], v161 offset:51200
	ds_read_b128 v[190:193], v161 offset:52224


; #define PG8_STAGE(bufoff, gbase, voff) do { _Pragma("unroll") for (int _i = 0; _i < 2; ++_i) \
;         __builtin_amdgcn_global_load_lds((const unsigned*)((const char*)(gbase) + (voff)[_i]), (LAS unsigned*)(lds + (bufoff) + ldsw + _i * 8192), 16, 0, 0); } while (0)
; #define PG8_LDA(dst, b, h) do { _Pragma("unroll") for (int m = 0; m < 4; ++m) _Pragma("unroll") for (int k = 0; k < 2; ++k) dst[m][k] = *(const LAS bf16x8*)(lds + PG8_SA(b, h) + aoff + m * 2048 + k * 1024); } while (0)
; #define PG8_MMA(ai, bj, At, Bt) do { __builtin_amdgcn_s_setprio(1); _Pragma("unroll") for (int m = 0; m < 4; ++m) _Pragma("unroll") for (int n = 0; n < 2; ++n) _Pragma("unroll") for (int k = 0; k < 2; ++k) \
;         acc[ai][bj][m][n] = __builtin_amdgcn_mfma_f32_16x16x32_bf16(Bt[n][k], At[m][k], acc[ai][bj][m][n], 0, 0, 0); __builtin_amdgcn_s_setprio(0); } while (0)
; #define PG8_WAIT_V(n) asm volatile("s_waitcnt vmcnt(" #n ")" ::: "memory")
; #define PG8_WAIT_L(n) asm volatile("s_waitcnt lgkmcnt(" #n ")" ::: "memory")
; #define PG8_BAR __builtin_amdgcn_s_barrier()
; #define PG8_SCHED __builtin_amdgcn_sched_barrier(0)
; template <class Epi, bool ALIGN_EPI>
; __device__ __forceinline__ void gemm_phase(LAS unsigned char* lds, const Gemm g, const StaticOrder& S, const Epi& E, const int tid) {
;     ...
;             PG8_LDA(At, 1, 1); PG8_STAGE(PG8_SB(1, 0), b3, voffB); PG8_STAGE(PG8_SB(1, 1), b3 + hstepB, voffB); PG8_STAGE(PG8_SA(1, 0), a3, voffA);
;             PG8_WAIT_V(8); PG8_WAIT_L(0); PG8_BAR; PG8_MMA(1, 0, At, B0); PG8_MMA(1, 1, At, B1); PG8_BAR; PG8_SCHED;
	global_load_lds_dwordx4 v144, s[54:55]
	s_add_i32 m0, s90, 0x2000
	s_add_u32 s52, s52, 0xc000
	s_addc_u32 s53, s53, 0
	global_load_lds_dwordx4 v140, s[54:55]
	s_add_i32 s54, s91, s71
	s_mov_b32 m0, s54
	ds_read_b128 v[218:221], v161 offset:56320
	global_load_lds_dwordx4 v144, s[52:53]
	s_add_i32 m0, s54, 0x2000
	ds_read_b128 v[214:217], v161 offset:55296
	global_load_lds_dwordx4 v140, s[52:53]
	s_mov_b32 m0, s79
	ds_read_b128 v[198:201], v161 offset:54272
	global_load_lds_dwordx4 v146, s[50:51]
	s_mov_b32 m0, s80
	ds_read_b128 v[194:197], v161 offset:53248
	global_load_lds_dwordx4 v142, s[50:51]
	s_waitcnt vmcnt(8)
	s_waitcnt lgkmcnt(0)
	s_barrier


	v_mfma_f32_16x16x32_bf16 v[24:27], v[132:135], v[178:181], v[24:27]
	v_mfma_f32_16x16x32_bf16 v[92:95], v[152:155], v[178:181], v[92:95]
	v_mfma_f32_16x16x32_bf16 v[16:19], v[132:135], v[186:189], v[16:19]
	v_mfma_f32_16x16x32_bf16 v[84:87], v[152:155], v[186:189], v[84:87]
	v_mfma_f32_16x16x32_bf16 v[6:9], v[132:135], v[194:197], v[8:11]
	v_mfma_f32_16x16x32_bf16 v[76:79], v[152:155], v[194:197], v[76:79]
	v_mfma_f32_16x16x32_bf16 v[2:5], v[132:135], v[214:217], v[2:5]
	v_mfma_f32_16x16x32_bf16 v[64:67], v[152:155], v[214:217], v[64:67]
	v_mfma_f32_16x16x32_bf16 v[24:27], v[136:139], v[182:185], v[24:27]
	v_mfma_f32_16x16x32_bf16 v[92:95], v[156:159], v[182:185], v[92:95]
	v_mfma_f32_16x16x32_bf16 v[16:19], v[136:139], v[190:193], v[16:19]
	v_mfma_f32_16x16x32_bf16 v[84:87], v[156:159], v[190:193], v[84:87]
	v_mfma_f32_16x16x32_bf16 v[8:11], v[136:139], v[198:201], v[6:9]
	v_mfma_f32_16x16x32_bf16 v[76:79], v[156:159], v[198:201], v[76:79]
	v_mfma_f32_16x16x32_bf16 v[4:7], v[136:139], v[218:221], v[2:5]
	v_mfma_f32_16x16x32_bf16 v[64:67], v[156:159], v[218:221], v[64:67]


	v_mfma_f32_16x16x32_bf16 v[32:35], v[162:165], v[178:181], v[32:35]
	v_mfma_f32_16x16x32_bf16 v[72:75], v[170:173], v[178:181], v[72:75]
	v_mfma_f32_16x16x32_bf16 v[28:31], v[162:165], v[186:189], v[28:31]
	v_mfma_f32_16x16x32_bf16 v[96:99], v[170:173], v[186:189], v[96:99]
	v_mfma_f32_16x16x32_bf16 v[20:23], v[162:165], v[194:197], v[20:23]
	v_mfma_f32_16x16x32_bf16 v[56:59], v[170:173], v[194:197], v[56:59]
	v_mfma_f32_16x16x32_bf16 v[12:15], v[162:165], v[214:217], v[12:15]
	v_mfma_f32_16x16x32_bf16 v[44:47], v[170:173], v[214:217], v[44:47]
	v_mfma_f32_16x16x32_bf16 v[32:35], v[166:169], v[182:185], v[32:35]
	v_mfma_f32_16x16x32_bf16 v[72:75], v[174:177], v[182:185], v[72:75]
	v_mfma_f32_16x16x32_bf16 v[28:31], v[166:169], v[190:193], v[28:31]
	v_mfma_f32_16x16x32_bf16 v[96:99], v[174:177], v[190:193], v[96:99]
	v_mfma_f32_16x16x32_bf16 v[20:23], v[166:169], v[198:201], v[20:23]
	v_mfma_f32_16x16x32_bf16 v[56:59], v[174:177], v[198:201], v[56:59]
	v_mfma_f32_16x16x32_bf16 v[12:15], v[166:169], v[218:221], v[12:15]
	v_mfma_f32_16x16x32_bf16 v[44:47], v[174:177], v[218:221], v[44:47]

; #define PG8_MMA(ai, bj, At, Bt) do { __builtin_amdgcn_s_setprio(1); _Pragma("unroll") for (int m = 0; m < 4; ++m) _Pragma("unroll") for (int n = 0; n < 2; ++n) _Pragma("unroll") for (int k = 0; k < 2; ++k) \
;         acc[ai][bj][m][n] = __builtin_amdgcn_mfma_f32_16x16x32_bf16(Bt[n][k], At[m][k], acc[ai][bj][m][n], 0, 0, 0); __builtin_amdgcn_s_setprio(0); } while (0)
; #define PG8_WAIT_V(n) asm volatile("s_waitcnt vmcnt(" #n ")" ::: "memory")
; #define PG8_WAIT_L(n) asm volatile("s_waitcnt lgkmcnt(" #n ")" ::: "memory")
; #define PG8_BAR __builtin_amdgcn_s_barrier()
; #define PG8_SCHED __builtin_amdgcn_sched_barrier(0)
; template <class Epi, bool ALIGN_EPI>
; __device__ __forceinline__ void gemm_phase(LAS unsigned char* lds, const Gemm g, const StaticOrder& S, const Epi& E, const int tid) {
;     ...
;             PG8_WAIT_V(8); PG8_WAIT_L(0); PG8_BAR; PG8_MMA(1, 0, At, B0); PG8_MMA(1, 1, At, B1); PG8_BAR; PG8_SCHED;
;         }
;         if constexpr (ALIGN_EPI) { if (wr == 0) PG8_BAR; }
	s_barrier
	s_add_i32 s89, s89, 2
	s_add_u32 s48, s48, 0x10000
	s_addc_u32 s49, s49, 0
	s_add_u32 vcc_hi, vcc_hi, 0x10000
	s_addc_u32 s88, s88, 0
	s_cmp_gt_u32 s89, 29
	s_cbranch_scc0 .LBB0_211
	s_and_b64 vcc, exec, s[22:23]
	s_cbranch_vccz .LBB0_214
	s_barrier

; #define PG8_STAGE(bufoff, gbase, voff) do { _Pragma("unroll") for (int _i = 0; _i < 2; ++_i) \
;         __builtin_amdgcn_global_load_lds((const unsigned*)((const char*)(gbase) + (voff)[_i]), (LAS unsigned*)(lds + (bufoff) + ldsw + _i * 8192), 16, 0, 0); } while (0)
; #define PG8_LDA(dst, b, h) do { _Pragma("unroll") for (int m = 0; m < 4; ++m) _Pragma("unroll") for (int k = 0; k < 2; ++k) dst[m][k] = *(const LAS bf16x8*)(lds + PG8_SA(b, h) + aoff + m * 2048 + k * 1024); } while (0)
; #define PG8_LDB(dst, b, h) do { _Pragma("unroll") for (int n = 0; n < 2; ++n) _Pragma("unroll") for (int k = 0; k < 2; ++k) dst[n][k] = *(const LAS bf16x8*)(lds + PG8_SB(b, h) + boff + n * 2048 + k * 1024); } while (0)
; #define PG8_SCHED __builtin_amdgcn_sched_barrier(0)
; template <class Epi, bool ALIGN_EPI>
; __device__ __forceinline__ void gemm_phase(LAS unsigned char* lds, const Gemm g, const StaticOrder& S, const Epi& E, const int tid) {
;     ...
;         const char* nA = has_next ? (const char*)g.A + (size_t)nxt.pm * tstepA + (size_t)nxt.pn * g.acs : cA; const char* nB = has_next ? (const char*)g.Bt + (size_t)nxt.pn * tstepB : cB;
;         for (int t = 0; t < nt; t += 2) {
;             const bool last = (t == nt - 2);
;             const char* a1 = cA + (size_t)(t + 1) * kstepA;
;             const char* a2 = last ? nA : cA + (size_t)(t + 2) * kstepA; const char* b2 = last ? nB : cB + (size_t)(t + 2) * kstepB;
;             const char* a3 = a2 + kstepA; const char* b3 = b2 + kstepB;
;             PG8_LDB(B0, 0, 0); PG8_LDB(B1, 0, 1); PG8_SCHED; PG8_LDA(At, 0, 0); PG8_STAGE(PG8_SA(1, 1), a1 + hstepA, voffA);
.LBB0_293:
	s_add_u32 s84, s10, 0x10000
	s_addc_u32 s85, s11, 0
	s_add_u32 s10, s22, 0xc000
	s_addc_u32 s11, s23, 0
	s_mov_b32 s86, -2
	v_add_u32_e32 v241, 0x10000, v154
	v_add_u32_e32 v242, 0x14000, v154
	v_add_u32_e32 v243, 0x18000, v154
	v_add_u32_e32 v244, 0x1c000, v154
.LBB0_294:
	s_add_u32 s22, s10, 0x4000
	s_addc_u32 s23, s11, 0
	s_cmpk_eq_i32 s86, 0x54
	s_cselect_b32 s42, s48, s22
	s_cselect_b32 s43, s49, s23
	s_cselect_b32 s34, s50, s84
	s_cselect_b32 s35, s51, s85
	s_add_u32 s22, s42, 0x8000
	s_addc_u32 s23, s43, 0
	s_add_i32 s87, 0, 0x10000

; #define PG8_STAGE(bufoff, gbase, voff) do { _Pragma("unroll") for (int _i = 0; _i < 2; ++_i) \
;         __builtin_amdgcn_global_load_lds((const unsigned*)((const char*)(gbase) + (voff)[_i]), (LAS unsigned*)(lds + (bufoff) + ldsw + _i * 8192), 16, 0, 0); } while (0)
; #define PG8_LDA(dst, b, h) do { _Pragma("unroll") for (int m = 0; m < 4; ++m) _Pragma("unroll") for (int k = 0; k < 2; ++k) dst[m][k] = *(const LAS bf16x8*)(lds + PG8_SA(b, h) + aoff + m * 2048 + k * 1024); } while (0)
; #define PG8_LDB(dst, b, h) do { _Pragma("unroll") for (int n = 0; n < 2; ++n) _Pragma("unroll") for (int k = 0; k < 2; ++k) dst[n][k] = *(const LAS bf16x8*)(lds + PG8_SB(b, h) + boff + n * 2048 + k * 1024); } while (0)
; #define PG8_SCHED __builtin_amdgcn_sched_barrier(0)
; template <class Epi, bool ALIGN_EPI>
; __device__ __forceinline__ void gemm_phase(LAS unsigned char* lds, const Gemm g, const StaticOrder& S, const Epi& E, const int tid) {
;     ...
;             PG8_LDB(B0, 0, 0); PG8_LDB(B1, 0, 1); PG8_SCHED; PG8_LDA(At, 0, 0); PG8_STAGE(PG8_SA(1, 1), a1 + hstepA, voffA);
	s_add_i32 s90, 0, 0x14000
	s_waitcnt lgkmcnt(0)
	ds_read_b128 v[132:135], v241
	ds_read_b128 v[148:151], v241 offset:1024
	ds_read_b128 v[156:159], v241 offset:2048
	ds_read_b128 v[160:163], v241 offset:3072

; #define PG8_STAGE(bufoff, gbase, voff) do { _Pragma("unroll") for (int _i = 0; _i < 2; ++_i) \
;         __builtin_amdgcn_global_load_lds((const unsigned*)((const char*)(gbase) + (voff)[_i]), (LAS unsigned*)(lds + (bufoff) + ldsw + _i * 8192), 16, 0, 0); } while (0)
; #define PG8_LDA(dst, b, h) do { _Pragma("unroll") for (int m = 0; m < 4; ++m) _Pragma("unroll") for (int k = 0; k < 2; ++k) dst[m][k] = *(const LAS bf16x8*)(lds + PG8_SA(b, h) + aoff + m * 2048 + k * 1024); } while (0)
; #define PG8_LDB(dst, b, h) do { _Pragma("unroll") for (int n = 0; n < 2; ++n) _Pragma("unroll") for (int k = 0; k < 2; ++k) dst[n][k] = *(const LAS bf16x8*)(lds + PG8_SB(b, h) + boff + n * 2048 + k * 1024); } while (0)
; #define PG8_SCHED __builtin_amdgcn_sched_barrier(0)
; template <class Epi, bool ALIGN_EPI>
; __device__ __forceinline__ void gemm_phase(LAS unsigned char* lds, const Gemm g, const StaticOrder& S, const Epi& E, const int tid) {
;     ...
;             PG8_LDB(B0, 0, 0); PG8_LDB(B1, 0, 1); PG8_SCHED; PG8_LDA(At, 0, 0); PG8_STAGE(PG8_SA(1, 1), a1 + hstepA, voffA);
	ds_read_b128 v[164:167], v242
	ds_read_b128 v[168:171], v242 offset:1024
	ds_read_b128 v[172:175], v242 offset:2048
	ds_read_b128 v[176:179], v242 offset:3072
	s_add_i32 m0, s57, 0xc000
	ds_read_b128 v[180:183], v155
	ds_read_b128 v[184:187], v155 offset:1024
	ds_read_b128 v[188:191], v155 offset:2048
	ds_read_b128 v[192:195], v155 offset:3072
	ds_read_b128 v[196:199], v155 offset:4096
	ds_read_b128 v[214:217], v155 offset:5120
	ds_read_b128 v[218:221], v155 offset:6144

; #define PG8_STAGE(bufoff, gbase, voff) do { _Pragma("unroll") for (int _i = 0; _i < 2; ++_i) \
;         __builtin_amdgcn_global_load_lds((const unsigned*)((const char*)(gbase) + (voff)[_i]), (LAS unsigned*)(lds + (bufoff) + ldsw + _i * 8192), 16, 0, 0); } while (0)
; #define PG8_LDA(dst, b, h) do { _Pragma("unroll") for (int m = 0; m < 4; ++m) _Pragma("unroll") for (int k = 0; k < 2; ++k) dst[m][k] = *(const LAS bf16x8*)(lds + PG8_SA(b, h) + aoff + m * 2048 + k * 1024); } while (0)
; #define PG8_LDB(dst, b, h) do { _Pragma("unroll") for (int n = 0; n < 2; ++n) _Pragma("unroll") for (int k = 0; k < 2; ++k) dst[n][k] = *(const LAS bf16x8*)(lds + PG8_SB(b, h) + boff + n * 2048 + k * 1024); } while (0)
; #define PG8_MMA(ai, bj, At, Bt) do { __builtin_amdgcn_s_setprio(1); _Pragma("unroll") for (int m = 0; m < 4; ++m) _Pragma("unroll") for (int n = 0; n < 2; ++n) _Pragma("unroll") for (int k = 0; k < 2; ++k) \
;         acc[ai][bj][m][n] = __builtin_amdgcn_mfma_f32_16x16x32_bf16(Bt[n][k], At[m][k], acc[ai][bj][m][n], 0, 0, 0); __builtin_amdgcn_s_setprio(0); } while (0)
; #define PG8_WAIT_V(n) asm volatile("s_waitcnt vmcnt(" #n ")" ::: "memory")
; #define PG8_WAIT_L(n) asm volatile("s_waitcnt lgkmcnt(" #n ")" ::: "memory")
; #define PG8_BAR __builtin_amdgcn_s_barrier()
; #define PG8_SCHED __builtin_amdgcn_sched_barrier(0)
; template <class Epi, bool ALIGN_EPI>
; __device__ __forceinline__ void gemm_phase(LAS unsigned char* lds, const Gemm g, const StaticOrder& S, const Epi& E, const int tid) {
;     ...
;             PG8_LDB(B0, 0, 0); PG8_LDB(B1, 0, 1); PG8_SCHED; PG8_LDA(At, 0, 0); PG8_STAGE(PG8_SA(1, 1), a1 + hstepA, voffA);
;             PG8_WAIT_V(8); PG8_WAIT_L(0); PG8_BAR; PG8_MMA(0, 0, At, B0); PG8_MMA(0, 1, At, B1); PG8_BAR; PG8_SCHED;
	global_load_lds_dwordx4 v144, s[10:11]
	s_add_i32 m0, s57, 0xe000
	ds_read_b128 v[222:225], v155 offset:7168
	global_load_lds_dwordx4 v146, s[10:11]
	s_waitcnt vmcnt(8)
	s_waitcnt lgkmcnt(0)
	s_barrier


; #define PG8_MMA(ai, bj, At, Bt) do { __builtin_amdgcn_s_setprio(1); _Pragma("unroll") for (int m = 0; m < 4; ++m) _Pragma("unroll") for (int n = 0; n < 2; ++n) _Pragma("unroll") for (int k = 0; k < 2; ++k) \
;         acc[ai][bj][m][n] = __builtin_amdgcn_mfma_f32_16x16x32_bf16(Bt[n][k], At[m][k], acc[ai][bj][m][n], 0, 0, 0); __builtin_amdgcn_s_setprio(0); } while (0)
; #define PG8_WAIT_V(n) asm volatile("s_waitcnt vmcnt(" #n ")" ::: "memory")
; #define PG8_WAIT_L(n) asm volatile("s_waitcnt lgkmcnt(" #n ")" ::: "memory")
; #define PG8_BAR __builtin_amdgcn_s_barrier()
; #define PG8_SCHED __builtin_amdgcn_sched_barrier(0)
; template <class Epi, bool ALIGN_EPI>
; __device__ __forceinline__ void gemm_phase(LAS unsigned char* lds, const Gemm g, const StaticOrder& S, const Epi& E, const int tid) {
;     ...
;             PG8_WAIT_V(8); PG8_WAIT_L(0); PG8_BAR; PG8_MMA(0, 0, At, B0); PG8_MMA(0, 1, At, B1); PG8_BAR; PG8_SCHED;
	v_mfma_f32_16x16x32_bf16 v[8:11], v[132:135], v[180:183], v[8:11]
	v_mfma_f32_16x16x32_bf16 v[56:59], v[156:159], v[180:183], v[56:59]
	v_mfma_f32_16x16x32_bf16 v[52:55], v[132:135], v[188:191], v[52:55]
	v_mfma_f32_16x16x32_bf16 v[48:51], v[156:159], v[188:191], v[48:51]
	v_mfma_f32_16x16x32_bf16 v[44:47], v[132:135], v[196:199], v[44:47]
	v_mfma_f32_16x16x32_bf16 v[40:43], v[156:159], v[196:199], v[40:43]
	v_mfma_f32_16x16x32_bf16 v[36:39], v[132:135], v[218:221], v[36:39]
	v_mfma_f32_16x16x32_bf16 v[32:35], v[156:159], v[218:221], v[32:35]
	v_mfma_f32_16x16x32_bf16 v[8:11], v[148:151], v[184:187], v[8:11]
	v_mfma_f32_16x16x32_bf16 v[56:59], v[160:163], v[184:187], v[56:59]
	v_mfma_f32_16x16x32_bf16 v[52:55], v[148:151], v[192:195], v[52:55]
	v_mfma_f32_16x16x32_bf16 v[48:51], v[160:163], v[192:195], v[48:51]
	v_mfma_f32_16x16x32_bf16 v[44:47], v[148:151], v[214:217], v[44:47]
	v_mfma_f32_16x16x32_bf16 v[40:43], v[160:163], v[214:217], v[40:43]
	v_mfma_f32_16x16x32_bf16 v[36:39], v[148:151], v[222:225], v[36:39]
	v_mfma_f32_16x16x32_bf16 v[32:35], v[160:163], v[222:225], v[32:35]


; #define PG8_MMA(ai, bj, At, Bt) do { __builtin_amdgcn_s_setprio(1); _Pragma("unroll") for (int m = 0; m < 4; ++m) _Pragma("unroll") for (int n = 0; n < 2; ++n) _Pragma("unroll") for (int k = 0; k < 2; ++k) \
;         acc[ai][bj][m][n] = __builtin_amdgcn_mfma_f32_16x16x32_bf16(Bt[n][k], At[m][k], acc[ai][bj][m][n], 0, 0, 0); __builtin_amdgcn_s_setprio(0); } while (0)
; #define PG8_WAIT_V(n) asm volatile("s_waitcnt vmcnt(" #n ")" ::: "memory")
; #define PG8_WAIT_L(n) asm volatile("s_waitcnt lgkmcnt(" #n ")" ::: "memory")
; #define PG8_BAR __builtin_amdgcn_s_barrier()
; #define PG8_SCHED __builtin_amdgcn_sched_barrier(0)
; template <class Epi, bool ALIGN_EPI>
; __device__ __forceinline__ void gemm_phase(LAS unsigned char* lds, const Gemm g, const StaticOrder& S, const Epi& E, const int tid) {
;     ...
;             PG8_WAIT_V(8); PG8_WAIT_L(0); PG8_BAR; PG8_MMA(0, 0, At, B0); PG8_MMA(0, 1, At, B1); PG8_BAR; PG8_SCHED;
	v_mfma_f32_16x16x32_bf16 v[2:5], v[164:167], v[180:183], v[4:7]
	v_mfma_f32_16x16x32_bf16 v[28:31], v[172:175], v[180:183], v[28:31]
	v_mfma_f32_16x16x32_bf16 v[96:99], v[164:167], v[188:191], v[96:99]
	v_mfma_f32_16x16x32_bf16 v[92:95], v[172:175], v[188:191], v[92:95]
	v_mfma_f32_16x16x32_bf16 v[88:91], v[164:167], v[196:199], v[88:91]
	v_mfma_f32_16x16x32_bf16 v[84:87], v[172:175], v[196:199], v[84:87]
	v_mfma_f32_16x16x32_bf16 v[80:83], v[164:167], v[218:221], v[80:83]
	v_mfma_f32_16x16x32_bf16 v[76:79], v[172:175], v[218:221], v[76:79]
	v_mfma_f32_16x16x32_bf16 v[2:5], v[168:171], v[184:187], v[2:5]
	v_mfma_f32_16x16x32_bf16 v[28:31], v[176:179], v[184:187], v[28:31]
	v_mfma_f32_16x16x32_bf16 v[96:99], v[168:171], v[192:195], v[96:99]
	v_mfma_f32_16x16x32_bf16 v[92:95], v[176:179], v[192:195], v[92:95]
	v_mfma_f32_16x16x32_bf16 v[88:91], v[168:171], v[214:217], v[88:91]
	v_mfma_f32_16x16x32_bf16 v[84:87], v[176:179], v[214:217], v[84:87]
	v_mfma_f32_16x16x32_bf16 v[80:83], v[168:171], v[222:225], v[80:83]
	v_mfma_f32_16x16x32_bf16 v[76:79], v[176:179], v[222:225], v[76:79]

; #define PG8_STAGE(bufoff, gbase, voff) do { _Pragma("unroll") for (int _i = 0; _i < 2; ++_i) \
;         __builtin_amdgcn_global_load_lds((const unsigned*)((const char*)(gbase) + (voff)[_i]), (LAS unsigned*)(lds + (bufoff) + ldsw + _i * 8192), 16, 0, 0); } while (0)
; #define PG8_LDA(dst, b, h) do { _Pragma("unroll") for (int m = 0; m < 4; ++m) _Pragma("unroll") for (int k = 0; k < 2; ++k) dst[m][k] = *(const LAS bf16x8*)(lds + PG8_SA(b, h) + aoff + m * 2048 + k * 1024); } while (0)
; #define PG8_MMA(ai, bj, At, Bt) do { __builtin_amdgcn_s_setprio(1); _Pragma("unroll") for (int m = 0; m < 4; ++m) _Pragma("unroll") for (int n = 0; n < 2; ++n) _Pragma("unroll") for (int k = 0; k < 2; ++k) \
;         acc[ai][bj][m][n] = __builtin_amdgcn_mfma_f32_16x16x32_bf16(Bt[n][k], At[m][k], acc[ai][bj][m][n], 0, 0, 0); __builtin_amdgcn_s_setprio(0); } while (0)
; #define PG8_WAIT_V(n) asm volatile("s_waitcnt vmcnt(" #n ")" ::: "memory")
; #define PG8_WAIT_L(n) asm volatile("s_waitcnt lgkmcnt(" #n ")" ::: "memory")
; #define PG8_BAR __builtin_amdgcn_s_barrier()
; #define PG8_SCHED __builtin_amdgcn_sched_barrier(0)
; template <class Epi, bool ALIGN_EPI>
; __device__ __forceinline__ void gemm_phase(LAS unsigned char* lds, const Gemm g, const StaticOrder& S, const Epi& E, const int tid) {
;     ...
;             PG8_WAIT_V(8); PG8_WAIT_L(0); PG8_BAR; PG8_MMA(0, 0, At, B0); PG8_MMA(0, 1, At, B1); PG8_BAR; PG8_SCHED;
;             PG8_LDA(At, 0, 1); PG8_STAGE(PG8_SB(0, 0), b2, voffB); PG8_STAGE(PG8_SB(0, 1), b2 + hstepB, voffB); PG8_STAGE(PG8_SA(0, 0), a2, voffA);
	s_barrier
	s_add_i32 s87, s87, s56
	s_mov_b32 m0, s87
	ds_read_b128 v[180:183], v155 offset:16384
	ds_read_b128 v[184:187], v155 offset:17408
	ds_read_b128 v[188:191], v155 offset:18432
	ds_read_b128 v[192:195], v155 offset:19456


; #define PG8_STAGE(bufoff, gbase, voff) do { _Pragma("unroll") for (int _i = 0; _i < 2; ++_i) \
;         __builtin_amdgcn_global_load_lds((const unsigned*)((const char*)(gbase) + (voff)[_i]), (LAS unsigned*)(lds + (bufoff) + ldsw + _i * 8192), 16, 0, 0); } while (0)
; #define PG8_LDA(dst, b, h) do { _Pragma("unroll") for (int m = 0; m < 4; ++m) _Pragma("unroll") for (int k = 0; k < 2; ++k) dst[m][k] = *(const LAS bf16x8*)(lds + PG8_SA(b, h) + aoff + m * 2048 + k * 1024); } while (0)
; #define PG8_MMA(ai, bj, At, Bt) do { __builtin_amdgcn_s_setprio(1); _Pragma("unroll") for (int m = 0; m < 4; ++m) _Pragma("unroll") for (int n = 0; n < 2; ++n) _Pragma("unroll") for (int k = 0; k < 2; ++k) \
;         acc[ai][bj][m][n] = __builtin_amdgcn_mfma_f32_16x16x32_bf16(Bt[n][k], At[m][k], acc[ai][bj][m][n], 0, 0, 0); __builtin_amdgcn_s_setprio(0); } while (0)
; #define PG8_WAIT_V(n) asm volatile("s_waitcnt vmcnt(" #n ")" ::: "memory")
; #define PG8_WAIT_L(n) asm volatile("s_waitcnt lgkmcnt(" #n ")" ::: "memory")
; #define PG8_BAR __builtin_amdgcn_s_barrier()
; #define PG8_SCHED __builtin_amdgcn_sched_barrier(0)
; template <class Epi, bool ALIGN_EPI>
; __device__ __forceinline__ void gemm_phase(LAS unsigned char* lds, const Gemm g, const StaticOrder& S, const Epi& E, const int tid) {
;     ...
;             PG8_LDA(At, 0, 1); PG8_STAGE(PG8_SB(0, 0), b2, voffB); PG8_STAGE(PG8_SB(0, 1), b2 + hstepB, voffB); PG8_STAGE(PG8_SA(0, 0), a2, voffA);
;             PG8_WAIT_V(8); PG8_WAIT_L(0); PG8_BAR; PG8_MMA(1, 0, At, B0); PG8_MMA(1, 1, At, B1); PG8_BAR; PG8_SCHED;
	global_load_lds_dwordx4 v140, s[34:35]
	s_add_i32 m0, s87, 0x2000
	s_add_u32 s88, s34, 0x4000
	s_addc_u32 s89, s35, 0
	s_add_i32 s87, s90, s56
	global_load_lds_dwordx4 v136, s[34:35]
	s_mov_b32 m0, s87
	ds_read_b128 v[222:225], v155 offset:23552
	global_load_lds_dwordx4 v140, s[88:89]
	s_add_i32 m0, s87, 0x2000
	ds_read_b128 v[218:221], v155 offset:22528
	global_load_lds_dwordx4 v136, s[88:89]
	s_mov_b32 m0, s57
	ds_read_b128 v[214:217], v155 offset:21504
	global_load_lds_dwordx4 v142, s[42:43]
	s_mov_b32 m0, s60
	ds_read_b128 v[196:199], v155 offset:20480
	global_load_lds_dwordx4 v138, s[42:43]
	s_waitcnt vmcnt(8)
	s_waitcnt lgkmcnt(0)
	s_barrier


; #define PG8_MMA(ai, bj, At, Bt) do { __builtin_amdgcn_s_setprio(1); _Pragma("unroll") for (int m = 0; m < 4; ++m) _Pragma("unroll") for (int n = 0; n < 2; ++n) _Pragma("unroll") for (int k = 0; k < 2; ++k) \
;         acc[ai][bj][m][n] = __builtin_amdgcn_mfma_f32_16x16x32_bf16(Bt[n][k], At[m][k], acc[ai][bj][m][n], 0, 0, 0); __builtin_amdgcn_s_setprio(0); } while (0)
; #define PG8_WAIT_V(n) asm volatile("s_waitcnt vmcnt(" #n ")" ::: "memory")
; #define PG8_WAIT_L(n) asm volatile("s_waitcnt lgkmcnt(" #n ")" ::: "memory")
; #define PG8_BAR __builtin_amdgcn_s_barrier()
; #define PG8_SCHED __builtin_amdgcn_sched_barrier(0)
; template <class Epi, bool ALIGN_EPI>
; __device__ __forceinline__ void gemm_phase(LAS unsigned char* lds, const Gemm g, const StaticOrder& S, const Epi& E, const int tid) {
;     ...
;             PG8_WAIT_V(8); PG8_WAIT_L(0); PG8_BAR; PG8_MMA(1, 0, At, B0); PG8_MMA(1, 1, At, B1); PG8_BAR; PG8_SCHED;
	v_mfma_f32_16x16x32_bf16 v[24:27], v[132:135], v[180:183], v[24:27]
	v_mfma_f32_16x16x32_bf16 v[20:23], v[156:159], v[180:183], v[20:23]
	v_mfma_f32_16x16x32_bf16 v[64:67], v[132:135], v[188:191], v[64:67]
	v_mfma_f32_16x16x32_bf16 v[72:75], v[156:159], v[188:191], v[72:75]
	v_mfma_f32_16x16x32_bf16 v[16:19], v[132:135], v[196:199], v[16:19]
	v_mfma_f32_16x16x32_bf16 v[12:15], v[156:159], v[196:199], v[12:15]
	v_mfma_f32_16x16x32_bf16 v[60:63], v[132:135], v[218:221], v[60:63]
	v_mfma_f32_16x16x32_bf16 v[68:71], v[156:159], v[218:221], v[68:71]
	v_mfma_f32_16x16x32_bf16 v[24:27], v[148:151], v[184:187], v[24:27]
	v_mfma_f32_16x16x32_bf16 v[20:23], v[160:163], v[184:187], v[20:23]
	v_mfma_f32_16x16x32_bf16 v[64:67], v[148:151], v[192:195], v[64:67]
	v_mfma_f32_16x16x32_bf16 v[72:75], v[160:163], v[192:195], v[72:75]
	v_mfma_f32_16x16x32_bf16 v[16:19], v[148:151], v[214:217], v[16:19]
	v_mfma_f32_16x16x32_bf16 v[12:15], v[160:163], v[214:217], v[12:15]
	v_mfma_f32_16x16x32_bf16 v[60:63], v[148:151], v[222:225], v[60:63]
	v_mfma_f32_16x16x32_bf16 v[68:71], v[160:163], v[222:225], v[68:71]


; #define PG8_MMA(ai, bj, At, Bt) do { __builtin_amdgcn_s_setprio(1); _Pragma("unroll") for (int m = 0; m < 4; ++m) _Pragma("unroll") for (int n = 0; n < 2; ++n) _Pragma("unroll") for (int k = 0; k < 2; ++k) \
;         acc[ai][bj][m][n] = __builtin_amdgcn_mfma_f32_16x16x32_bf16(Bt[n][k], At[m][k], acc[ai][bj][m][n], 0, 0, 0); __builtin_amdgcn_s_setprio(0); } while (0)
; #define PG8_WAIT_V(n) asm volatile("s_waitcnt vmcnt(" #n ")" ::: "memory")
; #define PG8_WAIT_L(n) asm volatile("s_waitcnt lgkmcnt(" #n ")" ::: "memory")
; #define PG8_BAR __builtin_amdgcn_s_barrier()
; #define PG8_SCHED __builtin_amdgcn_sched_barrier(0)
; template <class Epi, bool ALIGN_EPI>
; __device__ __forceinline__ void gemm_phase(LAS unsigned char* lds, const Gemm g, const StaticOrder& S, const Epi& E, const int tid) {
;     ...
;             PG8_WAIT_V(8); PG8_WAIT_L(0); PG8_BAR; PG8_MMA(1, 0, At, B0); PG8_MMA(1, 1, At, B1); PG8_BAR; PG8_SCHED;
	v_mfma_f32_16x16x32_bf16 v[128:131], v[164:167], v[180:183], v[128:131]
	v_mfma_f32_16x16x32_bf16 v[124:127], v[172:175], v[180:183], v[124:127]
	v_mfma_f32_16x16x32_bf16 v[120:123], v[164:167], v[188:191], v[120:123]
	v_mfma_f32_16x16x32_bf16 v[116:119], v[172:175], v[188:191], v[116:119]
	v_mfma_f32_16x16x32_bf16 v[112:115], v[164:167], v[196:199], v[112:115]
	v_mfma_f32_16x16x32_bf16 v[108:111], v[172:175], v[196:199], v[108:111]
	v_mfma_f32_16x16x32_bf16 v[104:107], v[164:167], v[218:221], v[104:107]
	v_mfma_f32_16x16x32_bf16 v[100:103], v[172:175], v[218:221], v[100:103]
	v_mfma_f32_16x16x32_bf16 v[128:131], v[168:171], v[184:187], v[128:131]
	v_mfma_f32_16x16x32_bf16 v[124:127], v[176:179], v[184:187], v[124:127]
	v_mfma_f32_16x16x32_bf16 v[120:123], v[168:171], v[192:195], v[120:123]
	v_mfma_f32_16x16x32_bf16 v[116:119], v[176:179], v[192:195], v[116:119]
	v_mfma_f32_16x16x32_bf16 v[112:115], v[168:171], v[214:217], v[112:115]
	v_mfma_f32_16x16x32_bf16 v[108:111], v[176:179], v[214:217], v[108:111]
	v_mfma_f32_16x16x32_bf16 v[104:107], v[168:171], v[222:225], v[104:107]
	v_mfma_f32_16x16x32_bf16 v[100:103], v[176:179], v[222:225], v[100:103]

; #define PG8_STAGE(bufoff, gbase, voff) do { _Pragma("unroll") for (int _i = 0; _i < 2; ++_i) \
;         __builtin_amdgcn_global_load_lds((const unsigned*)((const char*)(gbase) + (voff)[_i]), (LAS unsigned*)(lds + (bufoff) + ldsw + _i * 8192), 16, 0, 0); } while (0)
; #define PG8_LDA(dst, b, h) do { _Pragma("unroll") for (int m = 0; m < 4; ++m) _Pragma("unroll") for (int k = 0; k < 2; ++k) dst[m][k] = *(const LAS bf16x8*)(lds + PG8_SA(b, h) + aoff + m * 2048 + k * 1024); } while (0)
; #define PG8_LDB(dst, b, h) do { _Pragma("unroll") for (int n = 0; n < 2; ++n) _Pragma("unroll") for (int k = 0; k < 2; ++k) dst[n][k] = *(const LAS bf16x8*)(lds + PG8_SB(b, h) + boff + n * 2048 + k * 1024); } while (0)
; #define PG8_SCHED __builtin_amdgcn_sched_barrier(0)
; template <class Epi, bool ALIGN_EPI>
; __device__ __forceinline__ void gemm_phase(LAS unsigned char* lds, const Gemm g, const StaticOrder& S, const Epi& E, const int tid) {
;     ...
;             PG8_LDB(B0, 1, 0); PG8_LDB(B1, 1, 1); PG8_SCHED; PG8_LDA(At, 1, 0); PG8_STAGE(PG8_SA(0, 1), a2 + hstepA, voffA);
	s_barrier
	s_add_i32 s87, 0, 0x18000

; #define PG8_STAGE(bufoff, gbase, voff) do { _Pragma("unroll") for (int _i = 0; _i < 2; ++_i) \
;         __builtin_amdgcn_global_load_lds((const unsigned*)((const char*)(gbase) + (voff)[_i]), (LAS unsigned*)(lds + (bufoff) + ldsw + _i * 8192), 16, 0, 0); } while (0)
; #define PG8_LDA(dst, b, h) do { _Pragma("unroll") for (int m = 0; m < 4; ++m) _Pragma("unroll") for (int k = 0; k < 2; ++k) dst[m][k] = *(const LAS bf16x8*)(lds + PG8_SA(b, h) + aoff + m * 2048 + k * 1024); } while (0)
; #define PG8_LDB(dst, b, h) do { _Pragma("unroll") for (int n = 0; n < 2; ++n) _Pragma("unroll") for (int k = 0; k < 2; ++k) dst[n][k] = *(const LAS bf16x8*)(lds + PG8_SB(b, h) + boff + n * 2048 + k * 1024); } while (0)
; #define PG8_SCHED __builtin_amdgcn_sched_barrier(0)
; template <class Epi, bool ALIGN_EPI>
; __device__ __forceinline__ void gemm_phase(LAS unsigned char* lds, const Gemm g, const StaticOrder& S, const Epi& E, const int tid) {
;     ...
;             PG8_LDB(B0, 1, 0); PG8_LDB(B1, 1, 1); PG8_SCHED; PG8_LDA(At, 1, 0); PG8_STAGE(PG8_SA(0, 1), a2 + hstepA, voffA);
	s_add_i32 s88, 0, 0x1c000
	ds_read_b128 v[132:135], v243
	ds_read_b128 v[148:151], v243 offset:1024
	ds_read_b128 v[156:159], v243 offset:2048
	ds_read_b128 v[160:163], v243 offset:3072

; #define PG8_STAGE(bufoff, gbase, voff) do { _Pragma("unroll") for (int _i = 0; _i < 2; ++_i) \
;         __builtin_amdgcn_global_load_lds((const unsigned*)((const char*)(gbase) + (voff)[_i]), (LAS unsigned*)(lds + (bufoff) + ldsw + _i * 8192), 16, 0, 0); } while (0)
; #define PG8_LDA(dst, b, h) do { _Pragma("unroll") for (int m = 0; m < 4; ++m) _Pragma("unroll") for (int k = 0; k < 2; ++k) dst[m][k] = *(const LAS bf16x8*)(lds + PG8_SA(b, h) + aoff + m * 2048 + k * 1024); } while (0)
; #define PG8_LDB(dst, b, h) do { _Pragma("unroll") for (int n = 0; n < 2; ++n) _Pragma("unroll") for (int k = 0; k < 2; ++k) dst[n][k] = *(const LAS bf16x8*)(lds + PG8_SB(b, h) + boff + n * 2048 + k * 1024); } while (0)
; #define PG8_SCHED __builtin_amdgcn_sched_barrier(0)
; template <class Epi, bool ALIGN_EPI>
; __device__ __forceinline__ void gemm_phase(LAS unsigned char* lds, const Gemm g, const StaticOrder& S, const Epi& E, const int tid) {
;     ...
;             PG8_LDB(B0, 1, 0); PG8_LDB(B1, 1, 1); PG8_SCHED; PG8_LDA(At, 1, 0); PG8_STAGE(PG8_SA(0, 1), a2 + hstepA, voffA);
	ds_read_b128 v[164:167], v244
	ds_read_b128 v[168:171], v244 offset:1024
	ds_read_b128 v[172:175], v244 offset:2048
	ds_read_b128 v[176:179], v244 offset:3072
	s_add_u32 s42, s42, 0x4000
	s_addc_u32 s43, s43, 0
	s_mov_b32 m0, s61
	ds_read_b128 v[180:183], v155 offset:32768
	ds_read_b128 v[184:187], v155 offset:33792
	ds_read_b128 v[188:191], v155 offset:34816
	ds_read_b128 v[192:195], v155 offset:35840
	ds_read_b128 v[196:199], v155 offset:36864
	ds_read_b128 v[214:217], v155 offset:37888
	ds_read_b128 v[218:221], v155 offset:38912

; #define PG8_STAGE(bufoff, gbase, voff) do { _Pragma("unroll") for (int _i = 0; _i < 2; ++_i) \
;         __builtin_amdgcn_global_load_lds((const unsigned*)((const char*)(gbase) + (voff)[_i]), (LAS unsigned*)(lds + (bufoff) + ldsw + _i * 8192), 16, 0, 0); } while (0)
; #define PG8_LDA(dst, b, h) do { _Pragma("unroll") for (int m = 0; m < 4; ++m) _Pragma("unroll") for (int k = 0; k < 2; ++k) dst[m][k] = *(const LAS bf16x8*)(lds + PG8_SA(b, h) + aoff + m * 2048 + k * 1024); } while (0)
; #define PG8_LDB(dst, b, h) do { _Pragma("unroll") for (int n = 0; n < 2; ++n) _Pragma("unroll") for (int k = 0; k < 2; ++k) dst[n][k] = *(const LAS bf16x8*)(lds + PG8_SB(b, h) + boff + n * 2048 + k * 1024); } while (0)
; #define PG8_MMA(ai, bj, At, Bt) do { __builtin_amdgcn_s_setprio(1); _Pragma("unroll") for (int m = 0; m < 4; ++m) _Pragma("unroll") for (int n = 0; n < 2; ++n) _Pragma("unroll") for (int k = 0; k < 2; ++k) \
;         acc[ai][bj][m][n] = __builtin_amdgcn_mfma_f32_16x16x32_bf16(Bt[n][k], At[m][k], acc[ai][bj][m][n], 0, 0, 0); __builtin_amdgcn_s_setprio(0); } while (0)
; #define PG8_WAIT_V(n) asm volatile("s_waitcnt vmcnt(" #n ")" ::: "memory")
; #define PG8_WAIT_L(n) asm volatile("s_waitcnt lgkmcnt(" #n ")" ::: "memory")
; #define PG8_BAR __builtin_amdgcn_s_barrier()
; #define PG8_SCHED __builtin_amdgcn_sched_barrier(0)
; template <class Epi, bool ALIGN_EPI>
; __device__ __forceinline__ void gemm_phase(LAS unsigned char* lds, const Gemm g, const StaticOrder& S, const Epi& E, const int tid) {
;     ...
;             PG8_LDB(B0, 1, 0); PG8_LDB(B1, 1, 1); PG8_SCHED; PG8_LDA(At, 1, 0); PG8_STAGE(PG8_SA(0, 1), a2 + hstepA, voffA);
;             PG8_WAIT_V(8); PG8_WAIT_L(0); PG8_BAR; PG8_MMA(0, 0, At, B0); PG8_MMA(0, 1, At, B1); PG8_BAR; PG8_SCHED;
	global_load_lds_dwordx4 v142, s[42:43]
	s_mov_b32 m0, s71
	ds_read_b128 v[222:225], v155 offset:39936
	global_load_lds_dwordx4 v138, s[42:43]
	s_waitcnt vmcnt(8)
	s_waitcnt lgkmcnt(0)
	s_barrier


; #define PG8_MMA(ai, bj, At, Bt) do { __builtin_amdgcn_s_setprio(1); _Pragma("unroll") for (int m = 0; m < 4; ++m) _Pragma("unroll") for (int n = 0; n < 2; ++n) _Pragma("unroll") for (int k = 0; k < 2; ++k) \
;         acc[ai][bj][m][n] = __builtin_amdgcn_mfma_f32_16x16x32_bf16(Bt[n][k], At[m][k], acc[ai][bj][m][n], 0, 0, 0); __builtin_amdgcn_s_setprio(0); } while (0)
; #define PG8_WAIT_V(n) asm volatile("s_waitcnt vmcnt(" #n ")" ::: "memory")
; #define PG8_WAIT_L(n) asm volatile("s_waitcnt lgkmcnt(" #n ")" ::: "memory")
; #define PG8_BAR __builtin_amdgcn_s_barrier()
; #define PG8_SCHED __builtin_amdgcn_sched_barrier(0)
; template <class Epi, bool ALIGN_EPI>
; __device__ __forceinline__ void gemm_phase(LAS unsigned char* lds, const Gemm g, const StaticOrder& S, const Epi& E, const int tid) {
;     ...
;             PG8_WAIT_V(8); PG8_WAIT_L(0); PG8_BAR; PG8_MMA(0, 0, At, B0); PG8_MMA(0, 1, At, B1); PG8_BAR; PG8_SCHED;
	v_mfma_f32_16x16x32_bf16 v[6:9], v[132:135], v[180:183], v[8:11]
	v_mfma_f32_16x16x32_bf16 v[56:59], v[156:159], v[180:183], v[56:59]
	v_mfma_f32_16x16x32_bf16 v[52:55], v[132:135], v[188:191], v[52:55]
	v_mfma_f32_16x16x32_bf16 v[48:51], v[156:159], v[188:191], v[48:51]
	v_mfma_f32_16x16x32_bf16 v[44:47], v[132:135], v[196:199], v[44:47]
	v_mfma_f32_16x16x32_bf16 v[40:43], v[156:159], v[196:199], v[40:43]
	v_mfma_f32_16x16x32_bf16 v[36:39], v[132:135], v[218:221], v[36:39]
	v_mfma_f32_16x16x32_bf16 v[32:35], v[156:159], v[218:221], v[32:35]
	v_mfma_f32_16x16x32_bf16 v[8:11], v[148:151], v[184:187], v[6:9]
	v_mfma_f32_16x16x32_bf16 v[56:59], v[160:163], v[184:187], v[56:59]
	v_mfma_f32_16x16x32_bf16 v[52:55], v[148:151], v[192:195], v[52:55]
	v_mfma_f32_16x16x32_bf16 v[48:51], v[160:163], v[192:195], v[48:51]
	v_mfma_f32_16x16x32_bf16 v[44:47], v[148:151], v[214:217], v[44:47]
	v_mfma_f32_16x16x32_bf16 v[40:43], v[160:163], v[214:217], v[40:43]
	v_mfma_f32_16x16x32_bf16 v[36:39], v[148:151], v[222:225], v[36:39]
	v_mfma_f32_16x16x32_bf16 v[32:35], v[160:163], v[222:225], v[32:35]


; #define PG8_MMA(ai, bj, At, Bt) do { __builtin_amdgcn_s_setprio(1); _Pragma("unroll") for (int m = 0; m < 4; ++m) _Pragma("unroll") for (int n = 0; n < 2; ++n) _Pragma("unroll") for (int k = 0; k < 2; ++k) \
;         acc[ai][bj][m][n] = __builtin_amdgcn_mfma_f32_16x16x32_bf16(Bt[n][k], At[m][k], acc[ai][bj][m][n], 0, 0, 0); __builtin_amdgcn_s_setprio(0); } while (0)
; #define PG8_WAIT_V(n) asm volatile("s_waitcnt vmcnt(" #n ")" ::: "memory")
; #define PG8_WAIT_L(n) asm volatile("s_waitcnt lgkmcnt(" #n ")" ::: "memory")
; #define PG8_BAR __builtin_amdgcn_s_barrier()
; #define PG8_SCHED __builtin_amdgcn_sched_barrier(0)
; template <class Epi, bool ALIGN_EPI>
; __device__ __forceinline__ void gemm_phase(LAS unsigned char* lds, const Gemm g, const StaticOrder& S, const Epi& E, const int tid) {
;     ...
;             PG8_WAIT_V(8); PG8_WAIT_L(0); PG8_BAR; PG8_MMA(0, 0, At, B0); PG8_MMA(0, 1, At, B1); PG8_BAR; PG8_SCHED;
	v_mfma_f32_16x16x32_bf16 v[2:5], v[164:167], v[180:183], v[2:5]
	v_mfma_f32_16x16x32_bf16 v[28:31], v[172:175], v[180:183], v[28:31]
	v_mfma_f32_16x16x32_bf16 v[96:99], v[164:167], v[188:191], v[96:99]
	v_mfma_f32_16x16x32_bf16 v[92:95], v[172:175], v[188:191], v[92:95]
	v_mfma_f32_16x16x32_bf16 v[88:91], v[164:167], v[196:199], v[88:91]
	v_mfma_f32_16x16x32_bf16 v[84:87], v[172:175], v[196:199], v[84:87]
	v_mfma_f32_16x16x32_bf16 v[80:83], v[164:167], v[218:221], v[80:83]
	v_mfma_f32_16x16x32_bf16 v[76:79], v[172:175], v[218:221], v[76:79]
	v_mfma_f32_16x16x32_bf16 v[4:7], v[168:171], v[184:187], v[2:5]
	v_mfma_f32_16x16x32_bf16 v[28:31], v[176:179], v[184:187], v[28:31]
	v_mfma_f32_16x16x32_bf16 v[96:99], v[168:171], v[192:195], v[96:99]
	v_mfma_f32_16x16x32_bf16 v[92:95], v[176:179], v[192:195], v[92:95]
	v_mfma_f32_16x16x32_bf16 v[88:91], v[168:171], v[214:217], v[88:91]
	v_mfma_f32_16x16x32_bf16 v[84:87], v[176:179], v[214:217], v[84:87]
	v_mfma_f32_16x16x32_bf16 v[80:83], v[168:171], v[222:225], v[80:83]
	v_mfma_f32_16x16x32_bf16 v[76:79], v[176:179], v[222:225], v[76:79]

; #define PG8_STAGE(bufoff, gbase, voff) do { _Pragma("unroll") for (int _i = 0; _i < 2; ++_i) \
;         __builtin_amdgcn_global_load_lds((const unsigned*)((const char*)(gbase) + (voff)[_i]), (LAS unsigned*)(lds + (bufoff) + ldsw + _i * 8192), 16, 0, 0); } while (0)
; #define PG8_LDA(dst, b, h) do { _Pragma("unroll") for (int m = 0; m < 4; ++m) _Pragma("unroll") for (int k = 0; k < 2; ++k) dst[m][k] = *(const LAS bf16x8*)(lds + PG8_SA(b, h) + aoff + m * 2048 + k * 1024); } while (0)
; template <class Epi, bool ALIGN_EPI>
; __device__ __forceinline__ void gemm_phase(LAS unsigned char* lds, const Gemm g, const StaticOrder& S, const Epi& E, const int tid) {
;     ...
;             PG8_LDA(At, 1, 1); PG8_STAGE(PG8_SB(1, 0), b3, voffB); PG8_STAGE(PG8_SB(1, 1), b3 + hstepB, voffB); PG8_STAGE(PG8_SA(1, 0), a3, voffA);
	s_barrier
	s_add_u32 s42, s34, 0x8000
	s_addc_u32 s43, s35, 0
	s_add_i32 s87, s87, s56
	s_mov_b32 m0, s87
	ds_read_b128 v[180:183], v155 offset:49152
	ds_read_b128 v[184:187], v155 offset:50176
	ds_read_b128 v[188:191], v155 offset:51200
	ds_read_b128 v[192:195], v155 offset:52224


; #define PG8_STAGE(bufoff, gbase, voff) do { _Pragma("unroll") for (int _i = 0; _i < 2; ++_i) \
;         __builtin_amdgcn_global_load_lds((const unsigned*)((const char*)(gbase) + (voff)[_i]), (LAS unsigned*)(lds + (bufoff) + ldsw + _i * 8192), 16, 0, 0); } while (0)
; #define PG8_LDA(dst, b, h) do { _Pragma("unroll") for (int m = 0; m < 4; ++m) _Pragma("unroll") for (int k = 0; k < 2; ++k) dst[m][k] = *(const LAS bf16x8*)(lds + PG8_SA(b, h) + aoff + m * 2048 + k * 1024); } while (0)
; #define PG8_MMA(ai, bj, At, Bt) do { __builtin_amdgcn_s_setprio(1); _Pragma("unroll") for (int m = 0; m < 4; ++m) _Pragma("unroll") for (int n = 0; n < 2; ++n) _Pragma("unroll") for (int k = 0; k < 2; ++k) \
;         acc[ai][bj][m][n] = __builtin_amdgcn_mfma_f32_16x16x32_bf16(Bt[n][k], At[m][k], acc[ai][bj][m][n], 0, 0, 0); __builtin_amdgcn_s_setprio(0); } while (0)
; #define PG8_WAIT_V(n) asm volatile("s_waitcnt vmcnt(" #n ")" ::: "memory")
; #define PG8_WAIT_L(n) asm volatile("s_waitcnt lgkmcnt(" #n ")" ::: "memory")
; #define PG8_BAR __builtin_amdgcn_s_barrier()
; #define PG8_SCHED __builtin_amdgcn_sched_barrier(0)
; template <class Epi, bool ALIGN_EPI>
; __device__ __forceinline__ void gemm_phase(LAS unsigned char* lds, const Gemm g, const StaticOrder& S, const Epi& E, const int tid) {
;     ...
;             PG8_LDA(At, 1, 1); PG8_STAGE(PG8_SB(1, 0), b3, voffB); PG8_STAGE(PG8_SB(1, 1), b3 + hstepB, voffB); PG8_STAGE(PG8_SA(1, 0), a3, voffA);
;             PG8_WAIT_V(8); PG8_WAIT_L(0); PG8_BAR; PG8_MMA(1, 0, At, B0); PG8_MMA(1, 1, At, B1); PG8_BAR; PG8_SCHED;
	global_load_lds_dwordx4 v140, s[42:43]
	s_add_i32 m0, s87, 0x2000
	s_add_u32 s34, s34, 0xc000
	s_addc_u32 s35, s35, 0
	global_load_lds_dwordx4 v136, s[42:43]
	s_add_i32 s42, s88, s56
	s_mov_b32 m0, s42
	ds_read_b128 v[222:225], v155 offset:56320
	global_load_lds_dwordx4 v140, s[34:35]
	s_add_i32 m0, s42, 0x2000
	ds_read_b128 v[218:221], v155 offset:55296
	global_load_lds_dwordx4 v136, s[34:35]
	s_mov_b32 m0, s76
	ds_read_b128 v[214:217], v155 offset:54272
	global_load_lds_dwordx4 v142, s[22:23]
	s_mov_b32 m0, s77
	ds_read_b128 v[196:199], v155 offset:53248
	global_load_lds_dwordx4 v138, s[22:23]
	s_waitcnt vmcnt(8)
	s_waitcnt lgkmcnt(0)
	s_barrier


; #define PG8_MMA(ai, bj, At, Bt) do { __builtin_amdgcn_s_setprio(1); _Pragma("unroll") for (int m = 0; m < 4; ++m) _Pragma("unroll") for (int n = 0; n < 2; ++n) _Pragma("unroll") for (int k = 0; k < 2; ++k) \
;         acc[ai][bj][m][n] = __builtin_amdgcn_mfma_f32_16x16x32_bf16(Bt[n][k], At[m][k], acc[ai][bj][m][n], 0, 0, 0); __builtin_amdgcn_s_setprio(0); } while (0)
; #define PG8_WAIT_V(n) asm volatile("s_waitcnt vmcnt(" #n ")" ::: "memory")
; #define PG8_WAIT_L(n) asm volatile("s_waitcnt lgkmcnt(" #n ")" ::: "memory")
; #define PG8_BAR __builtin_amdgcn_s_barrier()
; #define PG8_SCHED __builtin_amdgcn_sched_barrier(0)
; template <class Epi, bool ALIGN_EPI>
; __device__ __forceinline__ void gemm_phase(LAS unsigned char* lds, const Gemm g, const StaticOrder& S, const Epi& E, const int tid) {
;     ...
;             PG8_WAIT_V(8); PG8_WAIT_L(0); PG8_BAR; PG8_MMA(1, 0, At, B0); PG8_MMA(1, 1, At, B1); PG8_BAR; PG8_SCHED;
	v_mfma_f32_16x16x32_bf16 v[24:27], v[132:135], v[180:183], v[24:27]
	v_mfma_f32_16x16x32_bf16 v[20:23], v[156:159], v[180:183], v[20:23]
	v_mfma_f32_16x16x32_bf16 v[64:67], v[132:135], v[188:191], v[64:67]
	v_mfma_f32_16x16x32_bf16 v[72:75], v[156:159], v[188:191], v[72:75]
	v_mfma_f32_16x16x32_bf16 v[16:19], v[132:135], v[196:199], v[16:19]
	v_mfma_f32_16x16x32_bf16 v[12:15], v[156:159], v[196:199], v[12:15]
	v_mfma_f32_16x16x32_bf16 v[60:63], v[132:135], v[218:221], v[60:63]
	v_mfma_f32_16x16x32_bf16 v[68:71], v[156:159], v[218:221], v[68:71]
	v_mfma_f32_16x16x32_bf16 v[24:27], v[148:151], v[184:187], v[24:27]
	v_mfma_f32_16x16x32_bf16 v[20:23], v[160:163], v[184:187], v[20:23]
	v_mfma_f32_16x16x32_bf16 v[64:67], v[148:151], v[192:195], v[64:67]
	v_mfma_f32_16x16x32_bf16 v[72:75], v[160:163], v[192:195], v[72:75]
	v_mfma_f32_16x16x32_bf16 v[16:19], v[148:151], v[214:217], v[16:19]
	v_mfma_f32_16x16x32_bf16 v[12:15], v[160:163], v[214:217], v[12:15]
	v_mfma_f32_16x16x32_bf16 v[60:63], v[148:151], v[222:225], v[60:63]
	v_mfma_f32_16x16x32_bf16 v[68:71], v[160:163], v[222:225], v[68:71]


; #define PG8_MMA(ai, bj, At, Bt) do { __builtin_amdgcn_s_setprio(1); _Pragma("unroll") for (int m = 0; m < 4; ++m) _Pragma("unroll") for (int n = 0; n < 2; ++n) _Pragma("unroll") for (int k = 0; k < 2; ++k) \
;         acc[ai][bj][m][n] = __builtin_amdgcn_mfma_f32_16x16x32_bf16(Bt[n][k], At[m][k], acc[ai][bj][m][n], 0, 0, 0); __builtin_amdgcn_s_setprio(0); } while (0)
; #define PG8_WAIT_V(n) asm volatile("s_waitcnt vmcnt(" #n ")" ::: "memory")
; #define PG8_WAIT_L(n) asm volatile("s_waitcnt lgkmcnt(" #n ")" ::: "memory")
; #define PG8_BAR __builtin_amdgcn_s_barrier()
; #define PG8_SCHED __builtin_amdgcn_sched_barrier(0)
; template <class Epi, bool ALIGN_EPI>
; __device__ __forceinline__ void gemm_phase(LAS unsigned char* lds, const Gemm g, const StaticOrder& S, const Epi& E, const int tid) {
;     ...
;             PG8_WAIT_V(8); PG8_WAIT_L(0); PG8_BAR; PG8_MMA(1, 0, At, B0); PG8_MMA(1, 1, At, B1); PG8_BAR; PG8_SCHED;
	v_mfma_f32_16x16x32_bf16 v[128:131], v[164:167], v[180:183], v[128:131]
	v_mfma_f32_16x16x32_bf16 v[124:127], v[172:175], v[180:183], v[124:127]
	v_mfma_f32_16x16x32_bf16 v[120:123], v[164:167], v[188:191], v[120:123]
	v_mfma_f32_16x16x32_bf16 v[116:119], v[172:175], v[188:191], v[116:119]
	v_mfma_f32_16x16x32_bf16 v[112:115], v[164:167], v[196:199], v[112:115]
	v_mfma_f32_16x16x32_bf16 v[108:111], v[172:175], v[196:199], v[108:111]
	v_mfma_f32_16x16x32_bf16 v[104:107], v[164:167], v[218:221], v[104:107]
	v_mfma_f32_16x16x32_bf16 v[100:103], v[172:175], v[218:221], v[100:103]
	v_mfma_f32_16x16x32_bf16 v[128:131], v[168:171], v[184:187], v[128:131]
	v_mfma_f32_16x16x32_bf16 v[124:127], v[176:179], v[184:187], v[124:127]
	v_mfma_f32_16x16x32_bf16 v[120:123], v[168:171], v[192:195], v[120:123]
	v_mfma_f32_16x16x32_bf16 v[116:119], v[176:179], v[192:195], v[116:119]
	v_mfma_f32_16x16x32_bf16 v[112:115], v[168:171], v[214:217], v[112:115]
	v_mfma_f32_16x16x32_bf16 v[108:111], v[176:179], v[214:217], v[108:111]
	v_mfma_f32_16x16x32_bf16 v[104:107], v[168:171], v[222:225], v[104:107]
	v_mfma_f32_16x16x32_bf16 v[100:103], v[176:179], v[222:225], v[100:103]

; #define PG8_MMA(ai, bj, At, Bt) do { __builtin_amdgcn_s_setprio(1); _Pragma("unroll") for (int m = 0; m < 4; ++m) _Pragma("unroll") for (int n = 0; n < 2; ++n) _Pragma("unroll") for (int k = 0; k < 2; ++k) \
;         acc[ai][bj][m][n] = __builtin_amdgcn_mfma_f32_16x16x32_bf16(Bt[n][k], At[m][k], acc[ai][bj][m][n], 0, 0, 0); __builtin_amdgcn_s_setprio(0); } while (0)
; #define PG8_WAIT_V(n) asm volatile("s_waitcnt vmcnt(" #n ")" ::: "memory")
; #define PG8_WAIT_L(n) asm volatile("s_waitcnt lgkmcnt(" #n ")" ::: "memory")
; #define PG8_BAR __builtin_amdgcn_s_barrier()
; #define PG8_SCHED __builtin_amdgcn_sched_barrier(0)
; __device__ __forceinline__ u32x4 zero_frag() { unsigned z_ = 0u; asm volatile("" : "+v"(z_)); return (u32x4){z_, z_, z_, z_}; }
; __device__ __forceinline__ void epi_lane(int& fr, int& fq) { unsigned ones = ~0u; asm volatile("" : "+s"(ones)); const int ln = (int)__builtin_amdgcn_mbcnt_hi(ones, __builtin_amdgcn_mbcnt_lo(ones, 0u)); fr = ln & 15; fq = ln >> 4; }
; template <class Epi, bool ALIGN_EPI>
; __device__ __forceinline__ void gemm_phase(LAS unsigned char* lds, const Gemm g, const StaticOrder& S, const Epi& E, const int tid) {
;     ...
;             PG8_WAIT_V(8); PG8_WAIT_L(0); PG8_BAR; PG8_MMA(1, 0, At, B0); PG8_MMA(1, 1, At, B1); PG8_BAR; PG8_SCHED;
;         }
;         if constexpr (ALIGN_EPI) { if (wr == 0) PG8_BAR; }
;         E(acc, cur, wr, wc, lds, rs_pm);
;     __device__ __forceinline__ void operator()(f32x4 (&acc)[2][2][4][2], const Unit& u, int wr, int wc, LAS unsigned char* lds, int& rs_pm) const {
;         int fr, fq; epi_lane(fr, fq);
;         const int row0 = u.pm * BM + wr * 64 + fr, col0 = u.pn * BM + wc * 32 + 8 * fq; u32x4 zb = zero_frag();
; #pragma unroll
;         for (int ai = 0; ai < 2; ++ai)
; #pragma unroll
;             for (int m = 0; m < 4; ++m) { float ss = 0.f;
;                 bf16* const xrow = xb + (((size_t)(u.pm * 32 + u.pn * 4 + (wc >> 1)) * BM + (wr * 64 + fr + ai * HALF + m * 16)) * 64 + (wc & 1) * 32 + 8 * fq);
; #pragma unroll
;                 for (int bj = 0; bj < 2; ++bj) {
;                     const u32x4 xw = *(const u32x4*)(xrow + (size_t)bj * (2 * BM * 64));
	s_barrier
	s_add_i32 s86, s86, 2
	s_add_u32 s84, s84, 0x10000
	s_addc_u32 s85, s85, 0
	s_add_u32 s10, s10, 0x10000
	s_addc_u32 s11, s11, 0
	s_cmpk_gt_u32 s86, 0x55
	s_cbranch_scc0 .LBB0_294
	v_and_b32_e32 v222, 15, v238
	v_lshrrev_b32_e32 v156, 4, v238
	s_lshl_b32 s100, s82, 5
	s_lshl_b32 s101, s83, 2
	v_lshlrev_b32_e32 v222, 7, v222
	s_add_i32 s100, s100, s101
	s_or_b32 s100, s100, s78
	v_lshl_or_b32 v222, v156, 4, v222
	s_ashr_i32 s101, s100, 31
	s_lshl_b64 s[100:101], s[100:101], 15
	s_add_u32 s98, s72, s100
	s_addc_u32 s99, s73, s101
	s_add_u32 s98, s98, s30
	s_addc_u32 s99, s99, s31
	s_lshl_b32 s100, s75, 7
	s_add_u32 s98, s98, s100
	s_addc_u32 s99, s99, 0
	s_lshl_b32 s100, s82, 15
	s_lshl_b32 s101, s75, 7
	s_add_i32 s100, s100, s101
	s_lshl_b32 s101, s83, 4
	s_add_i32 s100, s100, s101
	s_lshl_b32 s101, s74, 2
	s_add_i32 s100, s100, s101
	s_add_u32 s22, s44, s100
	s_addc_u32 s23, s45, 0
	global_load_dwordx4 v[176:179], v222, s[98:99]
	s_add_u32 s100, s98, 0x10000
	s_addc_u32 s101, s99, 0
	global_load_dwordx4 v[180:183], v222, s[100:101]
	global_load_dwordx4 v[184:187], v222, s[98:99] offset:2048
	s_add_u32 s100, s98, 0x10000
	s_addc_u32 s101, s99, 0
	global_load_dwordx4 v[188:191], v222, s[100:101] offset:2048
	s_add_u32 s100, s98, 0x1000
	s_addc_u32 s101, s99, 0
	global_load_dwordx4 v[192:195], v222, s[100:101]
	s_add_u32 s100, s98, 0x11000
	s_addc_u32 s101, s99, 0
	global_load_dwordx4 v[196:199], v222, s[100:101]
	s_add_u32 s100, s98, 0x1000
	s_addc_u32 s101, s99, 0
	global_load_dwordx4 v[214:217], v222, s[100:101] offset:2048
	s_add_u32 s100, s98, 0x11000
	s_addc_u32 s101, s99, 0
	global_load_dwordx4 v[218:221], v222, s[100:101] offset:2048
	s_and_b64 vcc, exec, s[46:47]
	s_cbranch_vccz .LBB0_297
	s_barrier

; #define PG8_STAGE(bufoff, gbase, voff) do { _Pragma("unroll") for (int _i = 0; _i < 2; ++_i) \
;         __builtin_amdgcn_global_load_lds((const unsigned*)((const char*)(gbase) + (voff)[_i]), (LAS unsigned*)(lds + (bufoff) + ldsw + _i * 8192), 16, 0, 0); } while (0)
; #define PG8_LDA(dst, b, h) do { _Pragma("unroll") for (int m = 0; m < 4; ++m) _Pragma("unroll") for (int k = 0; k < 2; ++k) dst[m][k] = *(const LAS bf16x8*)(lds + PG8_SA(b, h) + aoff + m * 2048 + k * 1024); } while (0)
; #define PG8_LDB(dst, b, h) do { _Pragma("unroll") for (int n = 0; n < 2; ++n) _Pragma("unroll") for (int k = 0; k < 2; ++k) dst[n][k] = *(const LAS bf16x8*)(lds + PG8_SB(b, h) + boff + n * 2048 + k * 1024); } while (0)
; #define PG8_SCHED __builtin_amdgcn_sched_barrier(0)
; template <class Epi, bool ALIGN_EPI>
; __device__ __forceinline__ void gemm_phase(LAS unsigned char* lds, const Gemm g, const StaticOrder& S, const Epi& E, const int tid) {
;     ...
;         const char* nA = has_next ? (const char*)g.A + (size_t)nxt.pm * tstepA + (size_t)nxt.pn * g.acs : cA; const char* nB = has_next ? (const char*)g.Bt + (size_t)nxt.pn * tstepB : cB;
;         for (int t = 0; t < nt; t += 2) {
;             const bool last = (t == nt - 2);
;             const char* a1 = cA + (size_t)(t + 1) * kstepA;
;             const char* a2 = last ? nA : cA + (size_t)(t + 2) * kstepA; const char* b2 = last ? nB : cB + (size_t)(t + 2) * kstepB;
;             const char* a3 = a2 + kstepA; const char* b3 = b2 + kstepB;
;             PG8_LDB(B0, 0, 0); PG8_LDB(B1, 0, 1); PG8_SCHED; PG8_LDA(At, 0, 0); PG8_STAGE(PG8_SA(1, 1), a1 + hstepA, voffA);
.LBB0_384:
	s_ashr_i32 s43, s42, 31
	s_lshl_b64 s[44:45], s[42:43], 20
	s_add_u32 s44, s30, s44
	s_addc_u32 s45, s56, s45
	s_and_b64 s[46:47], s[38:39], exec
	s_cselect_b32 s43, s45, s49
	s_cselect_b32 s84, s44, s48
	s_ashr_i32 s41, s40, 31
	s_lshl_b64 s[46:47], s[40:41], 20
	s_add_u32 s46, s57, s46
	s_addc_u32 s47, s60, s47
	s_and_b64 s[52:53], s[38:39], exec
	s_cselect_b32 s41, s47, s51
	s_cselect_b32 s85, s46, s50
	s_add_u32 s48, s48, 0xc000
	s_addc_u32 s49, s49, 0
	s_add_u32 s86, s50, 0x10000
	s_addc_u32 s87, s51, 0
	s_mov_b32 s88, -2
	v_add_u32_e32 v241, 0x10000, v167
	v_add_u32_e32 v242, 0x14000, v167
	v_add_u32_e32 v243, 0x18000, v167
	v_add_u32_e32 v244, 0x1c000, v167
.LBB0_385:
	s_add_u32 s50, s48, 0x4000
	s_addc_u32 s51, s49, 0
	s_cmp_eq_u32 s88, 28
	s_cselect_b32 s54, s84, s50
	s_cselect_b32 s55, s43, s51
	s_cselect_b32 s52, s85, s86
	s_cselect_b32 s53, s41, s87
	s_add_u32 s50, s54, 0x8000
	s_addc_u32 s51, s55, 0
	s_add_i32 s89, 0, 0x10000

; #define PG8_STAGE(bufoff, gbase, voff) do { _Pragma("unroll") for (int _i = 0; _i < 2; ++_i) \
;         __builtin_amdgcn_global_load_lds((const unsigned*)((const char*)(gbase) + (voff)[_i]), (LAS unsigned*)(lds + (bufoff) + ldsw + _i * 8192), 16, 0, 0); } while (0)
; #define PG8_LDA(dst, b, h) do { _Pragma("unroll") for (int m = 0; m < 4; ++m) _Pragma("unroll") for (int k = 0; k < 2; ++k) dst[m][k] = *(const LAS bf16x8*)(lds + PG8_SA(b, h) + aoff + m * 2048 + k * 1024); } while (0)
; #define PG8_LDB(dst, b, h) do { _Pragma("unroll") for (int n = 0; n < 2; ++n) _Pragma("unroll") for (int k = 0; k < 2; ++k) dst[n][k] = *(const LAS bf16x8*)(lds + PG8_SB(b, h) + boff + n * 2048 + k * 1024); } while (0)
; #define PG8_SCHED __builtin_amdgcn_sched_barrier(0)
; template <class Epi, bool ALIGN_EPI>
; __device__ __forceinline__ void gemm_phase(LAS unsigned char* lds, const Gemm g, const StaticOrder& S, const Epi& E, const int tid) {
;     ...
;             PG8_LDB(B0, 0, 0); PG8_LDB(B1, 0, 1); PG8_SCHED; PG8_LDA(At, 0, 0); PG8_STAGE(PG8_SA(1, 1), a1 + hstepA, voffA);
	s_add_i32 s92, 0, 0x14000
	ds_read_b128 v[132:135], v241
	ds_read_b128 v[136:139], v241 offset:1024
	ds_read_b128 v[152:155], v241 offset:2048
	ds_read_b128 v[156:159], v241 offset:3072

; #define PG8_STAGE(bufoff, gbase, voff) do { _Pragma("unroll") for (int _i = 0; _i < 2; ++_i) \
;         __builtin_amdgcn_global_load_lds((const unsigned*)((const char*)(gbase) + (voff)[_i]), (LAS unsigned*)(lds + (bufoff) + ldsw + _i * 8192), 16, 0, 0); } while (0)
; #define PG8_LDA(dst, b, h) do { _Pragma("unroll") for (int m = 0; m < 4; ++m) _Pragma("unroll") for (int k = 0; k < 2; ++k) dst[m][k] = *(const LAS bf16x8*)(lds + PG8_SA(b, h) + aoff + m * 2048 + k * 1024); } while (0)
; #define PG8_LDB(dst, b, h) do { _Pragma("unroll") for (int n = 0; n < 2; ++n) _Pragma("unroll") for (int k = 0; k < 2; ++k) dst[n][k] = *(const LAS bf16x8*)(lds + PG8_SB(b, h) + boff + n * 2048 + k * 1024); } while (0)
; #define PG8_SCHED __builtin_amdgcn_sched_barrier(0)
; template <class Epi, bool ALIGN_EPI>
; __device__ __forceinline__ void gemm_phase(LAS unsigned char* lds, const Gemm g, const StaticOrder& S, const Epi& E, const int tid) {
;     ...
;             PG8_LDB(B0, 0, 0); PG8_LDB(B1, 0, 1); PG8_SCHED; PG8_LDA(At, 0, 0); PG8_STAGE(PG8_SA(1, 1), a1 + hstepA, voffA);
	ds_read_b128 v[160:163], v242
	ds_read_b128 v[172:175], v242 offset:1024
	ds_read_b128 v[176:179], v242 offset:2048
	ds_read_b128 v[180:183], v242 offset:3072
	s_add_i32 m0, s71, 0xc000
	ds_read_b128 v[184:187], v171
	ds_read_b128 v[188:191], v171 offset:1024
	ds_read_b128 v[192:195], v171 offset:2048
	ds_read_b128 v[196:199], v171 offset:3072
	ds_read_b128 v[214:217], v171 offset:4096
	ds_read_b128 v[218:221], v171 offset:5120
	ds_read_b128 v[222:225], v171 offset:6144

; #define PG8_STAGE(bufoff, gbase, voff) do { _Pragma("unroll") for (int _i = 0; _i < 2; ++_i) \
;         __builtin_amdgcn_global_load_lds((const unsigned*)((const char*)(gbase) + (voff)[_i]), (LAS unsigned*)(lds + (bufoff) + ldsw + _i * 8192), 16, 0, 0); } while (0)
; #define PG8_LDA(dst, b, h) do { _Pragma("unroll") for (int m = 0; m < 4; ++m) _Pragma("unroll") for (int k = 0; k < 2; ++k) dst[m][k] = *(const LAS bf16x8*)(lds + PG8_SA(b, h) + aoff + m * 2048 + k * 1024); } while (0)
; #define PG8_LDB(dst, b, h) do { _Pragma("unroll") for (int n = 0; n < 2; ++n) _Pragma("unroll") for (int k = 0; k < 2; ++k) dst[n][k] = *(const LAS bf16x8*)(lds + PG8_SB(b, h) + boff + n * 2048 + k * 1024); } while (0)
; #define PG8_MMA(ai, bj, At, Bt) do { __builtin_amdgcn_s_setprio(1); _Pragma("unroll") for (int m = 0; m < 4; ++m) _Pragma("unroll") for (int n = 0; n < 2; ++n) _Pragma("unroll") for (int k = 0; k < 2; ++k) \
;         acc[ai][bj][m][n] = __builtin_amdgcn_mfma_f32_16x16x32_bf16(Bt[n][k], At[m][k], acc[ai][bj][m][n], 0, 0, 0); __builtin_amdgcn_s_setprio(0); } while (0)
; #define PG8_WAIT_V(n) asm volatile("s_waitcnt vmcnt(" #n ")" ::: "memory")
; #define PG8_WAIT_L(n) asm volatile("s_waitcnt lgkmcnt(" #n ")" ::: "memory")
; #define PG8_BAR __builtin_amdgcn_s_barrier()
; #define PG8_SCHED __builtin_amdgcn_sched_barrier(0)
; template <class Epi, bool ALIGN_EPI>
; __device__ __forceinline__ void gemm_phase(LAS unsigned char* lds, const Gemm g, const StaticOrder& S, const Epi& E, const int tid) {
;     ...
;             PG8_LDB(B0, 0, 0); PG8_LDB(B1, 0, 1); PG8_SCHED; PG8_LDA(At, 0, 0); PG8_STAGE(PG8_SA(1, 1), a1 + hstepA, voffA);
;             PG8_WAIT_V(8); PG8_WAIT_L(0); PG8_BAR; PG8_MMA(0, 0, At, B0); PG8_MMA(0, 1, At, B1); PG8_BAR; PG8_SCHED;
	global_load_lds_dwordx4 v148, s[48:49]
	s_add_i32 m0, s71, 0xe000
	ds_read_b128 v[226:229], v171 offset:7168
	global_load_lds_dwordx4 v150, s[48:49]
	s_waitcnt vmcnt(8)
	s_waitcnt lgkmcnt(0)
	s_barrier


; #define PG8_MMA(ai, bj, At, Bt) do { __builtin_amdgcn_s_setprio(1); _Pragma("unroll") for (int m = 0; m < 4; ++m) _Pragma("unroll") for (int n = 0; n < 2; ++n) _Pragma("unroll") for (int k = 0; k < 2; ++k) \
;         acc[ai][bj][m][n] = __builtin_amdgcn_mfma_f32_16x16x32_bf16(Bt[n][k], At[m][k], acc[ai][bj][m][n], 0, 0, 0); __builtin_amdgcn_s_setprio(0); } while (0)
; #define PG8_WAIT_V(n) asm volatile("s_waitcnt vmcnt(" #n ")" ::: "memory")
; #define PG8_WAIT_L(n) asm volatile("s_waitcnt lgkmcnt(" #n ")" ::: "memory")
; #define PG8_BAR __builtin_amdgcn_s_barrier()
; #define PG8_SCHED __builtin_amdgcn_sched_barrier(0)
; template <class Epi, bool ALIGN_EPI>
; __device__ __forceinline__ void gemm_phase(LAS unsigned char* lds, const Gemm g, const StaticOrder& S, const Epi& E, const int tid) {
;     ...
;             PG8_WAIT_V(8); PG8_WAIT_L(0); PG8_BAR; PG8_MMA(0, 0, At, B0); PG8_MMA(0, 1, At, B1); PG8_BAR; PG8_SCHED;
	v_mfma_f32_16x16x32_bf16 v[128:131], v[132:135], v[184:187], v[128:131]
	v_mfma_f32_16x16x32_bf16 v[116:119], v[152:155], v[184:187], v[116:119]
	v_mfma_f32_16x16x32_bf16 v[124:127], v[132:135], v[192:195], v[124:127]
	v_mfma_f32_16x16x32_bf16 v[108:111], v[152:155], v[192:195], v[108:111]
	v_mfma_f32_16x16x32_bf16 v[120:123], v[132:135], v[214:217], v[120:123]
	v_mfma_f32_16x16x32_bf16 v[100:103], v[152:155], v[214:217], v[100:103]
	v_mfma_f32_16x16x32_bf16 v[112:115], v[132:135], v[222:225], v[112:115]
	v_mfma_f32_16x16x32_bf16 v[92:95], v[152:155], v[222:225], v[92:95]
	v_mfma_f32_16x16x32_bf16 v[128:131], v[136:139], v[188:191], v[128:131]
	v_mfma_f32_16x16x32_bf16 v[116:119], v[156:159], v[188:191], v[116:119]
	v_mfma_f32_16x16x32_bf16 v[124:127], v[136:139], v[196:199], v[124:127]
	v_mfma_f32_16x16x32_bf16 v[108:111], v[156:159], v[196:199], v[108:111]
	v_mfma_f32_16x16x32_bf16 v[120:123], v[136:139], v[218:221], v[120:123]
	v_mfma_f32_16x16x32_bf16 v[100:103], v[156:159], v[218:221], v[100:103]
	v_mfma_f32_16x16x32_bf16 v[112:115], v[136:139], v[226:229], v[112:115]
	v_mfma_f32_16x16x32_bf16 v[92:95], v[156:159], v[226:229], v[92:95]


; #define PG8_MMA(ai, bj, At, Bt) do { __builtin_amdgcn_s_setprio(1); _Pragma("unroll") for (int m = 0; m < 4; ++m) _Pragma("unroll") for (int n = 0; n < 2; ++n) _Pragma("unroll") for (int k = 0; k < 2; ++k) \
;         acc[ai][bj][m][n] = __builtin_amdgcn_mfma_f32_16x16x32_bf16(Bt[n][k], At[m][k], acc[ai][bj][m][n], 0, 0, 0); __builtin_amdgcn_s_setprio(0); } while (0)
; #define PG8_WAIT_V(n) asm volatile("s_waitcnt vmcnt(" #n ")" ::: "memory")
; #define PG8_WAIT_L(n) asm volatile("s_waitcnt lgkmcnt(" #n ")" ::: "memory")
; #define PG8_BAR __builtin_amdgcn_s_barrier()
; #define PG8_SCHED __builtin_amdgcn_sched_barrier(0)
; template <class Epi, bool ALIGN_EPI>
; __device__ __forceinline__ void gemm_phase(LAS unsigned char* lds, const Gemm g, const StaticOrder& S, const Epi& E, const int tid) {
;     ...
;             PG8_WAIT_V(8); PG8_WAIT_L(0); PG8_BAR; PG8_MMA(0, 0, At, B0); PG8_MMA(0, 1, At, B1); PG8_BAR; PG8_SCHED;
	v_mfma_f32_16x16x32_bf16 v[104:107], v[160:163], v[184:187], v[104:107]
	v_mfma_f32_16x16x32_bf16 v[80:83], v[176:179], v[184:187], v[80:83]
	v_mfma_f32_16x16x32_bf16 v[96:99], v[160:163], v[192:195], v[96:99]
	v_mfma_f32_16x16x32_bf16 v[68:71], v[176:179], v[192:195], v[68:71]
	v_mfma_f32_16x16x32_bf16 v[88:91], v[160:163], v[214:217], v[88:91]
	v_mfma_f32_16x16x32_bf16 v[60:63], v[176:179], v[214:217], v[60:63]
	v_mfma_f32_16x16x32_bf16 v[76:79], v[160:163], v[222:225], v[76:79]
	v_mfma_f32_16x16x32_bf16 v[48:51], v[176:179], v[222:225], v[48:51]
	v_mfma_f32_16x16x32_bf16 v[104:107], v[172:175], v[188:191], v[104:107]
	v_mfma_f32_16x16x32_bf16 v[80:83], v[180:183], v[188:191], v[80:83]
	v_mfma_f32_16x16x32_bf16 v[96:99], v[172:175], v[196:199], v[96:99]
	v_mfma_f32_16x16x32_bf16 v[68:71], v[180:183], v[196:199], v[68:71]
	v_mfma_f32_16x16x32_bf16 v[88:91], v[172:175], v[218:221], v[88:91]
	v_mfma_f32_16x16x32_bf16 v[60:63], v[180:183], v[218:221], v[60:63]
	v_mfma_f32_16x16x32_bf16 v[76:79], v[172:175], v[226:229], v[76:79]
	v_mfma_f32_16x16x32_bf16 v[48:51], v[180:183], v[226:229], v[48:51]

; #define PG8_STAGE(bufoff, gbase, voff) do { _Pragma("unroll") for (int _i = 0; _i < 2; ++_i) \
;         __builtin_amdgcn_global_load_lds((const unsigned*)((const char*)(gbase) + (voff)[_i]), (LAS unsigned*)(lds + (bufoff) + ldsw + _i * 8192), 16, 0, 0); } while (0)
; #define PG8_LDA(dst, b, h) do { _Pragma("unroll") for (int m = 0; m < 4; ++m) _Pragma("unroll") for (int k = 0; k < 2; ++k) dst[m][k] = *(const LAS bf16x8*)(lds + PG8_SA(b, h) + aoff + m * 2048 + k * 1024); } while (0)
; #define PG8_MMA(ai, bj, At, Bt) do { __builtin_amdgcn_s_setprio(1); _Pragma("unroll") for (int m = 0; m < 4; ++m) _Pragma("unroll") for (int n = 0; n < 2; ++n) _Pragma("unroll") for (int k = 0; k < 2; ++k) \
;         acc[ai][bj][m][n] = __builtin_amdgcn_mfma_f32_16x16x32_bf16(Bt[n][k], At[m][k], acc[ai][bj][m][n], 0, 0, 0); __builtin_amdgcn_s_setprio(0); } while (0)
; #define PG8_WAIT_V(n) asm volatile("s_waitcnt vmcnt(" #n ")" ::: "memory")
; #define PG8_WAIT_L(n) asm volatile("s_waitcnt lgkmcnt(" #n ")" ::: "memory")
; #define PG8_BAR __builtin_amdgcn_s_barrier()
; #define PG8_SCHED __builtin_amdgcn_sched_barrier(0)
; template <class Epi, bool ALIGN_EPI>
; __device__ __forceinline__ void gemm_phase(LAS unsigned char* lds, const Gemm g, const StaticOrder& S, const Epi& E, const int tid) {
;     ...
;             PG8_WAIT_V(8); PG8_WAIT_L(0); PG8_BAR; PG8_MMA(0, 0, At, B0); PG8_MMA(0, 1, At, B1); PG8_BAR; PG8_SCHED;
;             PG8_LDA(At, 0, 1); PG8_STAGE(PG8_SB(0, 0), b2, voffB); PG8_STAGE(PG8_SB(0, 1), b2 + hstepB, voffB); PG8_STAGE(PG8_SA(0, 0), a2, voffA);
	s_barrier
	s_add_i32 s89, s89, s61
	s_mov_b32 m0, s89
	ds_read_b128 v[184:187], v171 offset:16384
	ds_read_b128 v[188:191], v171 offset:17408
	ds_read_b128 v[192:195], v171 offset:18432
	ds_read_b128 v[196:199], v171 offset:19456


; #define PG8_STAGE(bufoff, gbase, voff) do { _Pragma("unroll") for (int _i = 0; _i < 2; ++_i) \
;         __builtin_amdgcn_global_load_lds((const unsigned*)((const char*)(gbase) + (voff)[_i]), (LAS unsigned*)(lds + (bufoff) + ldsw + _i * 8192), 16, 0, 0); } while (0)
; #define PG8_LDA(dst, b, h) do { _Pragma("unroll") for (int m = 0; m < 4; ++m) _Pragma("unroll") for (int k = 0; k < 2; ++k) dst[m][k] = *(const LAS bf16x8*)(lds + PG8_SA(b, h) + aoff + m * 2048 + k * 1024); } while (0)
; #define PG8_MMA(ai, bj, At, Bt) do { __builtin_amdgcn_s_setprio(1); _Pragma("unroll") for (int m = 0; m < 4; ++m) _Pragma("unroll") for (int n = 0; n < 2; ++n) _Pragma("unroll") for (int k = 0; k < 2; ++k) \
;         acc[ai][bj][m][n] = __builtin_amdgcn_mfma_f32_16x16x32_bf16(Bt[n][k], At[m][k], acc[ai][bj][m][n], 0, 0, 0); __builtin_amdgcn_s_setprio(0); } while (0)
; #define PG8_WAIT_V(n) asm volatile("s_waitcnt vmcnt(" #n ")" ::: "memory")
; #define PG8_WAIT_L(n) asm volatile("s_waitcnt lgkmcnt(" #n ")" ::: "memory")
; #define PG8_BAR __builtin_amdgcn_s_barrier()
; #define PG8_SCHED __builtin_amdgcn_sched_barrier(0)
; template <class Epi, bool ALIGN_EPI>
; __device__ __forceinline__ void gemm_phase(LAS unsigned char* lds, const Gemm g, const StaticOrder& S, const Epi& E, const int tid) {
;     ...
;             PG8_LDA(At, 0, 1); PG8_STAGE(PG8_SB(0, 0), b2, voffB); PG8_STAGE(PG8_SB(0, 1), b2 + hstepB, voffB); PG8_STAGE(PG8_SA(0, 0), a2, voffA);
;             PG8_WAIT_V(8); PG8_WAIT_L(0); PG8_BAR; PG8_MMA(1, 0, At, B0); PG8_MMA(1, 1, At, B1); PG8_BAR; PG8_SCHED;
	global_load_lds_dwordx4 v144, s[52:53]
	s_add_i32 m0, s89, 0x2000
	s_add_u32 s90, s52, 0x4000
	s_addc_u32 s91, s53, 0
	s_add_i32 s89, s92, s61
	global_load_lds_dwordx4 v140, s[52:53]
	s_mov_b32 m0, s89
	ds_read_b128 v[226:229], v171 offset:23552
	global_load_lds_dwordx4 v144, s[90:91]
	s_add_i32 m0, s89, 0x2000
	ds_read_b128 v[222:225], v171 offset:22528
	global_load_lds_dwordx4 v140, s[90:91]
	s_mov_b32 m0, s71
	ds_read_b128 v[218:221], v171 offset:21504
	global_load_lds_dwordx4 v146, s[54:55]
	s_mov_b32 m0, s72
	ds_read_b128 v[214:217], v171 offset:20480
	global_load_lds_dwordx4 v142, s[54:55]
	s_waitcnt vmcnt(8)
	s_waitcnt lgkmcnt(0)
	s_barrier


; #define PG8_MMA(ai, bj, At, Bt) do { __builtin_amdgcn_s_setprio(1); _Pragma("unroll") for (int m = 0; m < 4; ++m) _Pragma("unroll") for (int n = 0; n < 2; ++n) _Pragma("unroll") for (int k = 0; k < 2; ++k) \
;         acc[ai][bj][m][n] = __builtin_amdgcn_mfma_f32_16x16x32_bf16(Bt[n][k], At[m][k], acc[ai][bj][m][n], 0, 0, 0); __builtin_amdgcn_s_setprio(0); } while (0)
; #define PG8_WAIT_V(n) asm volatile("s_waitcnt vmcnt(" #n ")" ::: "memory")
; #define PG8_WAIT_L(n) asm volatile("s_waitcnt lgkmcnt(" #n ")" ::: "memory")
; #define PG8_BAR __builtin_amdgcn_s_barrier()
; #define PG8_SCHED __builtin_amdgcn_sched_barrier(0)
; template <class Epi, bool ALIGN_EPI>
; __device__ __forceinline__ void gemm_phase(LAS unsigned char* lds, const Gemm g, const StaticOrder& S, const Epi& E, const int tid) {
;     ...
;             PG8_WAIT_V(8); PG8_WAIT_L(0); PG8_BAR; PG8_MMA(1, 0, At, B0); PG8_MMA(1, 1, At, B1); PG8_BAR; PG8_SCHED;
	v_mfma_f32_16x16x32_bf16 v[84:87], v[132:135], v[184:187], v[84:87]
	v_mfma_f32_16x16x32_bf16 v[56:59], v[152:155], v[184:187], v[56:59]
	v_mfma_f32_16x16x32_bf16 v[72:75], v[132:135], v[192:195], v[72:75]
	v_mfma_f32_16x16x32_bf16 v[44:47], v[152:155], v[192:195], v[44:47]
	v_mfma_f32_16x16x32_bf16 v[64:67], v[132:135], v[214:217], v[64:67]
	v_mfma_f32_16x16x32_bf16 v[36:39], v[152:155], v[214:217], v[36:39]
	v_mfma_f32_16x16x32_bf16 v[52:55], v[132:135], v[222:225], v[52:55]
	v_mfma_f32_16x16x32_bf16 v[28:31], v[152:155], v[222:225], v[28:31]
	v_mfma_f32_16x16x32_bf16 v[84:87], v[136:139], v[188:191], v[84:87]
	v_mfma_f32_16x16x32_bf16 v[56:59], v[156:159], v[188:191], v[56:59]
	v_mfma_f32_16x16x32_bf16 v[72:75], v[136:139], v[196:199], v[72:75]
	v_mfma_f32_16x16x32_bf16 v[44:47], v[156:159], v[196:199], v[44:47]
	v_mfma_f32_16x16x32_bf16 v[64:67], v[136:139], v[218:221], v[64:67]
	v_mfma_f32_16x16x32_bf16 v[36:39], v[156:159], v[218:221], v[36:39]
	v_mfma_f32_16x16x32_bf16 v[52:55], v[136:139], v[226:229], v[52:55]
	v_mfma_f32_16x16x32_bf16 v[28:31], v[156:159], v[226:229], v[28:31]


; #define PG8_MMA(ai, bj, At, Bt) do { __builtin_amdgcn_s_setprio(1); _Pragma("unroll") for (int m = 0; m < 4; ++m) _Pragma("unroll") for (int n = 0; n < 2; ++n) _Pragma("unroll") for (int k = 0; k < 2; ++k) \
;         acc[ai][bj][m][n] = __builtin_amdgcn_mfma_f32_16x16x32_bf16(Bt[n][k], At[m][k], acc[ai][bj][m][n], 0, 0, 0); __builtin_amdgcn_s_setprio(0); } while (0)
; #define PG8_WAIT_V(n) asm volatile("s_waitcnt vmcnt(" #n ")" ::: "memory")
; #define PG8_WAIT_L(n) asm volatile("s_waitcnt lgkmcnt(" #n ")" ::: "memory")
; #define PG8_BAR __builtin_amdgcn_s_barrier()
; #define PG8_SCHED __builtin_amdgcn_sched_barrier(0)
; template <class Epi, bool ALIGN_EPI>
; __device__ __forceinline__ void gemm_phase(LAS unsigned char* lds, const Gemm g, const StaticOrder& S, const Epi& E, const int tid) {
;     ...
;             PG8_WAIT_V(8); PG8_WAIT_L(0); PG8_BAR; PG8_MMA(1, 0, At, B0); PG8_MMA(1, 1, At, B1); PG8_BAR; PG8_SCHED;
	v_mfma_f32_16x16x32_bf16 v[40:43], v[160:163], v[184:187], v[40:43]
	v_mfma_f32_16x16x32_bf16 v[20:23], v[176:179], v[184:187], v[20:23]
	v_mfma_f32_16x16x32_bf16 v[32:35], v[160:163], v[192:195], v[32:35]
	v_mfma_f32_16x16x32_bf16 v[12:15], v[176:179], v[192:195], v[12:15]
	v_mfma_f32_16x16x32_bf16 v[24:27], v[160:163], v[214:217], v[24:27]
	v_mfma_f32_16x16x32_bf16 v[8:11], v[176:179], v[214:217], v[8:11]
	v_mfma_f32_16x16x32_bf16 v[16:19], v[160:163], v[222:225], v[16:19]
	v_mfma_f32_16x16x32_bf16 v[2:5], v[176:179], v[222:225], v[4:7]
	v_mfma_f32_16x16x32_bf16 v[40:43], v[172:175], v[188:191], v[40:43]
	v_mfma_f32_16x16x32_bf16 v[20:23], v[180:183], v[188:191], v[20:23]
	v_mfma_f32_16x16x32_bf16 v[32:35], v[172:175], v[196:199], v[32:35]
	v_mfma_f32_16x16x32_bf16 v[12:15], v[180:183], v[196:199], v[12:15]
	v_mfma_f32_16x16x32_bf16 v[24:27], v[172:175], v[218:221], v[24:27]
	v_mfma_f32_16x16x32_bf16 v[8:11], v[180:183], v[218:221], v[8:11]
	v_mfma_f32_16x16x32_bf16 v[16:19], v[172:175], v[226:229], v[16:19]
	v_mfma_f32_16x16x32_bf16 v[2:5], v[180:183], v[226:229], v[2:5]

; #define PG8_STAGE(bufoff, gbase, voff) do { _Pragma("unroll") for (int _i = 0; _i < 2; ++_i) \
;         __builtin_amdgcn_global_load_lds((const unsigned*)((const char*)(gbase) + (voff)[_i]), (LAS unsigned*)(lds + (bufoff) + ldsw + _i * 8192), 16, 0, 0); } while (0)
; #define PG8_LDA(dst, b, h) do { _Pragma("unroll") for (int m = 0; m < 4; ++m) _Pragma("unroll") for (int k = 0; k < 2; ++k) dst[m][k] = *(const LAS bf16x8*)(lds + PG8_SA(b, h) + aoff + m * 2048 + k * 1024); } while (0)
; #define PG8_LDB(dst, b, h) do { _Pragma("unroll") for (int n = 0; n < 2; ++n) _Pragma("unroll") for (int k = 0; k < 2; ++k) dst[n][k] = *(const LAS bf16x8*)(lds + PG8_SB(b, h) + boff + n * 2048 + k * 1024); } while (0)
; #define PG8_SCHED __builtin_amdgcn_sched_barrier(0)
; template <class Epi, bool ALIGN_EPI>
; __device__ __forceinline__ void gemm_phase(LAS unsigned char* lds, const Gemm g, const StaticOrder& S, const Epi& E, const int tid) {
;     ...
;             PG8_LDB(B0, 1, 0); PG8_LDB(B1, 1, 1); PG8_SCHED; PG8_LDA(At, 1, 0); PG8_STAGE(PG8_SA(0, 1), a2 + hstepA, voffA);
	s_barrier
	s_add_i32 s89, 0, 0x18000

; #define PG8_STAGE(bufoff, gbase, voff) do { _Pragma("unroll") for (int _i = 0; _i < 2; ++_i) \
;         __builtin_amdgcn_global_load_lds((const unsigned*)((const char*)(gbase) + (voff)[_i]), (LAS unsigned*)(lds + (bufoff) + ldsw + _i * 8192), 16, 0, 0); } while (0)
; #define PG8_LDA(dst, b, h) do { _Pragma("unroll") for (int m = 0; m < 4; ++m) _Pragma("unroll") for (int k = 0; k < 2; ++k) dst[m][k] = *(const LAS bf16x8*)(lds + PG8_SA(b, h) + aoff + m * 2048 + k * 1024); } while (0)
; #define PG8_LDB(dst, b, h) do { _Pragma("unroll") for (int n = 0; n < 2; ++n) _Pragma("unroll") for (int k = 0; k < 2; ++k) dst[n][k] = *(const LAS bf16x8*)(lds + PG8_SB(b, h) + boff + n * 2048 + k * 1024); } while (0)
; #define PG8_SCHED __builtin_amdgcn_sched_barrier(0)
; template <class Epi, bool ALIGN_EPI>
; __device__ __forceinline__ void gemm_phase(LAS unsigned char* lds, const Gemm g, const StaticOrder& S, const Epi& E, const int tid) {
;     ...
;             PG8_LDB(B0, 1, 0); PG8_LDB(B1, 1, 1); PG8_SCHED; PG8_LDA(At, 1, 0); PG8_STAGE(PG8_SA(0, 1), a2 + hstepA, voffA);
	s_add_i32 s90, 0, 0x1c000
	ds_read_b128 v[132:135], v243
	ds_read_b128 v[136:139], v243 offset:1024
	ds_read_b128 v[152:155], v243 offset:2048
	ds_read_b128 v[156:159], v243 offset:3072

; #define PG8_STAGE(bufoff, gbase, voff) do { _Pragma("unroll") for (int _i = 0; _i < 2; ++_i) \
;         __builtin_amdgcn_global_load_lds((const unsigned*)((const char*)(gbase) + (voff)[_i]), (LAS unsigned*)(lds + (bufoff) + ldsw + _i * 8192), 16, 0, 0); } while (0)
; #define PG8_LDA(dst, b, h) do { _Pragma("unroll") for (int m = 0; m < 4; ++m) _Pragma("unroll") for (int k = 0; k < 2; ++k) dst[m][k] = *(const LAS bf16x8*)(lds + PG8_SA(b, h) + aoff + m * 2048 + k * 1024); } while (0)
; #define PG8_LDB(dst, b, h) do { _Pragma("unroll") for (int n = 0; n < 2; ++n) _Pragma("unroll") for (int k = 0; k < 2; ++k) dst[n][k] = *(const LAS bf16x8*)(lds + PG8_SB(b, h) + boff + n * 2048 + k * 1024); } while (0)
; #define PG8_SCHED __builtin_amdgcn_sched_barrier(0)
; template <class Epi, bool ALIGN_EPI>
; __device__ __forceinline__ void gemm_phase(LAS unsigned char* lds, const Gemm g, const StaticOrder& S, const Epi& E, const int tid) {
;     ...
;             PG8_LDB(B0, 1, 0); PG8_LDB(B1, 1, 1); PG8_SCHED; PG8_LDA(At, 1, 0); PG8_STAGE(PG8_SA(0, 1), a2 + hstepA, voffA);
	ds_read_b128 v[160:163], v244
	ds_read_b128 v[172:175], v244 offset:1024
	ds_read_b128 v[176:179], v244 offset:2048
	ds_read_b128 v[180:183], v244 offset:3072
	s_add_u32 s54, s54, 0x4000
	s_addc_u32 s55, s55, 0
	s_mov_b32 m0, s73
	ds_read_b128 v[184:187], v171 offset:32768
	ds_read_b128 v[188:191], v171 offset:33792
	ds_read_b128 v[192:195], v171 offset:34816
	ds_read_b128 v[196:199], v171 offset:35840
	ds_read_b128 v[214:217], v171 offset:36864
	ds_read_b128 v[218:221], v171 offset:37888
	ds_read_b128 v[222:225], v171 offset:38912

; #define PG8_STAGE(bufoff, gbase, voff) do { _Pragma("unroll") for (int _i = 0; _i < 2; ++_i) \
;         __builtin_amdgcn_global_load_lds((const unsigned*)((const char*)(gbase) + (voff)[_i]), (LAS unsigned*)(lds + (bufoff) + ldsw + _i * 8192), 16, 0, 0); } while (0)
; #define PG8_LDA(dst, b, h) do { _Pragma("unroll") for (int m = 0; m < 4; ++m) _Pragma("unroll") for (int k = 0; k < 2; ++k) dst[m][k] = *(const LAS bf16x8*)(lds + PG8_SA(b, h) + aoff + m * 2048 + k * 1024); } while (0)
; #define PG8_LDB(dst, b, h) do { _Pragma("unroll") for (int n = 0; n < 2; ++n) _Pragma("unroll") for (int k = 0; k < 2; ++k) dst[n][k] = *(const LAS bf16x8*)(lds + PG8_SB(b, h) + boff + n * 2048 + k * 1024); } while (0)
; #define PG8_MMA(ai, bj, At, Bt) do { __builtin_amdgcn_s_setprio(1); _Pragma("unroll") for (int m = 0; m < 4; ++m) _Pragma("unroll") for (int n = 0; n < 2; ++n) _Pragma("unroll") for (int k = 0; k < 2; ++k) \
;         acc[ai][bj][m][n] = __builtin_amdgcn_mfma_f32_16x16x32_bf16(Bt[n][k], At[m][k], acc[ai][bj][m][n], 0, 0, 0); __builtin_amdgcn_s_setprio(0); } while (0)
; #define PG8_WAIT_V(n) asm volatile("s_waitcnt vmcnt(" #n ")" ::: "memory")
; #define PG8_WAIT_L(n) asm volatile("s_waitcnt lgkmcnt(" #n ")" ::: "memory")
; #define PG8_BAR __builtin_amdgcn_s_barrier()
; #define PG8_SCHED __builtin_amdgcn_sched_barrier(0)
; template <class Epi, bool ALIGN_EPI>
; __device__ __forceinline__ void gemm_phase(LAS unsigned char* lds, const Gemm g, const StaticOrder& S, const Epi& E, const int tid) {
;     ...
;             PG8_LDB(B0, 1, 0); PG8_LDB(B1, 1, 1); PG8_SCHED; PG8_LDA(At, 1, 0); PG8_STAGE(PG8_SA(0, 1), a2 + hstepA, voffA);
;             PG8_WAIT_V(8); PG8_WAIT_L(0); PG8_BAR; PG8_MMA(0, 0, At, B0); PG8_MMA(0, 1, At, B1); PG8_BAR; PG8_SCHED;
	global_load_lds_dwordx4 v146, s[54:55]
	s_mov_b32 m0, s74
	ds_read_b128 v[226:229], v171 offset:39936
	global_load_lds_dwordx4 v142, s[54:55]
	s_waitcnt vmcnt(8)
	s_waitcnt lgkmcnt(0)
	s_barrier


; #define PG8_MMA(ai, bj, At, Bt) do { __builtin_amdgcn_s_setprio(1); _Pragma("unroll") for (int m = 0; m < 4; ++m) _Pragma("unroll") for (int n = 0; n < 2; ++n) _Pragma("unroll") for (int k = 0; k < 2; ++k) \
;         acc[ai][bj][m][n] = __builtin_amdgcn_mfma_f32_16x16x32_bf16(Bt[n][k], At[m][k], acc[ai][bj][m][n], 0, 0, 0); __builtin_amdgcn_s_setprio(0); } while (0)
; #define PG8_WAIT_V(n) asm volatile("s_waitcnt vmcnt(" #n ")" ::: "memory")
; #define PG8_WAIT_L(n) asm volatile("s_waitcnt lgkmcnt(" #n ")" ::: "memory")
; #define PG8_BAR __builtin_amdgcn_s_barrier()
; #define PG8_SCHED __builtin_amdgcn_sched_barrier(0)
; template <class Epi, bool ALIGN_EPI>
; __device__ __forceinline__ void gemm_phase(LAS unsigned char* lds, const Gemm g, const StaticOrder& S, const Epi& E, const int tid) {
;     ...
;             PG8_WAIT_V(8); PG8_WAIT_L(0); PG8_BAR; PG8_MMA(0, 0, At, B0); PG8_MMA(0, 1, At, B1); PG8_BAR; PG8_SCHED;
	v_mfma_f32_16x16x32_bf16 v[128:131], v[132:135], v[184:187], v[128:131]
	v_mfma_f32_16x16x32_bf16 v[116:119], v[152:155], v[184:187], v[116:119]
	v_mfma_f32_16x16x32_bf16 v[124:127], v[132:135], v[192:195], v[124:127]
	v_mfma_f32_16x16x32_bf16 v[108:111], v[152:155], v[192:195], v[108:111]
	v_mfma_f32_16x16x32_bf16 v[120:123], v[132:135], v[214:217], v[120:123]
	v_mfma_f32_16x16x32_bf16 v[100:103], v[152:155], v[214:217], v[100:103]
	v_mfma_f32_16x16x32_bf16 v[112:115], v[132:135], v[222:225], v[112:115]
	v_mfma_f32_16x16x32_bf16 v[92:95], v[152:155], v[222:225], v[92:95]
	v_mfma_f32_16x16x32_bf16 v[128:131], v[136:139], v[188:191], v[128:131]
	v_mfma_f32_16x16x32_bf16 v[116:119], v[156:159], v[188:191], v[116:119]
	v_mfma_f32_16x16x32_bf16 v[124:127], v[136:139], v[196:199], v[124:127]
	v_mfma_f32_16x16x32_bf16 v[108:111], v[156:159], v[196:199], v[108:111]
	v_mfma_f32_16x16x32_bf16 v[120:123], v[136:139], v[218:221], v[120:123]
	v_mfma_f32_16x16x32_bf16 v[100:103], v[156:159], v[218:221], v[100:103]
	v_mfma_f32_16x16x32_bf16 v[112:115], v[136:139], v[226:229], v[112:115]
	v_mfma_f32_16x16x32_bf16 v[92:95], v[156:159], v[226:229], v[92:95]


; #define PG8_MMA(ai, bj, At, Bt) do { __builtin_amdgcn_s_setprio(1); _Pragma("unroll") for (int m = 0; m < 4; ++m) _Pragma("unroll") for (int n = 0; n < 2; ++n) _Pragma("unroll") for (int k = 0; k < 2; ++k) \
;         acc[ai][bj][m][n] = __builtin_amdgcn_mfma_f32_16x16x32_bf16(Bt[n][k], At[m][k], acc[ai][bj][m][n], 0, 0, 0); __builtin_amdgcn_s_setprio(0); } while (0)
; #define PG8_WAIT_V(n) asm volatile("s_waitcnt vmcnt(" #n ")" ::: "memory")
; #define PG8_WAIT_L(n) asm volatile("s_waitcnt lgkmcnt(" #n ")" ::: "memory")
; #define PG8_BAR __builtin_amdgcn_s_barrier()
; #define PG8_SCHED __builtin_amdgcn_sched_barrier(0)
; template <class Epi, bool ALIGN_EPI>
; __device__ __forceinline__ void gemm_phase(LAS unsigned char* lds, const Gemm g, const StaticOrder& S, const Epi& E, const int tid) {
;     ...
;             PG8_WAIT_V(8); PG8_WAIT_L(0); PG8_BAR; PG8_MMA(0, 0, At, B0); PG8_MMA(0, 1, At, B1); PG8_BAR; PG8_SCHED;
	v_mfma_f32_16x16x32_bf16 v[104:107], v[160:163], v[184:187], v[104:107]
	v_mfma_f32_16x16x32_bf16 v[80:83], v[176:179], v[184:187], v[80:83]
	v_mfma_f32_16x16x32_bf16 v[96:99], v[160:163], v[192:195], v[96:99]
	v_mfma_f32_16x16x32_bf16 v[68:71], v[176:179], v[192:195], v[68:71]
	v_mfma_f32_16x16x32_bf16 v[88:91], v[160:163], v[214:217], v[88:91]
	v_mfma_f32_16x16x32_bf16 v[60:63], v[176:179], v[214:217], v[60:63]
	v_mfma_f32_16x16x32_bf16 v[76:79], v[160:163], v[222:225], v[76:79]
	v_mfma_f32_16x16x32_bf16 v[48:51], v[176:179], v[222:225], v[48:51]
	v_mfma_f32_16x16x32_bf16 v[104:107], v[172:175], v[188:191], v[104:107]
	v_mfma_f32_16x16x32_bf16 v[80:83], v[180:183], v[188:191], v[80:83]
	v_mfma_f32_16x16x32_bf16 v[96:99], v[172:175], v[196:199], v[96:99]
	v_mfma_f32_16x16x32_bf16 v[68:71], v[180:183], v[196:199], v[68:71]
	v_mfma_f32_16x16x32_bf16 v[88:91], v[172:175], v[218:221], v[88:91]
	v_mfma_f32_16x16x32_bf16 v[60:63], v[180:183], v[218:221], v[60:63]
	v_mfma_f32_16x16x32_bf16 v[76:79], v[172:175], v[226:229], v[76:79]
	v_mfma_f32_16x16x32_bf16 v[48:51], v[180:183], v[226:229], v[48:51]

; #define PG8_STAGE(bufoff, gbase, voff) do { _Pragma("unroll") for (int _i = 0; _i < 2; ++_i) \
;         __builtin_amdgcn_global_load_lds((const unsigned*)((const char*)(gbase) + (voff)[_i]), (LAS unsigned*)(lds + (bufoff) + ldsw + _i * 8192), 16, 0, 0); } while (0)
; #define PG8_LDA(dst, b, h) do { _Pragma("unroll") for (int m = 0; m < 4; ++m) _Pragma("unroll") for (int k = 0; k < 2; ++k) dst[m][k] = *(const LAS bf16x8*)(lds + PG8_SA(b, h) + aoff + m * 2048 + k * 1024); } while (0)
; template <class Epi, bool ALIGN_EPI>
; __device__ __forceinline__ void gemm_phase(LAS unsigned char* lds, const Gemm g, const StaticOrder& S, const Epi& E, const int tid) {
;     ...
;             PG8_LDA(At, 1, 1); PG8_STAGE(PG8_SB(1, 0), b3, voffB); PG8_STAGE(PG8_SB(1, 1), b3 + hstepB, voffB); PG8_STAGE(PG8_SA(1, 0), a3, voffA);
	s_barrier
	s_add_u32 s54, s52, 0x8000
	s_addc_u32 s55, s53, 0
	s_add_i32 s89, s89, s61
	s_mov_b32 m0, s89
	ds_read_b128 v[184:187], v171 offset:49152
	ds_read_b128 v[188:191], v171 offset:50176
	ds_read_b128 v[192:195], v171 offset:51200
	ds_read_b128 v[196:199], v171 offset:52224


; #define PG8_STAGE(bufoff, gbase, voff) do { _Pragma("unroll") for (int _i = 0; _i < 2; ++_i) \
;         __builtin_amdgcn_global_load_lds((const unsigned*)((const char*)(gbase) + (voff)[_i]), (LAS unsigned*)(lds + (bufoff) + ldsw + _i * 8192), 16, 0, 0); } while (0)
; #define PG8_LDA(dst, b, h) do { _Pragma("unroll") for (int m = 0; m < 4; ++m) _Pragma("unroll") for (int k = 0; k < 2; ++k) dst[m][k] = *(const LAS bf16x8*)(lds + PG8_SA(b, h) + aoff + m * 2048 + k * 1024); } while (0)
; #define PG8_MMA(ai, bj, At, Bt) do { __builtin_amdgcn_s_setprio(1); _Pragma("unroll") for (int m = 0; m < 4; ++m) _Pragma("unroll") for (int n = 0; n < 2; ++n) _Pragma("unroll") for (int k = 0; k < 2; ++k) \
;         acc[ai][bj][m][n] = __builtin_amdgcn_mfma_f32_16x16x32_bf16(Bt[n][k], At[m][k], acc[ai][bj][m][n], 0, 0, 0); __builtin_amdgcn_s_setprio(0); } while (0)
; #define PG8_WAIT_V(n) asm volatile("s_waitcnt vmcnt(" #n ")" ::: "memory")
; #define PG8_WAIT_L(n) asm volatile("s_waitcnt lgkmcnt(" #n ")" ::: "memory")
; #define PG8_BAR __builtin_amdgcn_s_barrier()
; #define PG8_SCHED __builtin_amdgcn_sched_barrier(0)
; template <class Epi, bool ALIGN_EPI>
; __device__ __forceinline__ void gemm_phase(LAS unsigned char* lds, const Gemm g, const StaticOrder& S, const Epi& E, const int tid) {
;     ...
;             PG8_LDA(At, 1, 1); PG8_STAGE(PG8_SB(1, 0), b3, voffB); PG8_STAGE(PG8_SB(1, 1), b3 + hstepB, voffB); PG8_STAGE(PG8_SA(1, 0), a3, voffA);
;             PG8_WAIT_V(8); PG8_WAIT_L(0); PG8_BAR; PG8_MMA(1, 0, At, B0); PG8_MMA(1, 1, At, B1); PG8_BAR; PG8_SCHED;
	global_load_lds_dwordx4 v144, s[54:55]
	s_add_i32 m0, s89, 0x2000
	s_add_u32 s52, s52, 0xc000
	s_addc_u32 s53, s53, 0
	global_load_lds_dwordx4 v140, s[54:55]
	s_add_i32 s54, s90, s61
	s_mov_b32 m0, s54
	ds_read_b128 v[226:229], v171 offset:56320
	global_load_lds_dwordx4 v144, s[52:53]
	s_add_i32 m0, s54, 0x2000
	ds_read_b128 v[222:225], v171 offset:55296
	global_load_lds_dwordx4 v140, s[52:53]
	s_mov_b32 m0, s77
	ds_read_b128 v[218:221], v171 offset:54272
	global_load_lds_dwordx4 v146, s[50:51]
	s_mov_b32 m0, s78
	ds_read_b128 v[214:217], v171 offset:53248
	global_load_lds_dwordx4 v142, s[50:51]
	s_waitcnt vmcnt(8)
	s_waitcnt lgkmcnt(0)
	s_barrier


; #define PG8_MMA(ai, bj, At, Bt) do { __builtin_amdgcn_s_setprio(1); _Pragma("unroll") for (int m = 0; m < 4; ++m) _Pragma("unroll") for (int n = 0; n < 2; ++n) _Pragma("unroll") for (int k = 0; k < 2; ++k) \
;         acc[ai][bj][m][n] = __builtin_amdgcn_mfma_f32_16x16x32_bf16(Bt[n][k], At[m][k], acc[ai][bj][m][n], 0, 0, 0); __builtin_amdgcn_s_setprio(0); } while (0)
; #define PG8_WAIT_V(n) asm volatile("s_waitcnt vmcnt(" #n ")" ::: "memory")
; #define PG8_WAIT_L(n) asm volatile("s_waitcnt lgkmcnt(" #n ")" ::: "memory")
; #define PG8_BAR __builtin_amdgcn_s_barrier()
; #define PG8_SCHED __builtin_amdgcn_sched_barrier(0)
; template <class Epi, bool ALIGN_EPI>
; __device__ __forceinline__ void gemm_phase(LAS unsigned char* lds, const Gemm g, const StaticOrder& S, const Epi& E, const int tid) {
;     ...
;             PG8_WAIT_V(8); PG8_WAIT_L(0); PG8_BAR; PG8_MMA(1, 0, At, B0); PG8_MMA(1, 1, At, B1); PG8_BAR; PG8_SCHED;
	v_mfma_f32_16x16x32_bf16 v[84:87], v[132:135], v[184:187], v[84:87]
	v_mfma_f32_16x16x32_bf16 v[56:59], v[152:155], v[184:187], v[56:59]
	v_mfma_f32_16x16x32_bf16 v[72:75], v[132:135], v[192:195], v[72:75]
	v_mfma_f32_16x16x32_bf16 v[44:47], v[152:155], v[192:195], v[44:47]
	v_mfma_f32_16x16x32_bf16 v[64:67], v[132:135], v[214:217], v[64:67]
	v_mfma_f32_16x16x32_bf16 v[36:39], v[152:155], v[214:217], v[36:39]
	v_mfma_f32_16x16x32_bf16 v[52:55], v[132:135], v[222:225], v[52:55]
	v_mfma_f32_16x16x32_bf16 v[28:31], v[152:155], v[222:225], v[28:31]
	v_mfma_f32_16x16x32_bf16 v[84:87], v[136:139], v[188:191], v[84:87]
	v_mfma_f32_16x16x32_bf16 v[56:59], v[156:159], v[188:191], v[56:59]
	v_mfma_f32_16x16x32_bf16 v[72:75], v[136:139], v[196:199], v[72:75]
	v_mfma_f32_16x16x32_bf16 v[44:47], v[156:159], v[196:199], v[44:47]
	v_mfma_f32_16x16x32_bf16 v[64:67], v[136:139], v[218:221], v[64:67]
	v_mfma_f32_16x16x32_bf16 v[36:39], v[156:159], v[218:221], v[36:39]
	v_mfma_f32_16x16x32_bf16 v[52:55], v[136:139], v[226:229], v[52:55]
	v_mfma_f32_16x16x32_bf16 v[28:31], v[156:159], v[226:229], v[28:31]


; #define PG8_MMA(ai, bj, At, Bt) do { __builtin_amdgcn_s_setprio(1); _Pragma("unroll") for (int m = 0; m < 4; ++m) _Pragma("unroll") for (int n = 0; n < 2; ++n) _Pragma("unroll") for (int k = 0; k < 2; ++k) \
;         acc[ai][bj][m][n] = __builtin_amdgcn_mfma_f32_16x16x32_bf16(Bt[n][k], At[m][k], acc[ai][bj][m][n], 0, 0, 0); __builtin_amdgcn_s_setprio(0); } while (0)
; #define PG8_WAIT_V(n) asm volatile("s_waitcnt vmcnt(" #n ")" ::: "memory")
; #define PG8_WAIT_L(n) asm volatile("s_waitcnt lgkmcnt(" #n ")" ::: "memory")
; #define PG8_BAR __builtin_amdgcn_s_barrier()
; #define PG8_SCHED __builtin_amdgcn_sched_barrier(0)
; template <class Epi, bool ALIGN_EPI>
; __device__ __forceinline__ void gemm_phase(LAS unsigned char* lds, const Gemm g, const StaticOrder& S, const Epi& E, const int tid) {
;     ...
;             PG8_WAIT_V(8); PG8_WAIT_L(0); PG8_BAR; PG8_MMA(1, 0, At, B0); PG8_MMA(1, 1, At, B1); PG8_BAR; PG8_SCHED;
	v_mfma_f32_16x16x32_bf16 v[40:43], v[160:163], v[184:187], v[40:43]
	v_mfma_f32_16x16x32_bf16 v[20:23], v[176:179], v[184:187], v[20:23]
	v_mfma_f32_16x16x32_bf16 v[32:35], v[160:163], v[192:195], v[32:35]
	v_mfma_f32_16x16x32_bf16 v[12:15], v[176:179], v[192:195], v[12:15]
	v_mfma_f32_16x16x32_bf16 v[24:27], v[160:163], v[214:217], v[24:27]
	v_mfma_f32_16x16x32_bf16 v[6:9], v[176:179], v[214:217], v[8:11]
	v_mfma_f32_16x16x32_bf16 v[16:19], v[160:163], v[222:225], v[16:19]
	v_mfma_f32_16x16x32_bf16 v[2:5], v[176:179], v[222:225], v[2:5]
	v_mfma_f32_16x16x32_bf16 v[40:43], v[172:175], v[188:191], v[40:43]
	v_mfma_f32_16x16x32_bf16 v[20:23], v[180:183], v[188:191], v[20:23]
	v_mfma_f32_16x16x32_bf16 v[32:35], v[172:175], v[196:199], v[32:35]
	v_mfma_f32_16x16x32_bf16 v[12:15], v[180:183], v[196:199], v[12:15]
	v_mfma_f32_16x16x32_bf16 v[24:27], v[172:175], v[218:221], v[24:27]
	v_mfma_f32_16x16x32_bf16 v[8:11], v[180:183], v[218:221], v[6:9]
	v_mfma_f32_16x16x32_bf16 v[16:19], v[172:175], v[226:229], v[16:19]
	v_mfma_f32_16x16x32_bf16 v[4:7], v[180:183], v[226:229], v[2:5]

; #define PG8_MMA(ai, bj, At, Bt) do { __builtin_amdgcn_s_setprio(1); _Pragma("unroll") for (int m = 0; m < 4; ++m) _Pragma("unroll") for (int n = 0; n < 2; ++n) _Pragma("unroll") for (int k = 0; k < 2; ++k) \
;         acc[ai][bj][m][n] = __builtin_amdgcn_mfma_f32_16x16x32_bf16(Bt[n][k], At[m][k], acc[ai][bj][m][n], 0, 0, 0); __builtin_amdgcn_s_setprio(0); } while (0)
; #define PG8_WAIT_V(n) asm volatile("s_waitcnt vmcnt(" #n ")" ::: "memory")
; #define PG8_WAIT_L(n) asm volatile("s_waitcnt lgkmcnt(" #n ")" ::: "memory")
; #define PG8_BAR __builtin_amdgcn_s_barrier()
; #define PG8_SCHED __builtin_amdgcn_sched_barrier(0)
; template <class Epi, bool ALIGN_EPI>
; __device__ __forceinline__ void gemm_phase(LAS unsigned char* lds, const Gemm g, const StaticOrder& S, const Epi& E, const int tid) {
;     ...
;             PG8_WAIT_V(8); PG8_WAIT_L(0); PG8_BAR; PG8_MMA(1, 0, At, B0); PG8_MMA(1, 1, At, B1); PG8_BAR; PG8_SCHED;
;         }
;         if constexpr (ALIGN_EPI) { if (wr == 0) PG8_BAR; }
	s_barrier
	s_add_i32 s88, s88, 2
	s_add_u32 s48, s48, 0x10000
	s_addc_u32 s49, s49, 0
	s_add_u32 s86, s86, 0x10000
	s_addc_u32 s87, s87, 0
	s_cmp_gt_u32 s88, 29
	s_cbranch_scc0 .LBB0_385
	s_and_b64 vcc, exec, s[34:35]
	s_cbranch_vccz .LBB0_388
	s_barrier

; #define PG8_STAGE(bufoff, gbase, voff) do { _Pragma("unroll") for (int _i = 0; _i < 2; ++_i) \
;         __builtin_amdgcn_global_load_lds((const unsigned*)((const char*)(gbase) + (voff)[_i]), (LAS unsigned*)(lds + (bufoff) + ldsw + _i * 8192), 16, 0, 0); } while (0)
; #define PG8_LDA(dst, b, h) do { _Pragma("unroll") for (int m = 0; m < 4; ++m) _Pragma("unroll") for (int k = 0; k < 2; ++k) dst[m][k] = *(const LAS bf16x8*)(lds + PG8_SA(b, h) + aoff + m * 2048 + k * 1024); } while (0)
; #define PG8_LDB(dst, b, h) do { _Pragma("unroll") for (int n = 0; n < 2; ++n) _Pragma("unroll") for (int k = 0; k < 2; ++k) dst[n][k] = *(const LAS bf16x8*)(lds + PG8_SB(b, h) + boff + n * 2048 + k * 1024); } while (0)
; #define PG8_SCHED __builtin_amdgcn_sched_barrier(0)
; template <class Epi, bool ALIGN_EPI>
; __device__ __forceinline__ void gemm_phase(LAS unsigned char* lds, const Gemm g, const StaticOrder& S, const Epi& E, const int tid) {
;     ...
;         const char* nA = has_next ? (const char*)g.A + (size_t)nxt.pm * tstepA + (size_t)nxt.pn * g.acs : cA; const char* nB = has_next ? (const char*)g.Bt + (size_t)nxt.pn * tstepB : cB;
;         for (int t = 0; t < nt; t += 2) {
;             const bool last = (t == nt - 2);
;             const char* a1 = cA + (size_t)(t + 1) * kstepA;
;             const char* a2 = last ? nA : cA + (size_t)(t + 2) * kstepA; const char* b2 = last ? nB : cB + (size_t)(t + 2) * kstepB;
;             const char* a3 = a2 + kstepA; const char* b3 = b2 + kstepB;
;             PG8_LDB(B0, 0, 0); PG8_LDB(B1, 0, 1); PG8_SCHED; PG8_LDA(At, 0, 0); PG8_STAGE(PG8_SA(1, 1), a1 + hstepA, voffA);
.LBB0_846:
	s_ashr_i32 s49, s48, 31
	s_lshl_b64 s[34:35], s[48:49], 20
	s_add_u32 s50, s55, s34
	s_addc_u32 s51, s56, s35
	s_and_b64 s[34:35], s[38:39], exec
	s_cselect_b32 s49, s51, s11
	s_cselect_b32 s82, s50, s10
	s_ashr_i32 s47, s46, 31
	s_lshl_b64 s[34:35], s[46:47], 20
	s_add_u32 s52, s57, s34
	s_addc_u32 s53, s60, s35
	s_and_b64 s[34:35], s[38:39], exec
	s_cselect_b32 s47, s53, s23
	s_cselect_b32 s83, s52, s22
	s_add_u32 s10, s10, 0x80080
	s_addc_u32 s11, s11, 0
	s_add_u32 s84, s22, 0x10000
	s_addc_u32 s85, s23, 0
	s_mov_b32 s86, -2
	v_add_u32_e32 v241, 0x10000, v154
	v_add_u32_e32 v242, 0x14000, v154
	v_add_u32_e32 v243, 0x18000, v154
	v_add_u32_e32 v244, 0x1c000, v154
.LBB0_847:
	s_add_u32 s22, s10, 0xfff80080
	s_addc_u32 s23, s11, -1
	s_add_i32 s87, 0, 0x10000
	s_cmp_eq_u32 s86, 28
	s_cselect_b32 s35, s49, s23
	s_cselect_b32 s34, s82, s22

; #define PG8_STAGE(bufoff, gbase, voff) do { _Pragma("unroll") for (int _i = 0; _i < 2; ++_i) \
;         __builtin_amdgcn_global_load_lds((const unsigned*)((const char*)(gbase) + (voff)[_i]), (LAS unsigned*)(lds + (bufoff) + ldsw + _i * 8192), 16, 0, 0); } while (0)
; #define PG8_LDA(dst, b, h) do { _Pragma("unroll") for (int m = 0; m < 4; ++m) _Pragma("unroll") for (int k = 0; k < 2; ++k) dst[m][k] = *(const LAS bf16x8*)(lds + PG8_SA(b, h) + aoff + m * 2048 + k * 1024); } while (0)
; #define PG8_LDB(dst, b, h) do { _Pragma("unroll") for (int n = 0; n < 2; ++n) _Pragma("unroll") for (int k = 0; k < 2; ++k) dst[n][k] = *(const LAS bf16x8*)(lds + PG8_SB(b, h) + boff + n * 2048 + k * 1024); } while (0)
; #define PG8_SCHED __builtin_amdgcn_sched_barrier(0)
; template <class Epi, bool ALIGN_EPI>
; __device__ __forceinline__ void gemm_phase(LAS unsigned char* lds, const Gemm g, const StaticOrder& S, const Epi& E, const int tid) {
;     ...
;             PG8_LDB(B0, 0, 0); PG8_LDB(B1, 0, 1); PG8_SCHED; PG8_LDA(At, 0, 0); PG8_STAGE(PG8_SA(1, 1), a1 + hstepA, voffA);
	s_cselect_b32 s23, s47, s85
	s_cselect_b32 s22, s83, s84
	s_add_i32 s90, 0, 0x14000
	s_waitcnt lgkmcnt(0)
	ds_read_b128 v[132:135], v241
	ds_read_b128 v[148:151], v241 offset:1024
	ds_read_b128 v[156:159], v241 offset:2048
	ds_read_b128 v[160:163], v241 offset:3072

; #define PG8_STAGE(bufoff, gbase, voff) do { _Pragma("unroll") for (int _i = 0; _i < 2; ++_i) \
;         __builtin_amdgcn_global_load_lds((const unsigned*)((const char*)(gbase) + (voff)[_i]), (LAS unsigned*)(lds + (bufoff) + ldsw + _i * 8192), 16, 0, 0); } while (0)
; #define PG8_LDA(dst, b, h) do { _Pragma("unroll") for (int m = 0; m < 4; ++m) _Pragma("unroll") for (int k = 0; k < 2; ++k) dst[m][k] = *(const LAS bf16x8*)(lds + PG8_SA(b, h) + aoff + m * 2048 + k * 1024); } while (0)
; #define PG8_LDB(dst, b, h) do { _Pragma("unroll") for (int n = 0; n < 2; ++n) _Pragma("unroll") for (int k = 0; k < 2; ++k) dst[n][k] = *(const LAS bf16x8*)(lds + PG8_SB(b, h) + boff + n * 2048 + k * 1024); } while (0)
; #define PG8_SCHED __builtin_amdgcn_sched_barrier(0)
; template <class Epi, bool ALIGN_EPI>
; __device__ __forceinline__ void gemm_phase(LAS unsigned char* lds, const Gemm g, const StaticOrder& S, const Epi& E, const int tid) {
;     ...
;             PG8_LDB(B0, 0, 0); PG8_LDB(B1, 0, 1); PG8_SCHED; PG8_LDA(At, 0, 0); PG8_STAGE(PG8_SA(1, 1), a1 + hstepA, voffA);
	ds_read_b128 v[164:167], v242
	ds_read_b128 v[168:171], v242 offset:1024
	ds_read_b128 v[172:175], v242 offset:2048
	ds_read_b128 v[176:179], v242 offset:3072
	s_add_i32 m0, s70, 0xc000
	ds_read_b128 v[180:183], v155
	ds_read_b128 v[184:187], v155 offset:1024
	ds_read_b128 v[188:191], v155 offset:2048
	ds_read_b128 v[192:195], v155 offset:3072
	ds_read_b128 v[196:199], v155 offset:4096
	ds_read_b128 v[214:217], v155 offset:5120
	ds_read_b128 v[218:221], v155 offset:6144

; #define PG8_STAGE(bufoff, gbase, voff) do { _Pragma("unroll") for (int _i = 0; _i < 2; ++_i) \
;         __builtin_amdgcn_global_load_lds((const unsigned*)((const char*)(gbase) + (voff)[_i]), (LAS unsigned*)(lds + (bufoff) + ldsw + _i * 8192), 16, 0, 0); } while (0)
; #define PG8_LDA(dst, b, h) do { _Pragma("unroll") for (int m = 0; m < 4; ++m) _Pragma("unroll") for (int k = 0; k < 2; ++k) dst[m][k] = *(const LAS bf16x8*)(lds + PG8_SA(b, h) + aoff + m * 2048 + k * 1024); } while (0)
; #define PG8_LDB(dst, b, h) do { _Pragma("unroll") for (int n = 0; n < 2; ++n) _Pragma("unroll") for (int k = 0; k < 2; ++k) dst[n][k] = *(const LAS bf16x8*)(lds + PG8_SB(b, h) + boff + n * 2048 + k * 1024); } while (0)
; #define PG8_MMA(ai, bj, At, Bt) do { __builtin_amdgcn_s_setprio(1); _Pragma("unroll") for (int m = 0; m < 4; ++m) _Pragma("unroll") for (int n = 0; n < 2; ++n) _Pragma("unroll") for (int k = 0; k < 2; ++k) \
;         acc[ai][bj][m][n] = __builtin_amdgcn_mfma_f32_16x16x32_bf16(Bt[n][k], At[m][k], acc[ai][bj][m][n], 0, 0, 0); __builtin_amdgcn_s_setprio(0); } while (0)
; #define PG8_WAIT_V(n) asm volatile("s_waitcnt vmcnt(" #n ")" ::: "memory")
; #define PG8_WAIT_L(n) asm volatile("s_waitcnt lgkmcnt(" #n ")" ::: "memory")
; #define PG8_BAR __builtin_amdgcn_s_barrier()
; #define PG8_SCHED __builtin_amdgcn_sched_barrier(0)
; template <class Epi, bool ALIGN_EPI>
; __device__ __forceinline__ void gemm_phase(LAS unsigned char* lds, const Gemm g, const StaticOrder& S, const Epi& E, const int tid) {
;     ...
;             PG8_LDB(B0, 0, 0); PG8_LDB(B1, 0, 1); PG8_SCHED; PG8_LDA(At, 0, 0); PG8_STAGE(PG8_SA(1, 1), a1 + hstepA, voffA);
;             PG8_WAIT_V(8); PG8_WAIT_L(0); PG8_BAR; PG8_MMA(0, 0, At, B0); PG8_MMA(0, 1, At, B1); PG8_BAR; PG8_SCHED;
	global_load_lds_dwordx4 v144, s[10:11]
	s_add_i32 m0, s70, 0xe000
	ds_read_b128 v[222:225], v155 offset:7168
	global_load_lds_dwordx4 v146, s[10:11]
	s_waitcnt vmcnt(8)
	s_waitcnt lgkmcnt(0)
	s_barrier


; #define PG8_MMA(ai, bj, At, Bt) do { __builtin_amdgcn_s_setprio(1); _Pragma("unroll") for (int m = 0; m < 4; ++m) _Pragma("unroll") for (int n = 0; n < 2; ++n) _Pragma("unroll") for (int k = 0; k < 2; ++k) \
;         acc[ai][bj][m][n] = __builtin_amdgcn_mfma_f32_16x16x32_bf16(Bt[n][k], At[m][k], acc[ai][bj][m][n], 0, 0, 0); __builtin_amdgcn_s_setprio(0); } while (0)
; #define PG8_WAIT_V(n) asm volatile("s_waitcnt vmcnt(" #n ")" ::: "memory")
; #define PG8_WAIT_L(n) asm volatile("s_waitcnt lgkmcnt(" #n ")" ::: "memory")
; #define PG8_BAR __builtin_amdgcn_s_barrier()
; #define PG8_SCHED __builtin_amdgcn_sched_barrier(0)
; template <class Epi, bool ALIGN_EPI>
; __device__ __forceinline__ void gemm_phase(LAS unsigned char* lds, const Gemm g, const StaticOrder& S, const Epi& E, const int tid) {
;     ...
;             PG8_WAIT_V(8); PG8_WAIT_L(0); PG8_BAR; PG8_MMA(0, 0, At, B0); PG8_MMA(0, 1, At, B1); PG8_BAR; PG8_SCHED;
	v_mfma_f32_16x16x32_bf16 v[8:11], v[132:135], v[180:183], v[8:11]
	v_mfma_f32_16x16x32_bf16 v[56:59], v[156:159], v[180:183], v[56:59]
	v_mfma_f32_16x16x32_bf16 v[52:55], v[132:135], v[188:191], v[52:55]
	v_mfma_f32_16x16x32_bf16 v[48:51], v[156:159], v[188:191], v[48:51]
	v_mfma_f32_16x16x32_bf16 v[44:47], v[132:135], v[196:199], v[44:47]
	v_mfma_f32_16x16x32_bf16 v[40:43], v[156:159], v[196:199], v[40:43]
	v_mfma_f32_16x16x32_bf16 v[36:39], v[132:135], v[218:221], v[36:39]
	v_mfma_f32_16x16x32_bf16 v[32:35], v[156:159], v[218:221], v[32:35]
	v_mfma_f32_16x16x32_bf16 v[8:11], v[148:151], v[184:187], v[8:11]
	v_mfma_f32_16x16x32_bf16 v[56:59], v[160:163], v[184:187], v[56:59]
	v_mfma_f32_16x16x32_bf16 v[52:55], v[148:151], v[192:195], v[52:55]
	v_mfma_f32_16x16x32_bf16 v[48:51], v[160:163], v[192:195], v[48:51]
	v_mfma_f32_16x16x32_bf16 v[44:47], v[148:151], v[214:217], v[44:47]
	v_mfma_f32_16x16x32_bf16 v[40:43], v[160:163], v[214:217], v[40:43]
	v_mfma_f32_16x16x32_bf16 v[36:39], v[148:151], v[222:225], v[36:39]
	v_mfma_f32_16x16x32_bf16 v[32:35], v[160:163], v[222:225], v[32:35]


; #define PG8_MMA(ai, bj, At, Bt) do { __builtin_amdgcn_s_setprio(1); _Pragma("unroll") for (int m = 0; m < 4; ++m) _Pragma("unroll") for (int n = 0; n < 2; ++n) _Pragma("unroll") for (int k = 0; k < 2; ++k) \
;         acc[ai][bj][m][n] = __builtin_amdgcn_mfma_f32_16x16x32_bf16(Bt[n][k], At[m][k], acc[ai][bj][m][n], 0, 0, 0); __builtin_amdgcn_s_setprio(0); } while (0)
; #define PG8_WAIT_V(n) asm volatile("s_waitcnt vmcnt(" #n ")" ::: "memory")
; #define PG8_WAIT_L(n) asm volatile("s_waitcnt lgkmcnt(" #n ")" ::: "memory")
; #define PG8_BAR __builtin_amdgcn_s_barrier()
; #define PG8_SCHED __builtin_amdgcn_sched_barrier(0)
; template <class Epi, bool ALIGN_EPI>
; __device__ __forceinline__ void gemm_phase(LAS unsigned char* lds, const Gemm g, const StaticOrder& S, const Epi& E, const int tid) {
;     ...
;             PG8_WAIT_V(8); PG8_WAIT_L(0); PG8_BAR; PG8_MMA(0, 0, At, B0); PG8_MMA(0, 1, At, B1); PG8_BAR; PG8_SCHED;
	v_mfma_f32_16x16x32_bf16 v[2:5], v[164:167], v[180:183], v[4:7]
	v_mfma_f32_16x16x32_bf16 v[28:31], v[172:175], v[180:183], v[28:31]
	v_mfma_f32_16x16x32_bf16 v[96:99], v[164:167], v[188:191], v[96:99]
	v_mfma_f32_16x16x32_bf16 v[92:95], v[172:175], v[188:191], v[92:95]
	v_mfma_f32_16x16x32_bf16 v[88:91], v[164:167], v[196:199], v[88:91]
	v_mfma_f32_16x16x32_bf16 v[84:87], v[172:175], v[196:199], v[84:87]
	v_mfma_f32_16x16x32_bf16 v[80:83], v[164:167], v[218:221], v[80:83]
	v_mfma_f32_16x16x32_bf16 v[76:79], v[172:175], v[218:221], v[76:79]
	v_mfma_f32_16x16x32_bf16 v[2:5], v[168:171], v[184:187], v[2:5]
	v_mfma_f32_16x16x32_bf16 v[28:31], v[176:179], v[184:187], v[28:31]
	v_mfma_f32_16x16x32_bf16 v[96:99], v[168:171], v[192:195], v[96:99]
	v_mfma_f32_16x16x32_bf16 v[92:95], v[176:179], v[192:195], v[92:95]
	v_mfma_f32_16x16x32_bf16 v[88:91], v[168:171], v[214:217], v[88:91]
	v_mfma_f32_16x16x32_bf16 v[84:87], v[176:179], v[214:217], v[84:87]
	v_mfma_f32_16x16x32_bf16 v[80:83], v[168:171], v[222:225], v[80:83]
	v_mfma_f32_16x16x32_bf16 v[76:79], v[176:179], v[222:225], v[76:79]

; #define PG8_STAGE(bufoff, gbase, voff) do { _Pragma("unroll") for (int _i = 0; _i < 2; ++_i) \
;         __builtin_amdgcn_global_load_lds((const unsigned*)((const char*)(gbase) + (voff)[_i]), (LAS unsigned*)(lds + (bufoff) + ldsw + _i * 8192), 16, 0, 0); } while (0)
; #define PG8_LDA(dst, b, h) do { _Pragma("unroll") for (int m = 0; m < 4; ++m) _Pragma("unroll") for (int k = 0; k < 2; ++k) dst[m][k] = *(const LAS bf16x8*)(lds + PG8_SA(b, h) + aoff + m * 2048 + k * 1024); } while (0)
; #define PG8_MMA(ai, bj, At, Bt) do { __builtin_amdgcn_s_setprio(1); _Pragma("unroll") for (int m = 0; m < 4; ++m) _Pragma("unroll") for (int n = 0; n < 2; ++n) _Pragma("unroll") for (int k = 0; k < 2; ++k) \
;         acc[ai][bj][m][n] = __builtin_amdgcn_mfma_f32_16x16x32_bf16(Bt[n][k], At[m][k], acc[ai][bj][m][n], 0, 0, 0); __builtin_amdgcn_s_setprio(0); } while (0)
; #define PG8_WAIT_V(n) asm volatile("s_waitcnt vmcnt(" #n ")" ::: "memory")
; #define PG8_WAIT_L(n) asm volatile("s_waitcnt lgkmcnt(" #n ")" ::: "memory")
; #define PG8_BAR __builtin_amdgcn_s_barrier()
; #define PG8_SCHED __builtin_amdgcn_sched_barrier(0)
; template <class Epi, bool ALIGN_EPI>
; __device__ __forceinline__ void gemm_phase(LAS unsigned char* lds, const Gemm g, const StaticOrder& S, const Epi& E, const int tid) {
;     ...
;             PG8_WAIT_V(8); PG8_WAIT_L(0); PG8_BAR; PG8_MMA(0, 0, At, B0); PG8_MMA(0, 1, At, B1); PG8_BAR; PG8_SCHED;
;             PG8_LDA(At, 0, 1); PG8_STAGE(PG8_SB(0, 0), b2, voffB); PG8_STAGE(PG8_SB(0, 1), b2 + hstepB, voffB); PG8_STAGE(PG8_SA(0, 0), a2, voffA);
	s_barrier
	s_add_i32 s87, s87, s61
	s_mov_b32 m0, s87
	ds_read_b128 v[180:183], v155 offset:16384
	ds_read_b128 v[184:187], v155 offset:17408
	ds_read_b128 v[188:191], v155 offset:18432
	ds_read_b128 v[192:195], v155 offset:19456
	ds_read_b128 v[196:199], v155 offset:20480
	ds_read_b128 v[214:217], v155 offset:21504


; #define PG8_STAGE(bufoff, gbase, voff) do { _Pragma("unroll") for (int _i = 0; _i < 2; ++_i) \
;         __builtin_amdgcn_global_load_lds((const unsigned*)((const char*)(gbase) + (voff)[_i]), (LAS unsigned*)(lds + (bufoff) + ldsw + _i * 8192), 16, 0, 0); } while (0)
; #define PG8_LDA(dst, b, h) do { _Pragma("unroll") for (int m = 0; m < 4; ++m) _Pragma("unroll") for (int k = 0; k < 2; ++k) dst[m][k] = *(const LAS bf16x8*)(lds + PG8_SA(b, h) + aoff + m * 2048 + k * 1024); } while (0)
; #define PG8_MMA(ai, bj, At, Bt) do { __builtin_amdgcn_s_setprio(1); _Pragma("unroll") for (int m = 0; m < 4; ++m) _Pragma("unroll") for (int n = 0; n < 2; ++n) _Pragma("unroll") for (int k = 0; k < 2; ++k) \
;         acc[ai][bj][m][n] = __builtin_amdgcn_mfma_f32_16x16x32_bf16(Bt[n][k], At[m][k], acc[ai][bj][m][n], 0, 0, 0); __builtin_amdgcn_s_setprio(0); } while (0)
; #define PG8_WAIT_V(n) asm volatile("s_waitcnt vmcnt(" #n ")" ::: "memory")
; #define PG8_WAIT_L(n) asm volatile("s_waitcnt lgkmcnt(" #n ")" ::: "memory")
; #define PG8_BAR __builtin_amdgcn_s_barrier()
; #define PG8_SCHED __builtin_amdgcn_sched_barrier(0)
; template <class Epi, bool ALIGN_EPI>
; __device__ __forceinline__ void gemm_phase(LAS unsigned char* lds, const Gemm g, const StaticOrder& S, const Epi& E, const int tid) {
;     ...
;             PG8_LDA(At, 0, 1); PG8_STAGE(PG8_SB(0, 0), b2, voffB); PG8_STAGE(PG8_SB(0, 1), b2 + hstepB, voffB); PG8_STAGE(PG8_SA(0, 0), a2, voffA);
;             PG8_WAIT_V(8); PG8_WAIT_L(0); PG8_BAR; PG8_MMA(1, 0, At, B0); PG8_MMA(1, 1, At, B1); PG8_BAR; PG8_SCHED;
	global_load_lds_dwordx4 v140, s[22:23]
	s_add_i32 m0, s87, 0x2000
	s_add_u32 s88, s22, 0x4000
	s_addc_u32 s89, s23, 0
	s_add_i32 s87, s90, s61
	global_load_lds_dwordx4 v136, s[22:23]
	s_mov_b32 m0, s87
	v_lshl_add_u64 v[152:153], s[34:35], 0, v[142:143]
	global_load_lds_dwordx4 v140, s[88:89]
	s_add_i32 m0, s87, 0x2000
	v_lshl_add_u64 v[200:201], s[34:35], 0, v[138:139]
	global_load_lds_dwordx4 v136, s[88:89]
	s_mov_b32 m0, s70
	ds_read_b128 v[222:225], v155 offset:23552
	global_load_lds_dwordx4 v[152:153], off
	s_mov_b32 m0, s71
	ds_read_b128 v[218:221], v155 offset:22528
	global_load_lds_dwordx4 v[200:201], off
	s_waitcnt vmcnt(8)
	s_waitcnt lgkmcnt(0)
	s_barrier


; #define PG8_MMA(ai, bj, At, Bt) do { __builtin_amdgcn_s_setprio(1); _Pragma("unroll") for (int m = 0; m < 4; ++m) _Pragma("unroll") for (int n = 0; n < 2; ++n) _Pragma("unroll") for (int k = 0; k < 2; ++k) \
;         acc[ai][bj][m][n] = __builtin_amdgcn_mfma_f32_16x16x32_bf16(Bt[n][k], At[m][k], acc[ai][bj][m][n], 0, 0, 0); __builtin_amdgcn_s_setprio(0); } while (0)
; #define PG8_WAIT_V(n) asm volatile("s_waitcnt vmcnt(" #n ")" ::: "memory")
; #define PG8_WAIT_L(n) asm volatile("s_waitcnt lgkmcnt(" #n ")" ::: "memory")
; #define PG8_BAR __builtin_amdgcn_s_barrier()
; #define PG8_SCHED __builtin_amdgcn_sched_barrier(0)
; template <class Epi, bool ALIGN_EPI>
; __device__ __forceinline__ void gemm_phase(LAS unsigned char* lds, const Gemm g, const StaticOrder& S, const Epi& E, const int tid) {
;     ...
;             PG8_WAIT_V(8); PG8_WAIT_L(0); PG8_BAR; PG8_MMA(1, 0, At, B0); PG8_MMA(1, 1, At, B1); PG8_BAR; PG8_SCHED;
	v_mfma_f32_16x16x32_bf16 v[24:27], v[132:135], v[180:183], v[24:27]
	v_mfma_f32_16x16x32_bf16 v[20:23], v[156:159], v[180:183], v[20:23]
	v_mfma_f32_16x16x32_bf16 v[64:67], v[132:135], v[188:191], v[64:67]
	v_mfma_f32_16x16x32_bf16 v[72:75], v[156:159], v[188:191], v[72:75]
	v_mfma_f32_16x16x32_bf16 v[16:19], v[132:135], v[196:199], v[16:19]
	v_mfma_f32_16x16x32_bf16 v[12:15], v[156:159], v[196:199], v[12:15]
	v_mfma_f32_16x16x32_bf16 v[60:63], v[132:135], v[218:221], v[60:63]
	v_mfma_f32_16x16x32_bf16 v[68:71], v[156:159], v[218:221], v[68:71]
	v_mfma_f32_16x16x32_bf16 v[24:27], v[148:151], v[184:187], v[24:27]
	v_mfma_f32_16x16x32_bf16 v[20:23], v[160:163], v[184:187], v[20:23]
	v_mfma_f32_16x16x32_bf16 v[64:67], v[148:151], v[192:195], v[64:67]
	v_mfma_f32_16x16x32_bf16 v[72:75], v[160:163], v[192:195], v[72:75]
	v_mfma_f32_16x16x32_bf16 v[16:19], v[148:151], v[214:217], v[16:19]
	v_mfma_f32_16x16x32_bf16 v[12:15], v[160:163], v[214:217], v[12:15]
	v_mfma_f32_16x16x32_bf16 v[60:63], v[148:151], v[222:225], v[60:63]
	v_mfma_f32_16x16x32_bf16 v[68:71], v[160:163], v[222:225], v[68:71]


; #define PG8_MMA(ai, bj, At, Bt) do { __builtin_amdgcn_s_setprio(1); _Pragma("unroll") for (int m = 0; m < 4; ++m) _Pragma("unroll") for (int n = 0; n < 2; ++n) _Pragma("unroll") for (int k = 0; k < 2; ++k) \
;         acc[ai][bj][m][n] = __builtin_amdgcn_mfma_f32_16x16x32_bf16(Bt[n][k], At[m][k], acc[ai][bj][m][n], 0, 0, 0); __builtin_amdgcn_s_setprio(0); } while (0)
; #define PG8_WAIT_V(n) asm volatile("s_waitcnt vmcnt(" #n ")" ::: "memory")
; #define PG8_WAIT_L(n) asm volatile("s_waitcnt lgkmcnt(" #n ")" ::: "memory")
; #define PG8_BAR __builtin_amdgcn_s_barrier()
; #define PG8_SCHED __builtin_amdgcn_sched_barrier(0)
; template <class Epi, bool ALIGN_EPI>
; __device__ __forceinline__ void gemm_phase(LAS unsigned char* lds, const Gemm g, const StaticOrder& S, const Epi& E, const int tid) {
;     ...
;             PG8_WAIT_V(8); PG8_WAIT_L(0); PG8_BAR; PG8_MMA(1, 0, At, B0); PG8_MMA(1, 1, At, B1); PG8_BAR; PG8_SCHED;
	v_mfma_f32_16x16x32_bf16 v[128:131], v[164:167], v[180:183], v[128:131]
	v_mfma_f32_16x16x32_bf16 v[124:127], v[172:175], v[180:183], v[124:127]
	v_mfma_f32_16x16x32_bf16 v[120:123], v[164:167], v[188:191], v[120:123]
	v_mfma_f32_16x16x32_bf16 v[116:119], v[172:175], v[188:191], v[116:119]
	v_mfma_f32_16x16x32_bf16 v[112:115], v[164:167], v[196:199], v[112:115]
	v_mfma_f32_16x16x32_bf16 v[108:111], v[172:175], v[196:199], v[108:111]
	v_mfma_f32_16x16x32_bf16 v[104:107], v[164:167], v[218:221], v[104:107]
	v_mfma_f32_16x16x32_bf16 v[100:103], v[172:175], v[218:221], v[100:103]
	v_mfma_f32_16x16x32_bf16 v[128:131], v[168:171], v[184:187], v[128:131]
	v_mfma_f32_16x16x32_bf16 v[124:127], v[176:179], v[184:187], v[124:127]
	v_mfma_f32_16x16x32_bf16 v[120:123], v[168:171], v[192:195], v[120:123]
	v_mfma_f32_16x16x32_bf16 v[116:119], v[176:179], v[192:195], v[116:119]
	v_mfma_f32_16x16x32_bf16 v[112:115], v[168:171], v[214:217], v[112:115]
	v_mfma_f32_16x16x32_bf16 v[108:111], v[176:179], v[214:217], v[108:111]
	v_mfma_f32_16x16x32_bf16 v[104:107], v[168:171], v[222:225], v[104:107]
	v_mfma_f32_16x16x32_bf16 v[100:103], v[176:179], v[222:225], v[100:103]

; #define PG8_STAGE(bufoff, gbase, voff) do { _Pragma("unroll") for (int _i = 0; _i < 2; ++_i) \
;         __builtin_amdgcn_global_load_lds((const unsigned*)((const char*)(gbase) + (voff)[_i]), (LAS unsigned*)(lds + (bufoff) + ldsw + _i * 8192), 16, 0, 0); } while (0)
; #define PG8_LDA(dst, b, h) do { _Pragma("unroll") for (int m = 0; m < 4; ++m) _Pragma("unroll") for (int k = 0; k < 2; ++k) dst[m][k] = *(const LAS bf16x8*)(lds + PG8_SA(b, h) + aoff + m * 2048 + k * 1024); } while (0)
; #define PG8_LDB(dst, b, h) do { _Pragma("unroll") for (int n = 0; n < 2; ++n) _Pragma("unroll") for (int k = 0; k < 2; ++k) dst[n][k] = *(const LAS bf16x8*)(lds + PG8_SB(b, h) + boff + n * 2048 + k * 1024); } while (0)
; #define PG8_SCHED __builtin_amdgcn_sched_barrier(0)
; template <class Epi, bool ALIGN_EPI>
; __device__ __forceinline__ void gemm_phase(LAS unsigned char* lds, const Gemm g, const StaticOrder& S, const Epi& E, const int tid) {
;     ...
;             PG8_LDB(B0, 1, 0); PG8_LDB(B1, 1, 1); PG8_SCHED; PG8_LDA(At, 1, 0); PG8_STAGE(PG8_SA(0, 1), a2 + hstepA, voffA);
	s_barrier
	s_add_i32 s87, 0, 0x18000

; #define PG8_STAGE(bufoff, gbase, voff) do { _Pragma("unroll") for (int _i = 0; _i < 2; ++_i) \
;         __builtin_amdgcn_global_load_lds((const unsigned*)((const char*)(gbase) + (voff)[_i]), (LAS unsigned*)(lds + (bufoff) + ldsw + _i * 8192), 16, 0, 0); } while (0)
; #define PG8_LDA(dst, b, h) do { _Pragma("unroll") for (int m = 0; m < 4; ++m) _Pragma("unroll") for (int k = 0; k < 2; ++k) dst[m][k] = *(const LAS bf16x8*)(lds + PG8_SA(b, h) + aoff + m * 2048 + k * 1024); } while (0)
; #define PG8_LDB(dst, b, h) do { _Pragma("unroll") for (int n = 0; n < 2; ++n) _Pragma("unroll") for (int k = 0; k < 2; ++k) dst[n][k] = *(const LAS bf16x8*)(lds + PG8_SB(b, h) + boff + n * 2048 + k * 1024); } while (0)
; #define PG8_SCHED __builtin_amdgcn_sched_barrier(0)
; template <class Epi, bool ALIGN_EPI>
; __device__ __forceinline__ void gemm_phase(LAS unsigned char* lds, const Gemm g, const StaticOrder& S, const Epi& E, const int tid) {
;     ...
;             PG8_LDB(B0, 1, 0); PG8_LDB(B1, 1, 1); PG8_SCHED; PG8_LDA(At, 1, 0); PG8_STAGE(PG8_SA(0, 1), a2 + hstepA, voffA);
	s_add_i32 s88, 0, 0x1c000
	ds_read_b128 v[132:135], v243
	ds_read_b128 v[148:151], v243 offset:1024
	ds_read_b128 v[156:159], v243 offset:2048
	ds_read_b128 v[160:163], v243 offset:3072

; #define PG8_STAGE(bufoff, gbase, voff) do { _Pragma("unroll") for (int _i = 0; _i < 2; ++_i) \
;         __builtin_amdgcn_global_load_lds((const unsigned*)((const char*)(gbase) + (voff)[_i]), (LAS unsigned*)(lds + (bufoff) + ldsw + _i * 8192), 16, 0, 0); } while (0)
; #define PG8_LDA(dst, b, h) do { _Pragma("unroll") for (int m = 0; m < 4; ++m) _Pragma("unroll") for (int k = 0; k < 2; ++k) dst[m][k] = *(const LAS bf16x8*)(lds + PG8_SA(b, h) + aoff + m * 2048 + k * 1024); } while (0)
; #define PG8_LDB(dst, b, h) do { _Pragma("unroll") for (int n = 0; n < 2; ++n) _Pragma("unroll") for (int k = 0; k < 2; ++k) dst[n][k] = *(const LAS bf16x8*)(lds + PG8_SB(b, h) + boff + n * 2048 + k * 1024); } while (0)
; #define PG8_SCHED __builtin_amdgcn_sched_barrier(0)
; template <class Epi, bool ALIGN_EPI>
; __device__ __forceinline__ void gemm_phase(LAS unsigned char* lds, const Gemm g, const StaticOrder& S, const Epi& E, const int tid) {
;     ...
;             PG8_LDB(B0, 1, 0); PG8_LDB(B1, 1, 1); PG8_SCHED; PG8_LDA(At, 1, 0); PG8_STAGE(PG8_SA(0, 1), a2 + hstepA, voffA);
	ds_read_b128 v[164:167], v244
	ds_read_b128 v[168:171], v244 offset:1024
	ds_read_b128 v[172:175], v244 offset:2048
	ds_read_b128 v[176:179], v244 offset:3072
	s_add_u32 s34, s34, 0x80000
	s_addc_u32 s35, s35, 0
	s_mov_b32 m0, s72
	ds_read_b128 v[180:183], v155 offset:32768
	ds_read_b128 v[184:187], v155 offset:33792
	ds_read_b128 v[188:191], v155 offset:34816
	ds_read_b128 v[192:195], v155 offset:35840
	ds_read_b128 v[196:199], v155 offset:36864
	ds_read_b128 v[214:217], v155 offset:37888
	ds_read_b128 v[218:221], v155 offset:38912

; #define PG8_STAGE(bufoff, gbase, voff) do { _Pragma("unroll") for (int _i = 0; _i < 2; ++_i) \
;         __builtin_amdgcn_global_load_lds((const unsigned*)((const char*)(gbase) + (voff)[_i]), (LAS unsigned*)(lds + (bufoff) + ldsw + _i * 8192), 16, 0, 0); } while (0)
; #define PG8_LDA(dst, b, h) do { _Pragma("unroll") for (int m = 0; m < 4; ++m) _Pragma("unroll") for (int k = 0; k < 2; ++k) dst[m][k] = *(const LAS bf16x8*)(lds + PG8_SA(b, h) + aoff + m * 2048 + k * 1024); } while (0)
; #define PG8_LDB(dst, b, h) do { _Pragma("unroll") for (int n = 0; n < 2; ++n) _Pragma("unroll") for (int k = 0; k < 2; ++k) dst[n][k] = *(const LAS bf16x8*)(lds + PG8_SB(b, h) + boff + n * 2048 + k * 1024); } while (0)
; #define PG8_MMA(ai, bj, At, Bt) do { __builtin_amdgcn_s_setprio(1); _Pragma("unroll") for (int m = 0; m < 4; ++m) _Pragma("unroll") for (int n = 0; n < 2; ++n) _Pragma("unroll") for (int k = 0; k < 2; ++k) \
;         acc[ai][bj][m][n] = __builtin_amdgcn_mfma_f32_16x16x32_bf16(Bt[n][k], At[m][k], acc[ai][bj][m][n], 0, 0, 0); __builtin_amdgcn_s_setprio(0); } while (0)
; #define PG8_WAIT_V(n) asm volatile("s_waitcnt vmcnt(" #n ")" ::: "memory")
; #define PG8_WAIT_L(n) asm volatile("s_waitcnt lgkmcnt(" #n ")" ::: "memory")
; #define PG8_BAR __builtin_amdgcn_s_barrier()
; #define PG8_SCHED __builtin_amdgcn_sched_barrier(0)
; template <class Epi, bool ALIGN_EPI>
; __device__ __forceinline__ void gemm_phase(LAS unsigned char* lds, const Gemm g, const StaticOrder& S, const Epi& E, const int tid) {
;     ...
;             PG8_LDB(B0, 1, 0); PG8_LDB(B1, 1, 1); PG8_SCHED; PG8_LDA(At, 1, 0); PG8_STAGE(PG8_SA(0, 1), a2 + hstepA, voffA);
;             PG8_WAIT_V(8); PG8_WAIT_L(0); PG8_BAR; PG8_MMA(0, 0, At, B0); PG8_MMA(0, 1, At, B1); PG8_BAR; PG8_SCHED;
	global_load_lds_dwordx4 v142, s[34:35]
	s_mov_b32 m0, s73
	ds_read_b128 v[222:225], v155 offset:39936
	global_load_lds_dwordx4 v138, s[34:35]
	s_waitcnt vmcnt(8)
	s_waitcnt lgkmcnt(0)
	s_barrier


; #define PG8_MMA(ai, bj, At, Bt) do { __builtin_amdgcn_s_setprio(1); _Pragma("unroll") for (int m = 0; m < 4; ++m) _Pragma("unroll") for (int n = 0; n < 2; ++n) _Pragma("unroll") for (int k = 0; k < 2; ++k) \
;         acc[ai][bj][m][n] = __builtin_amdgcn_mfma_f32_16x16x32_bf16(Bt[n][k], At[m][k], acc[ai][bj][m][n], 0, 0, 0); __builtin_amdgcn_s_setprio(0); } while (0)
; #define PG8_WAIT_V(n) asm volatile("s_waitcnt vmcnt(" #n ")" ::: "memory")
; #define PG8_WAIT_L(n) asm volatile("s_waitcnt lgkmcnt(" #n ")" ::: "memory")
; #define PG8_BAR __builtin_amdgcn_s_barrier()
; #define PG8_SCHED __builtin_amdgcn_sched_barrier(0)
; template <class Epi, bool ALIGN_EPI>
; __device__ __forceinline__ void gemm_phase(LAS unsigned char* lds, const Gemm g, const StaticOrder& S, const Epi& E, const int tid) {
;     ...
;             PG8_WAIT_V(8); PG8_WAIT_L(0); PG8_BAR; PG8_MMA(0, 0, At, B0); PG8_MMA(0, 1, At, B1); PG8_BAR; PG8_SCHED;
	v_mfma_f32_16x16x32_bf16 v[6:9], v[132:135], v[180:183], v[8:11]
	v_mfma_f32_16x16x32_bf16 v[56:59], v[156:159], v[180:183], v[56:59]
	v_mfma_f32_16x16x32_bf16 v[52:55], v[132:135], v[188:191], v[52:55]
	v_mfma_f32_16x16x32_bf16 v[48:51], v[156:159], v[188:191], v[48:51]
	v_mfma_f32_16x16x32_bf16 v[44:47], v[132:135], v[196:199], v[44:47]
	v_mfma_f32_16x16x32_bf16 v[40:43], v[156:159], v[196:199], v[40:43]
	v_mfma_f32_16x16x32_bf16 v[36:39], v[132:135], v[218:221], v[36:39]
	v_mfma_f32_16x16x32_bf16 v[32:35], v[156:159], v[218:221], v[32:35]
	v_mfma_f32_16x16x32_bf16 v[8:11], v[148:151], v[184:187], v[6:9]
	v_mfma_f32_16x16x32_bf16 v[56:59], v[160:163], v[184:187], v[56:59]
	v_mfma_f32_16x16x32_bf16 v[52:55], v[148:151], v[192:195], v[52:55]
	v_mfma_f32_16x16x32_bf16 v[48:51], v[160:163], v[192:195], v[48:51]
	v_mfma_f32_16x16x32_bf16 v[44:47], v[148:151], v[214:217], v[44:47]
	v_mfma_f32_16x16x32_bf16 v[40:43], v[160:163], v[214:217], v[40:43]
	v_mfma_f32_16x16x32_bf16 v[36:39], v[148:151], v[222:225], v[36:39]
	v_mfma_f32_16x16x32_bf16 v[32:35], v[160:163], v[222:225], v[32:35]


; #define PG8_MMA(ai, bj, At, Bt) do { __builtin_amdgcn_s_setprio(1); _Pragma("unroll") for (int m = 0; m < 4; ++m) _Pragma("unroll") for (int n = 0; n < 2; ++n) _Pragma("unroll") for (int k = 0; k < 2; ++k) \
;         acc[ai][bj][m][n] = __builtin_amdgcn_mfma_f32_16x16x32_bf16(Bt[n][k], At[m][k], acc[ai][bj][m][n], 0, 0, 0); __builtin_amdgcn_s_setprio(0); } while (0)
; #define PG8_WAIT_V(n) asm volatile("s_waitcnt vmcnt(" #n ")" ::: "memory")
; #define PG8_WAIT_L(n) asm volatile("s_waitcnt lgkmcnt(" #n ")" ::: "memory")
; #define PG8_BAR __builtin_amdgcn_s_barrier()
; #define PG8_SCHED __builtin_amdgcn_sched_barrier(0)
; template <class Epi, bool ALIGN_EPI>
; __device__ __forceinline__ void gemm_phase(LAS unsigned char* lds, const Gemm g, const StaticOrder& S, const Epi& E, const int tid) {
;     ...
;             PG8_WAIT_V(8); PG8_WAIT_L(0); PG8_BAR; PG8_MMA(0, 0, At, B0); PG8_MMA(0, 1, At, B1); PG8_BAR; PG8_SCHED;
	v_mfma_f32_16x16x32_bf16 v[2:5], v[164:167], v[180:183], v[2:5]
	v_mfma_f32_16x16x32_bf16 v[28:31], v[172:175], v[180:183], v[28:31]
	v_mfma_f32_16x16x32_bf16 v[96:99], v[164:167], v[188:191], v[96:99]
	v_mfma_f32_16x16x32_bf16 v[92:95], v[172:175], v[188:191], v[92:95]
	v_mfma_f32_16x16x32_bf16 v[88:91], v[164:167], v[196:199], v[88:91]
	v_mfma_f32_16x16x32_bf16 v[84:87], v[172:175], v[196:199], v[84:87]
	v_mfma_f32_16x16x32_bf16 v[80:83], v[164:167], v[218:221], v[80:83]
	v_mfma_f32_16x16x32_bf16 v[76:79], v[172:175], v[218:221], v[76:79]
	v_mfma_f32_16x16x32_bf16 v[4:7], v[168:171], v[184:187], v[2:5]
	v_mfma_f32_16x16x32_bf16 v[28:31], v[176:179], v[184:187], v[28:31]
	v_mfma_f32_16x16x32_bf16 v[96:99], v[168:171], v[192:195], v[96:99]
	v_mfma_f32_16x16x32_bf16 v[92:95], v[176:179], v[192:195], v[92:95]
	v_mfma_f32_16x16x32_bf16 v[88:91], v[168:171], v[214:217], v[88:91]
	v_mfma_f32_16x16x32_bf16 v[84:87], v[176:179], v[214:217], v[84:87]
	v_mfma_f32_16x16x32_bf16 v[80:83], v[168:171], v[222:225], v[80:83]
	v_mfma_f32_16x16x32_bf16 v[76:79], v[176:179], v[222:225], v[76:79]

; #define PG8_STAGE(bufoff, gbase, voff) do { _Pragma("unroll") for (int _i = 0; _i < 2; ++_i) \
;         __builtin_amdgcn_global_load_lds((const unsigned*)((const char*)(gbase) + (voff)[_i]), (LAS unsigned*)(lds + (bufoff) + ldsw + _i * 8192), 16, 0, 0); } while (0)
; #define PG8_LDA(dst, b, h) do { _Pragma("unroll") for (int m = 0; m < 4; ++m) _Pragma("unroll") for (int k = 0; k < 2; ++k) dst[m][k] = *(const LAS bf16x8*)(lds + PG8_SA(b, h) + aoff + m * 2048 + k * 1024); } while (0)
; template <class Epi, bool ALIGN_EPI>
; __device__ __forceinline__ void gemm_phase(LAS unsigned char* lds, const Gemm g, const StaticOrder& S, const Epi& E, const int tid) {
;     ...
;             PG8_LDA(At, 1, 1); PG8_STAGE(PG8_SB(1, 0), b3, voffB); PG8_STAGE(PG8_SB(1, 1), b3 + hstepB, voffB); PG8_STAGE(PG8_SA(1, 0), a3, voffA);
	s_barrier
	s_add_u32 s34, s22, 0x8000
	s_addc_u32 s35, s23, 0
	s_add_i32 s87, s87, s61
	s_mov_b32 m0, s87
	ds_read_b128 v[180:183], v155 offset:49152
	ds_read_b128 v[184:187], v155 offset:50176
	ds_read_b128 v[188:191], v155 offset:51200
	ds_read_b128 v[192:195], v155 offset:52224


; #define PG8_STAGE(bufoff, gbase, voff) do { _Pragma("unroll") for (int _i = 0; _i < 2; ++_i) \
;         __builtin_amdgcn_global_load_lds((const unsigned*)((const char*)(gbase) + (voff)[_i]), (LAS unsigned*)(lds + (bufoff) + ldsw + _i * 8192), 16, 0, 0); } while (0)
; #define PG8_LDA(dst, b, h) do { _Pragma("unroll") for (int m = 0; m < 4; ++m) _Pragma("unroll") for (int k = 0; k < 2; ++k) dst[m][k] = *(const LAS bf16x8*)(lds + PG8_SA(b, h) + aoff + m * 2048 + k * 1024); } while (0)
; #define PG8_MMA(ai, bj, At, Bt) do { __builtin_amdgcn_s_setprio(1); _Pragma("unroll") for (int m = 0; m < 4; ++m) _Pragma("unroll") for (int n = 0; n < 2; ++n) _Pragma("unroll") for (int k = 0; k < 2; ++k) \
;         acc[ai][bj][m][n] = __builtin_amdgcn_mfma_f32_16x16x32_bf16(Bt[n][k], At[m][k], acc[ai][bj][m][n], 0, 0, 0); __builtin_amdgcn_s_setprio(0); } while (0)
; #define PG8_WAIT_V(n) asm volatile("s_waitcnt vmcnt(" #n ")" ::: "memory")
; #define PG8_WAIT_L(n) asm volatile("s_waitcnt lgkmcnt(" #n ")" ::: "memory")
; #define PG8_BAR __builtin_amdgcn_s_barrier()
; #define PG8_SCHED __builtin_amdgcn_sched_barrier(0)
; template <class Epi, bool ALIGN_EPI>
; __device__ __forceinline__ void gemm_phase(LAS unsigned char* lds, const Gemm g, const StaticOrder& S, const Epi& E, const int tid) {
;     ...
;             PG8_LDA(At, 1, 1); PG8_STAGE(PG8_SB(1, 0), b3, voffB); PG8_STAGE(PG8_SB(1, 1), b3 + hstepB, voffB); PG8_STAGE(PG8_SA(1, 0), a3, voffA);
;             PG8_WAIT_V(8); PG8_WAIT_L(0); PG8_BAR; PG8_MMA(1, 0, At, B0); PG8_MMA(1, 1, At, B1); PG8_BAR; PG8_SCHED;
	global_load_lds_dwordx4 v140, s[34:35]
	s_add_i32 m0, s87, 0x2000
	s_add_u32 s22, s22, 0xc000
	s_addc_u32 s23, s23, 0
	global_load_lds_dwordx4 v136, s[34:35]
	s_add_i32 s34, s88, s61
	s_mov_b32 m0, s34
	ds_read_b128 v[222:225], v155 offset:56320
	global_load_lds_dwordx4 v140, s[22:23]
	s_add_i32 m0, s34, 0x2000
	ds_read_b128 v[218:221], v155 offset:55296
	global_load_lds_dwordx4 v136, s[22:23]
	v_lshl_add_u64 v[2:3], v[152:153], 0, s[6:7]
	s_mov_b32 m0, s78
	ds_read_b128 v[214:217], v155 offset:54272
	global_load_lds_dwordx4 v[2:3], off
	v_lshl_add_u64 v[2:3], v[200:201], 0, s[6:7]
	s_mov_b32 m0, s79
	ds_read_b128 v[196:199], v155 offset:53248
	global_load_lds_dwordx4 v[2:3], off
	s_waitcnt vmcnt(8)
	s_waitcnt lgkmcnt(0)
	s_barrier


; #define PG8_MMA(ai, bj, At, Bt) do { __builtin_amdgcn_s_setprio(1); _Pragma("unroll") for (int m = 0; m < 4; ++m) _Pragma("unroll") for (int n = 0; n < 2; ++n) _Pragma("unroll") for (int k = 0; k < 2; ++k) \
;         acc[ai][bj][m][n] = __builtin_amdgcn_mfma_f32_16x16x32_bf16(Bt[n][k], At[m][k], acc[ai][bj][m][n], 0, 0, 0); __builtin_amdgcn_s_setprio(0); } while (0)
; #define PG8_WAIT_V(n) asm volatile("s_waitcnt vmcnt(" #n ")" ::: "memory")
; #define PG8_WAIT_L(n) asm volatile("s_waitcnt lgkmcnt(" #n ")" ::: "memory")
; #define PG8_BAR __builtin_amdgcn_s_barrier()
; #define PG8_SCHED __builtin_amdgcn_sched_barrier(0)
; template <class Epi, bool ALIGN_EPI>
; __device__ __forceinline__ void gemm_phase(LAS unsigned char* lds, const Gemm g, const StaticOrder& S, const Epi& E, const int tid) {
;     ...
;             PG8_WAIT_V(8); PG8_WAIT_L(0); PG8_BAR; PG8_MMA(1, 0, At, B0); PG8_MMA(1, 1, At, B1); PG8_BAR; PG8_SCHED;
	v_mfma_f32_16x16x32_bf16 v[24:27], v[132:135], v[180:183], v[24:27]
	v_mfma_f32_16x16x32_bf16 v[20:23], v[156:159], v[180:183], v[20:23]
	v_mfma_f32_16x16x32_bf16 v[64:67], v[132:135], v[188:191], v[64:67]
	v_mfma_f32_16x16x32_bf16 v[72:75], v[156:159], v[188:191], v[72:75]
	v_mfma_f32_16x16x32_bf16 v[16:19], v[132:135], v[196:199], v[16:19]
	v_mfma_f32_16x16x32_bf16 v[12:15], v[156:159], v[196:199], v[12:15]
	v_mfma_f32_16x16x32_bf16 v[60:63], v[132:135], v[218:221], v[60:63]
	v_mfma_f32_16x16x32_bf16 v[68:71], v[156:159], v[218:221], v[68:71]
	v_mfma_f32_16x16x32_bf16 v[24:27], v[148:151], v[184:187], v[24:27]
	v_mfma_f32_16x16x32_bf16 v[20:23], v[160:163], v[184:187], v[20:23]
	v_mfma_f32_16x16x32_bf16 v[64:67], v[148:151], v[192:195], v[64:67]
	v_mfma_f32_16x16x32_bf16 v[72:75], v[160:163], v[192:195], v[72:75]
	v_mfma_f32_16x16x32_bf16 v[16:19], v[148:151], v[214:217], v[16:19]
	v_mfma_f32_16x16x32_bf16 v[12:15], v[160:163], v[214:217], v[12:15]
	v_mfma_f32_16x16x32_bf16 v[60:63], v[148:151], v[222:225], v[60:63]
	v_mfma_f32_16x16x32_bf16 v[68:71], v[160:163], v[222:225], v[68:71]


; #define PG8_MMA(ai, bj, At, Bt) do { __builtin_amdgcn_s_setprio(1); _Pragma("unroll") for (int m = 0; m < 4; ++m) _Pragma("unroll") for (int n = 0; n < 2; ++n) _Pragma("unroll") for (int k = 0; k < 2; ++k) \
;         acc[ai][bj][m][n] = __builtin_amdgcn_mfma_f32_16x16x32_bf16(Bt[n][k], At[m][k], acc[ai][bj][m][n], 0, 0, 0); __builtin_amdgcn_s_setprio(0); } while (0)
; #define PG8_WAIT_V(n) asm volatile("s_waitcnt vmcnt(" #n ")" ::: "memory")
; #define PG8_WAIT_L(n) asm volatile("s_waitcnt lgkmcnt(" #n ")" ::: "memory")
; #define PG8_BAR __builtin_amdgcn_s_barrier()
; #define PG8_SCHED __builtin_amdgcn_sched_barrier(0)
; template <class Epi, bool ALIGN_EPI>
; __device__ __forceinline__ void gemm_phase(LAS unsigned char* lds, const Gemm g, const StaticOrder& S, const Epi& E, const int tid) {
;     ...
;             PG8_WAIT_V(8); PG8_WAIT_L(0); PG8_BAR; PG8_MMA(1, 0, At, B0); PG8_MMA(1, 1, At, B1); PG8_BAR; PG8_SCHED;
	v_mfma_f32_16x16x32_bf16 v[128:131], v[164:167], v[180:183], v[128:131]
	v_mfma_f32_16x16x32_bf16 v[124:127], v[172:175], v[180:183], v[124:127]
	v_mfma_f32_16x16x32_bf16 v[120:123], v[164:167], v[188:191], v[120:123]
	v_mfma_f32_16x16x32_bf16 v[116:119], v[172:175], v[188:191], v[116:119]
	v_mfma_f32_16x16x32_bf16 v[112:115], v[164:167], v[196:199], v[112:115]
	v_mfma_f32_16x16x32_bf16 v[108:111], v[172:175], v[196:199], v[108:111]
	v_mfma_f32_16x16x32_bf16 v[104:107], v[164:167], v[218:221], v[104:107]
	v_mfma_f32_16x16x32_bf16 v[100:103], v[172:175], v[218:221], v[100:103]
	v_mfma_f32_16x16x32_bf16 v[128:131], v[168:171], v[184:187], v[128:131]
	v_mfma_f32_16x16x32_bf16 v[124:127], v[176:179], v[184:187], v[124:127]
	v_mfma_f32_16x16x32_bf16 v[120:123], v[168:171], v[192:195], v[120:123]
	v_mfma_f32_16x16x32_bf16 v[116:119], v[176:179], v[192:195], v[116:119]
	v_mfma_f32_16x16x32_bf16 v[112:115], v[168:171], v[214:217], v[112:115]
	v_mfma_f32_16x16x32_bf16 v[108:111], v[176:179], v[214:217], v[108:111]
	v_mfma_f32_16x16x32_bf16 v[104:107], v[168:171], v[222:225], v[104:107]
	v_mfma_f32_16x16x32_bf16 v[100:103], v[176:179], v[222:225], v[100:103]

; #define PG8_MMA(ai, bj, At, Bt) do { __builtin_amdgcn_s_setprio(1); _Pragma("unroll") for (int m = 0; m < 4; ++m) _Pragma("unroll") for (int n = 0; n < 2; ++n) _Pragma("unroll") for (int k = 0; k < 2; ++k) \
;         acc[ai][bj][m][n] = __builtin_amdgcn_mfma_f32_16x16x32_bf16(Bt[n][k], At[m][k], acc[ai][bj][m][n], 0, 0, 0); __builtin_amdgcn_s_setprio(0); } while (0)
; #define PG8_WAIT_V(n) asm volatile("s_waitcnt vmcnt(" #n ")" ::: "memory")
; #define PG8_WAIT_L(n) asm volatile("s_waitcnt lgkmcnt(" #n ")" ::: "memory")
; #define PG8_BAR __builtin_amdgcn_s_barrier()
; #define PG8_SCHED __builtin_amdgcn_sched_barrier(0)
; template <class Epi, bool ALIGN_EPI>
; __device__ __forceinline__ void gemm_phase(LAS unsigned char* lds, const Gemm g, const StaticOrder& S, const Epi& E, const int tid) {
;     ...
;             PG8_WAIT_V(8); PG8_WAIT_L(0); PG8_BAR; PG8_MMA(1, 0, At, B0); PG8_MMA(1, 1, At, B1); PG8_BAR; PG8_SCHED;
;         }
;         if constexpr (ALIGN_EPI) { if (wr == 0) PG8_BAR; }
;     __device__ __forceinline__ void operator()(f32x4 (&acc)[2][2][4][2], const Unit& u, int wr, int wc, LAS unsigned char* lds, int& rs_pm) const {
;     ...
;                 bf16* const xrow = xb + (((size_t)(u.pm * 32 + u.pn * 4 + (wc >> 1)) * BM + (wr * 64 + fr + ai * HALF + m * 16)) * 64 + (wc & 1) * 32 + 8 * fq);
; #pragma unroll
;                 for (int bj = 0; bj < 2; ++bj) {
;                     const u32x4 xw = *(const u32x4*)(xrow + (size_t)bj * (2 * BM * 64));
	s_barrier
	s_add_i32 s86, s86, 2
	s_add_u32 s10, s10, 0x100
	s_addc_u32 s11, s11, 0
	s_add_u32 s84, s84, 0x10000
	s_addc_u32 s85, s85, 0
	s_cmp_gt_u32 s86, 29
	s_cbranch_scc0 .LBB0_847
	v_and_b32_e32 v222, 15, v238
	v_lshrrev_b32_e32 v156, 4, v238
	s_lshl_b32 s100, s40, 5
	s_lshl_b32 s101, s41, 2
	v_lshlrev_b32_e32 v222, 7, v222
	s_add_i32 s100, s100, s101
	s_or_b32 s100, s100, s80
	v_lshl_or_b32 v222, v156, 4, v222
	s_ashr_i32 s101, s100, 31
	s_lshl_b64 s[100:101], s[100:101], 15
	s_add_u32 s98, s74, s100
	s_addc_u32 s99, s75, s101
	s_add_u32 s98, s98, s30
	s_addc_u32 s99, s99, s31
	s_lshl_b32 s100, s77, 7
	s_add_u32 s98, s98, s100
	s_addc_u32 s99, s99, 0
	s_lshl_b32 s100, s40, 15
	s_lshl_b32 s101, s77, 7
	s_add_i32 s100, s100, s101
	s_lshl_b32 s101, s41, 4
	s_add_i32 s100, s100, s101
	s_lshl_b32 s101, s76, 2
	s_add_i32 s100, s100, s101
	s_add_u32 s22, s42, s100
	s_addc_u32 s23, s43, 0
	global_load_dwordx4 v[176:179], v222, s[98:99]
	s_add_u32 s100, s98, 0x10000
	s_addc_u32 s101, s99, 0
	global_load_dwordx4 v[180:183], v222, s[100:101]
	global_load_dwordx4 v[184:187], v222, s[98:99] offset:2048
	s_add_u32 s100, s98, 0x10000
	s_addc_u32 s101, s99, 0
	global_load_dwordx4 v[188:191], v222, s[100:101] offset:2048
	s_add_u32 s100, s98, 0x1000
	s_addc_u32 s101, s99, 0
	global_load_dwordx4 v[192:195], v222, s[100:101]
	s_add_u32 s100, s98, 0x11000
	s_addc_u32 s101, s99, 0
	global_load_dwordx4 v[196:199], v222, s[100:101]
	s_add_u32 s100, s98, 0x1000
	s_addc_u32 s101, s99, 0
	global_load_dwordx4 v[214:217], v222, s[100:101] offset:2048
	s_add_u32 s100, s98, 0x11000
	s_addc_u32 s101, s99, 0
	global_load_dwordx4 v[218:221], v222, s[100:101] offset:2048
	s_and_b64 vcc, exec, s[44:45]
	s_cbranch_vccz .LBB0_850
	s_barrier
